# v49 with the required wait state restored between every m0 write and its LDS-DMA load (35 s_nop 0 that the dead-code pass had exposed)
# speedup vs baseline: 1.0063x; 1.0033x over previous
; DI int tid_opaque() { int t = threadIdx.x; asm volatile("" : "+v"(t)); return t; }
; #define BAR8 __builtin_amdgcn_s_barrier()
;   constexpr int HT = 128 * 64;
;   bf16_t* shm = (bf16_t*)smem;
;   const int t = tid_opaque();
;     ...
;   const int nt = K / 64;
;   if (!pre) {
;     STAGE8(SB8(0, 0), Bt, K, bcol, 0); STAGE8(SA8(0, 0), A, lda, brow, 0);
;     STAGE8(SB8(0, 1), Bt, K, bcol + 128, 0); STAGE8(SA8(0, 1), A, lda, brow + 128, 0);
;   }
;   if (wr == 1) BAR8;
.LBB0_188:
	s_and_b32 s0, s25, 63
	s_lshl_b32 s30, s0, 19
	s_and_b32 s0, s24, 0xffffff00
	s_ashr_i32 s1, s0, 31
	s_lshl_b64 s[56:57], s[0:1], 11
	s_mov_b32 s0, 25
	s_ashr_i32 s1, s0, 31
	s_and_b32 s20, s33, 63
	s_lshl_b64 s[0:1], s[0:1], 3
	s_add_u32 s0, s70, s0
	s_addc_u32 s1, s71, s1
	v_readlane_b32 s0, v255, 60
	v_readlane_b32 s1, v255, 61
	s_nop 4
	v_readlane_b32 s12, v254, 35
	s_mov_b32 s31, s12
	v_readlane_b32 s13, v254, 36
	v_readlane_b32 s14, v254, 37
	s_waitcnt lgkmcnt(0)
	s_add_u32 s54, s0, 0xf640000
	s_mov_b32 s0, 25
	s_addc_u32 s55, s1, 0
	s_ashr_i32 s1, s0, 31
	s_lshl_b64 s[0:1], s[0:1], 3
	s_add_u32 s0, s70, s0
	s_addc_u32 s1, s71, s1
	v_readlane_b32 s0, v255, 60
	v_readlane_b32 s1, v255, 61
	s_nop 4
	v_readlane_b32 s15, v254, 38
	s_waitcnt lgkmcnt(0)
	s_add_u32 s50, s0, 0x2000000
	s_addc_u32 s51, s1, 0
	s_lshl_b32 s0, s33, 2
	s_lshl_b32 s36, s20, 8
	s_and_b32 s52, s0, 0xffffff00
	s_andn2_b64 vcc, exec, s[40:41]
	s_mov_b64 s[0:1], -1
	s_cbranch_vccnz .LBB0_238
	s_mov_b32 s0, 4
	s_ashr_i32 s1, s0, 31
	s_lshl_b64 s[0:1], s[0:1], 3
	s_add_u32 s0, s70, s0
	s_addc_u32 s1, s71, s1
	s_mov_b32 s2, 5
	s_load_dwordx2 s[0:1], s[0:1], 0x0
	s_ashr_i32 s3, s2, 31
	s_lshl_b64 s[2:3], s[2:3], 3
	s_add_u32 s2, s70, s2
	s_addc_u32 s3, s71, s3
	s_mov_b32 s4, 25
	s_load_dwordx2 s[2:3], s[2:3], 0x0
	s_ashr_i32 s5, s4, 31
	s_lshl_b64 s[4:5], s[4:5], 3
	s_add_u32 s4, s70, s4
	s_addc_u32 s5, s71, s5
	v_mov_b32_e32 v3, v224
	v_readlane_b32 s12, v255, 60
	v_readlane_b32 s13, v255, 61
	s_nop 4
	s_ashr_i32 s53, s52, 31
	v_bfe_i32 v1, v3, 27, 1
	s_waitcnt vmcnt(10)
	v_lshlrev_b32_e32 v150, 4, v3
	s_nop 0
	v_readfirstlane_b32 s100, v150
	v_lshrrev_b32_e32 v1, 22, v1
	v_add_u32_e32 v1, v150, v1
	v_and_b32_e32 v1, 0xfffffc00, v1
	v_ashrrev_i32_e32 v0, 31, v3
	v_sub_u32_e32 v1, v150, v1
	v_lshrrev_b32_e32 v0, 26, v0
	v_lshrrev_b32_e32 v5, 4, v1
	v_add_u32_e32 v0, v3, v0
	v_bitop3_b32 v5, v5, v1, 32 bitop3:0x6c
	v_ashrrev_i32_e32 v1, 31, v1
	v_ashrrev_i32_e32 v0, 6, v0
	v_lshrrev_b32_e32 v1, 26, v1
	v_lshlrev_b32_e32 v6, 3, v0
	v_add_u32_e32 v1, v5, v1
	v_and_b32_e32 v6, -16, v6
	v_ashrrev_i32_e32 v1, 6, v1
	v_add_u32_e32 v6, v1, v6
	v_mul_i32_i24_e32 v1, 64, v1
	v_lshlrev_b32_e32 v0, 5, v0
	v_sub_u32_e32 v1, v5, v1
	v_mov_b32_e32 v14, 1
	s_waitcnt vmcnt(9)
	s_lshl_b64 s[4:5], s[52:53], 11
	v_readlane_b32 s21, v254, 44
	v_and_b32_e32 v0, 32, v0
	v_ashrrev_i16_sdwa v1, v14, sext(v1) dst_sel:DWORD dst_unused:UNUSED_PAD src0_sel:DWORD src1_sel:BYTE_0
	s_add_u32 s4, s21, s4
	v_readlane_b32 s27, v254, 45
	v_add_u32_sdwa v0, v0, sext(v1) dst_sel:DWORD dst_unused:UNUSED_PAD src0_sel:DWORD src1_sel:WORD_0
	v_ashrrev_i32_e32 v7, 31, v6
	s_addc_u32 s5, s27, s5
	v_lshlrev_b64 v[132:133], 11, v[6:7]
	v_ashrrev_i32_e32 v1, 31, v0
	v_lshl_add_u64 v[8:9], s[4:5], 0, v[132:133]
	v_lshlrev_b64 v[6:7], 1, v[0:1]
	v_lshl_add_u64 v[10:11], v[8:9], 0, v[6:7]
	v_lshrrev_b32_e32 v134, 1, v6
	v_add_u32_e32 v136, 0x20000, v132
	v_mov_b32_e32 v137, v133
	s_waitcnt vmcnt(8)
	s_or_b32 m0, s100, 0x10000
	v_lshl_add_u64 v[12:13], s[4:5], 0, v[136:137]
	global_load_lds_dwordx4 v[10:11], off
	s_or_b32 m0, s100, 0x12000
	s_lshl_b32 s4, s20, 19
	v_mov_b32_e32 v135, v7
	s_waitcnt lgkmcnt(0)
	s_add_u32 s4, s12, s4
	v_mov_b64_e32 v[8:9], v[6:7]
	s_addc_u32 s5, s13, 0
	v_lshl_add_u64 v[12:13], v[12:13], 0, v[8:9]
	v_lshl_add_u64 v[14:15], s[4:5], 0, v[132:133]
	s_or_b32 s58, s52, 0x80
	global_load_lds_dwordx4 v[12:13], off
	v_lshl_add_u64 v[14:15], v[14:15], 0, v[6:7]
	s_mov_b32 m0, s100
	s_ashr_i32 s59, s58, 31
	global_load_lds_dwordx4 v[14:15], off
	s_or_b32 m0, s100, 0x2000
	s_lshl_b64 s[14:15], s[58:59], 11
	s_add_u32 s14, s21, s14
	v_lshl_add_u64 v[16:17], s[4:5], 0, v[136:137]
	s_addc_u32 s15, s27, s15
	v_lshl_add_u64 v[16:17], v[16:17], 0, v[8:9]
	v_lshl_add_u64 v[18:19], s[14:15], 0, v[132:133]
	global_load_lds_dwordx4 v[16:17], off
	v_lshl_add_u64 v[18:19], v[18:19], 0, v[6:7]
	s_or_b32 m0, s100, 0x14000
	v_lshl_add_u64 v[20:21], s[14:15], 0, v[136:137]
	global_load_lds_dwordx4 v[18:19], off
	s_or_b32 m0, s100, 0x16000
	s_add_u32 s14, s4, 0x40000
	s_addc_u32 s15, s5, 0
	v_lshl_add_u64 v[20:21], v[20:21], 0, v[8:9]
	v_lshl_add_u64 v[22:23], s[14:15], 0, v[132:133]
	global_load_lds_dwordx4 v[20:21], off
	v_lshl_add_u64 v[22:23], v[22:23], 0, v[6:7]
	s_or_b32 m0, s100, 0x4000
	s_nop 0
	global_load_lds_dwordx4 v[22:23], off
	v_lshl_add_u64 v[22:23], s[14:15], 0, v[136:137]
	v_lshl_add_u64 v[22:23], v[22:23], 0, v[8:9]
	s_or_b32 m0, s100, 0x6000
	v_ashrrev_i32_e32 v5, 8, v3
	global_load_lds_dwordx4 v[22:23], off
	v_cmp_eq_u32_e32 vcc, 1, v5
	s_and_saveexec_b64 s[14:15], vcc
	s_cbranch_execz .LBB0_191
	s_barrier
; #define LDA8(dst, b, h) _Pragma("unroll") for (int m = 0; m < 4; ++m) _Pragma("unroll") for (int k = 0; k < 2; ++k) \
;     dst[m][k] = *(const bf16x8*)((const char*)SA8(b, h) + lds_byte8(wr * 64 + m * 16 + fr, k * 32 + fq * 8))
; #define LDB8(dst, b, h) _Pragma("unroll") for (int n = 0; n < 2; ++n) _Pragma("unroll") for (int k = 0; k < 2; ++k) \
;     dst[n][k] = *(const bf16x8*)((const char*)SB8(b, h) + lds_byte8(wc * 32 + n * 16 + fr, k * 32 + fq * 8))
; #define WAIT_V8(n) asm volatile("s_waitcnt vmcnt(" #n ")" ::: "memory")
; #define WAIT_L8(n) asm volatile("s_waitcnt lgkmcnt(" #n ")" ::: "memory")
; #define BAR8 __builtin_amdgcn_s_barrier()
; #define SCHED8 __builtin_amdgcn_sched_barrier(0)
;     ...
;   if (wr == 1) BAR8;
;   WAIT_V8(4); BAR8;
;   STAGE8(SB8(1, 0), Bt, K, bcol, 1); STAGE8(SA8(1, 0), A, lda, brow, 1); STAGE8(SB8(1, 1), Bt, K, bcol + 128, 1);
;   WAIT_V8(6); BAR8;
;   for (int tt = 0; tt < nt - 2; tt += 2) {
;     LDB8(B0, 0, 0); SCHED8; LDA8(At, 0, 0); STAGE8(SA8(1, 1), A, lda, brow + 128, tt + 1);
;     WAIT_L8(8); BAR8; WAIT_L8(0); MMA8(0, 0, At, B0); BAR8; SCHED8;
;     LDB8(B1, 0, 1); STAGE8(SB8(0, 0), Bt, K, bcol, tt + 2);
;     BAR8; WAIT_L8(0); MMA8(0, 1, At, B1); BAR8;
.LBB0_191:
	s_or_b64 exec, exec, s[14:15]
	s_mov_b64 s[60:61], 0x80
	v_lshl_add_u64 v[10:11], v[10:11], 0, s[60:61]
	s_or_b32 m0, s100, 0x18000
	s_waitcnt vmcnt(4)
	s_barrier
	global_load_lds_dwordx4 v[10:11], off
	v_lshl_add_u64 v[10:11], v[12:13], 0, s[60:61]
	s_or_b32 m0, s100, 0x1a000
	s_nop 0
	global_load_lds_dwordx4 v[10:11], off
	v_lshl_add_u64 v[10:11], v[14:15], 0, s[60:61]
	s_or_b32 m0, s100, 0x8000
	s_nop 0
	global_load_lds_dwordx4 v[10:11], off
	v_lshl_add_u64 v[10:11], v[16:17], 0, s[60:61]
	s_or_b32 m0, s100, 0xa000
	s_nop 0
	global_load_lds_dwordx4 v[10:11], off
	s_or_b32 m0, s100, 0x1c000
	v_lshl_add_u64 v[10:11], v[18:19], 0, s[60:61]
	global_load_lds_dwordx4 v[10:11], off
	v_lshl_add_u64 v[10:11], v[20:21], 0, s[60:61]
	s_or_b32 m0, s100, 0x1e000
	v_and_b32_e32 v147, 15, v3
	global_load_lds_dwordx4 v[10:11], off
	v_bfe_u32 v148, v3, 4, 2
	v_lshlrev_b32_e32 v10, 4, v148
	v_lshlrev_b32_e32 v11, 6, v147
	v_lshlrev_b32_e32 v14, 2, v3
	v_or_b32_e32 v13, v10, v11
	v_and_b32_e32 v14, 32, v14
	s_mov_b32 s14, 0x10000
	v_bitop3_b32 v16, v13, s14, v14 bitop3:0xde
	s_mov_b32 s14, 0x14000
	v_bitop3_b32 v15, v10, v14, v11 bitop3:0x36
	v_bitop3_b32 v17, v13, s14, v14 bitop3:0xde
	s_mov_b32 s14, 0x18000
	v_lshlrev_b32_e32 v11, 6, v3
	v_bitop3_b32 v18, v13, s14, v14 bitop3:0xde
	s_mov_b32 s14, 0x1c000
	v_and_b32_e32 v11, 0x3c0, v11
	v_bitop3_b32 v13, v13, s14, v14 bitop3:0xde
	v_bitop3_b32 v14, v11, v14, v10 bitop3:0x36
	v_lshl_add_u64 v[10:11], s[30:31], 0, v[136:137]
	v_lshl_add_u64 v[10:11], v[10:11], 0, v[8:9]
	v_lshl_add_u64 v[138:139], s[12:13], 0, v[10:11]
	v_lshl_add_u64 v[10:11], s[30:31], 0, v[132:133]
	v_lshl_add_u64 v[10:11], v[10:11], 0, v[6:7]
	v_lshl_add_u64 v[140:141], s[12:13], 0, v[10:11]
	v_lshl_add_u64 v[10:11], s[56:57], 0, v[132:133]
	v_lshl_add_u64 v[6:7], v[10:11], 0, v[6:7]
	v_bfe_u32 v146, v3, 6, 2
	s_waitcnt vmcnt(6)
	v_lshlrev_b32_e32 v149, 6, v5
	v_lshlrev_b32_e32 v5, 13, v5
	v_lshl_add_u64 v[142:143], s[46:47], 0, v[6:7]
	v_lshl_add_u64 v[6:7], s[56:57], 0, v[136:137]
	v_lshlrev_b32_e32 v12, 12, v146
	v_or_b32_e32 v19, 0x800, v5
	v_or_b32_e32 v20, 0x1000, v5
	v_or_b32_e32 v21, 0x1800, v5
	v_lshl_add_u64 v[6:7], v[6:7], 0, v[8:9]
	v_lshl_add_u64 v[144:145], s[46:47], 0, v[6:7]
	s_mov_b32 s14, -2
	s_mov_b64 s[12:13], 0
	v_add_u32_e32 v173, v16, v12
	v_add_u32_e32 v156, v15, v5
	v_add_u32_e32 v154, v14, v19
	v_add_u32_e32 v153, v14, v20
	v_add_u32_e32 v152, v14, v21
	v_add_u32_e32 v169, v17, v12
	v_add_u32_e32 v159, v18, v12
	v_add_u32_e32 v158, v13, v12
	s_mov_b64 s[60:61], 0xc000100
	s_mov_b64 s[62:63], 0xc040100
	s_mov_b64 s[64:65], 0xc000180
	s_mov_b64 s[66:67], 0xc040180
	s_barrier
	ds_read_b128 v[174:177], v173
	ds_read_b128 v[178:181], v173 offset:1024
	ds_read_b128 v[182:185], v173 offset:2048
	ds_read_b128 v[186:189], v173 offset:3072
	v_lshl_add_u64 v[222:223], v[140:141], 0, s[12:13]
	v_lshl_add_u64 v[226:227], v[222:223], 0, s[34:35]
	s_or_b32 m0, s100, 0xc000
	ds_read_b128 v[190:193], v156
	ds_read_b128 v[194:197], v156 offset:1024
	ds_read_b128 v[198:201], v154
	ds_read_b128 v[202:205], v154 offset:1024
	ds_read_b128 v[206:209], v153
	ds_read_b128 v[210:213], v153 offset:1024
	ds_read_b128 v[214:217], v152
	ds_read_b128 v[218:221], v152 offset:1024
	global_load_lds_dwordx4 v[226:227], off
	v_lshl_add_u64 v[226:227], v[138:139], 0, s[12:13]
	s_or_b32 m0, s100, 0xe000
	v_lshl_add_u64 v[228:229], v[226:227], 0, s[34:35]
	global_load_lds_dwordx4 v[228:229], off
	s_waitcnt lgkmcnt(8)
	s_barrier
	s_waitcnt lgkmcnt(0)
	v_mfma_f32_16x16x32_f16 v[128:131], v[190:193], v[174:177], 0
	v_mfma_f32_16x16x32_f16 v[124:127], v[190:193], v[182:185], 0
	v_mfma_f32_16x16x32_f16 v[120:123], v[198:201], v[174:177], 0
	v_mfma_f32_16x16x32_f16 v[116:119], v[198:201], v[182:185], 0
	v_mfma_f32_16x16x32_f16 v[112:115], v[206:209], v[174:177], 0
	v_mfma_f32_16x16x32_f16 v[108:111], v[206:209], v[182:185], 0
	v_mfma_f32_16x16x32_f16 v[104:107], v[214:217], v[174:177], 0
	v_mfma_f32_16x16x32_f16 v[100:103], v[214:217], v[182:185], 0
	v_mfma_f32_16x16x32_f16 v[128:131], v[194:197], v[178:181], v[128:131]
	v_mfma_f32_16x16x32_f16 v[124:127], v[194:197], v[186:189], v[124:127]
	v_mfma_f32_16x16x32_f16 v[120:123], v[202:205], v[178:181], v[120:123]
	v_mfma_f32_16x16x32_f16 v[116:119], v[202:205], v[186:189], v[116:119]
	v_mfma_f32_16x16x32_f16 v[112:115], v[210:213], v[178:181], v[112:115]
	v_mfma_f32_16x16x32_f16 v[108:111], v[210:213], v[186:189], v[108:111]
	v_mfma_f32_16x16x32_f16 v[104:107], v[218:221], v[178:181], v[104:107]
	v_mfma_f32_16x16x32_f16 v[100:103], v[218:221], v[186:189], v[100:103]
	s_barrier
	v_lshl_add_u64 v[228:229], v[142:143], 0, s[12:13]
	v_lshl_add_u64 v[236:237], v[228:229], 0, s[60:61]
	s_or_b32 m0, s100, 0x10000
	ds_read_b128 v[238:241], v169
	ds_read_b128 v[242:245], v169 offset:1024
	ds_read_b128 v[246:249], v169 offset:2048
	ds_read_b128 v[230:233], v169 offset:3072
	global_load_lds_dwordx4 v[236:237], off
	v_lshl_add_u64 v[236:237], v[144:145], 0, s[12:13]
	s_or_b32 m0, s100, 0x12000
	v_lshl_add_u64 v[250:251], v[236:237], 0, s[60:61]
	global_load_lds_dwordx4 v[250:251], off
	s_barrier
; #define LDA8(dst, b, h) _Pragma("unroll") for (int m = 0; m < 4; ++m) _Pragma("unroll") for (int k = 0; k < 2; ++k) \
;     dst[m][k] = *(const bf16x8*)((const char*)SA8(b, h) + lds_byte8(wr * 64 + m * 16 + fr, k * 32 + fq * 8))
; #define LDB8(dst, b, h) _Pragma("unroll") for (int n = 0; n < 2; ++n) _Pragma("unroll") for (int k = 0; k < 2; ++k) \
;     dst[n][k] = *(const bf16x8*)((const char*)SB8(b, h) + lds_byte8(wc * 32 + n * 16 + fr, k * 32 + fq * 8))
; #define WAIT_V8(n) asm volatile("s_waitcnt vmcnt(" #n ")" ::: "memory")
; #define WAIT_L8(n) asm volatile("s_waitcnt lgkmcnt(" #n ")" ::: "memory")
; #define BAR8 __builtin_amdgcn_s_barrier()
; #define SCHED8 __builtin_amdgcn_sched_barrier(0)
;     ...
;     BAR8; WAIT_L8(0); MMA8(0, 1, At, B1); BAR8;
;     LDA8(At, 0, 1); STAGE8(SA8(0, 0), A, lda, brow, tt + 2);
;     BAR8; WAIT_L8(0); MMA8(1, 0, At, B0); BAR8; SCHED8;
;     STAGE8(SB8(0, 1), Bt, K, bcol + 128, tt + 2);
;     WAIT_V8(6); BAR8; MMA8(1, 1, At, B1); BAR8;
;     LDB8(B0, 1, 0); SCHED8; LDA8(At, 1, 0); STAGE8(SA8(0, 1), A, lda, brow + 128, tt + 2);
;     WAIT_L8(8); BAR8; WAIT_L8(0); MMA8(0, 0, At, B0); BAR8; SCHED8;
	s_waitcnt lgkmcnt(0)
	v_mfma_f32_16x16x32_f16 v[96:99], v[190:193], v[238:241], 0
	v_mfma_f32_16x16x32_f16 v[92:95], v[190:193], v[246:249], 0
	v_mfma_f32_16x16x32_f16 v[88:91], v[198:201], v[238:241], 0
	v_mfma_f32_16x16x32_f16 v[84:87], v[198:201], v[246:249], 0
	v_mfma_f32_16x16x32_f16 v[80:83], v[206:209], v[238:241], 0
	v_mfma_f32_16x16x32_f16 v[76:79], v[206:209], v[246:249], 0
	v_mfma_f32_16x16x32_f16 v[72:75], v[214:217], v[238:241], 0
	v_mfma_f32_16x16x32_f16 v[68:71], v[214:217], v[246:249], 0
	v_mfma_f32_16x16x32_f16 v[96:99], v[194:197], v[242:245], v[96:99]
	v_mfma_f32_16x16x32_f16 v[92:95], v[194:197], v[230:233], v[92:95]
	v_mfma_f32_16x16x32_f16 v[88:91], v[202:205], v[242:245], v[88:91]
	v_mfma_f32_16x16x32_f16 v[84:87], v[202:205], v[230:233], v[84:87]
	v_mfma_f32_16x16x32_f16 v[80:83], v[210:213], v[242:245], v[80:83]
	v_mfma_f32_16x16x32_f16 v[76:79], v[210:213], v[230:233], v[76:79]
	v_mfma_f32_16x16x32_f16 v[72:75], v[218:221], v[242:245], v[72:75]
	v_mfma_f32_16x16x32_f16 v[68:71], v[218:221], v[230:233], v[68:71]
	v_lshl_add_u64 v[250:251], v[222:223], 0, s[10:11]
	s_mov_b32 m0, s100
	s_barrier
	ds_read_b128 v[190:193], v156 offset:16384
	ds_read_b128 v[194:197], v156 offset:17408
	ds_read_b128 v[198:201], v154 offset:16384
	ds_read_b128 v[202:205], v154 offset:17408
	ds_read_b128 v[206:209], v153 offset:16384
	ds_read_b128 v[210:213], v153 offset:17408
	ds_read_b128 v[214:217], v152 offset:16384
	ds_read_b128 v[218:221], v152 offset:17408
	global_load_lds_dwordx4 v[250:251], off
	s_or_b32 m0, s100, 0x2000
	v_lshl_add_u64 v[250:251], v[226:227], 0, s[10:11]
	global_load_lds_dwordx4 v[250:251], off
	s_barrier
	s_waitcnt lgkmcnt(0)
	v_mfma_f32_16x16x32_f16 v[64:67], v[190:193], v[174:177], 0
	v_mfma_f32_16x16x32_f16 v[60:63], v[190:193], v[182:185], 0
	v_mfma_f32_16x16x32_f16 v[56:59], v[198:201], v[174:177], 0
	v_mfma_f32_16x16x32_f16 v[52:55], v[198:201], v[182:185], 0
	v_mfma_f32_16x16x32_f16 v[48:51], v[206:209], v[174:177], 0
	v_mfma_f32_16x16x32_f16 v[44:47], v[206:209], v[182:185], 0
	v_mfma_f32_16x16x32_f16 v[40:43], v[214:217], v[174:177], 0
	v_mfma_f32_16x16x32_f16 v[36:39], v[214:217], v[182:185], 0
	v_mfma_f32_16x16x32_f16 v[64:67], v[194:197], v[178:181], v[64:67]
	v_mfma_f32_16x16x32_f16 v[60:63], v[194:197], v[186:189], v[60:63]
	v_mfma_f32_16x16x32_f16 v[56:59], v[202:205], v[178:181], v[56:59]
	v_mfma_f32_16x16x32_f16 v[52:55], v[202:205], v[186:189], v[52:55]
	v_mfma_f32_16x16x32_f16 v[48:51], v[210:213], v[178:181], v[48:51]
	v_mfma_f32_16x16x32_f16 v[44:47], v[210:213], v[186:189], v[44:47]
	v_mfma_f32_16x16x32_f16 v[40:43], v[218:221], v[178:181], v[40:43]
	v_mfma_f32_16x16x32_f16 v[36:39], v[218:221], v[186:189], v[36:39]
	s_barrier
	s_or_b32 m0, s100, 0x14000
	v_lshl_add_u64 v[174:175], v[228:229], 0, s[62:63]
	global_load_lds_dwordx4 v[174:175], off
	s_or_b32 m0, s100, 0x16000
	v_lshl_add_u64 v[174:175], v[236:237], 0, s[62:63]
	global_load_lds_dwordx4 v[174:175], off
	s_waitcnt vmcnt(6)
	s_barrier
	v_mfma_f32_16x16x32_f16 v[32:35], v[190:193], v[238:241], 0
	v_mfma_f32_16x16x32_f16 v[28:31], v[190:193], v[246:249], 0
	v_mfma_f32_16x16x32_f16 v[24:27], v[198:201], v[238:241], 0
	v_mfma_f32_16x16x32_f16 v[20:23], v[198:201], v[246:249], 0
	v_mfma_f32_16x16x32_f16 v[16:19], v[206:209], v[238:241], 0
	v_mfma_f32_16x16x32_f16 v[12:15], v[206:209], v[246:249], 0
	v_mfma_f32_16x16x32_f16 v[8:11], v[214:217], v[238:241], 0
	v_mfma_f32_16x16x32_f16 v[4:7], v[214:217], v[246:249], 0
	v_mfma_f32_16x16x32_f16 v[32:35], v[194:197], v[242:245], v[32:35]
	v_mfma_f32_16x16x32_f16 v[28:31], v[194:197], v[230:233], v[28:31]
	v_mfma_f32_16x16x32_f16 v[24:27], v[202:205], v[242:245], v[24:27]
	v_mfma_f32_16x16x32_f16 v[20:23], v[202:205], v[230:233], v[20:23]
	v_mfma_f32_16x16x32_f16 v[16:19], v[210:213], v[242:245], v[16:19]
	v_mfma_f32_16x16x32_f16 v[12:15], v[210:213], v[230:233], v[12:15]
	v_mfma_f32_16x16x32_f16 v[8:11], v[218:221], v[242:245], v[8:11]
	v_mfma_f32_16x16x32_f16 v[4:7], v[218:221], v[230:233], v[4:7]
	s_barrier
	ds_read_b128 v[174:177], v159
	ds_read_b128 v[178:181], v159 offset:1024
	ds_read_b128 v[182:185], v159 offset:2048
	ds_read_b128 v[186:189], v159 offset:3072
	v_lshl_add_u64 v[230:231], v[222:223], 0, s[18:19]
	s_or_b32 m0, s100, 0x4000
	ds_read_b128 v[190:193], v156 offset:32768
	ds_read_b128 v[194:197], v156 offset:33792
	ds_read_b128 v[198:201], v154 offset:32768
	ds_read_b128 v[202:205], v154 offset:33792
	ds_read_b128 v[206:209], v153 offset:32768
	ds_read_b128 v[210:213], v153 offset:33792
	ds_read_b128 v[214:217], v152 offset:32768
	ds_read_b128 v[218:221], v152 offset:33792
	global_load_lds_dwordx4 v[230:231], off
	s_or_b32 m0, s100, 0x6000
	v_lshl_add_u64 v[230:231], v[226:227], 0, s[18:19]
	global_load_lds_dwordx4 v[230:231], off
	s_waitcnt lgkmcnt(8)
	s_barrier
; #define LDA8(dst, b, h) _Pragma("unroll") for (int m = 0; m < 4; ++m) _Pragma("unroll") for (int k = 0; k < 2; ++k) \
;     dst[m][k] = *(const bf16x8*)((const char*)SA8(b, h) + lds_byte8(wr * 64 + m * 16 + fr, k * 32 + fq * 8))
; #define LDB8(dst, b, h) _Pragma("unroll") for (int n = 0; n < 2; ++n) _Pragma("unroll") for (int k = 0; k < 2; ++k) \
;     dst[n][k] = *(const bf16x8*)((const char*)SB8(b, h) + lds_byte8(wc * 32 + n * 16 + fr, k * 32 + fq * 8))
; #define WAIT_V8(n) asm volatile("s_waitcnt vmcnt(" #n ")" ::: "memory")
; #define WAIT_L8(n) asm volatile("s_waitcnt lgkmcnt(" #n ")" ::: "memory")
; #define BAR8 __builtin_amdgcn_s_barrier()
; #define SCHED8 __builtin_amdgcn_sched_barrier(0)
;     ...
;     WAIT_L8(8); BAR8; WAIT_L8(0); MMA8(0, 0, At, B0); BAR8; SCHED8;
;     LDB8(B1, 1, 1); STAGE8(SB8(1, 0), Bt, K, bcol, tt + 3);
;     BAR8; WAIT_L8(0); MMA8(0, 1, At, B1); BAR8;
;     LDA8(At, 1, 1); STAGE8(SA8(1, 0), A, lda, brow, tt + 3);
;     BAR8; WAIT_L8(0); MMA8(1, 0, At, B0); BAR8; SCHED8;
;     STAGE8(SB8(1, 1), Bt, K, bcol + 128, tt + 3);
;     WAIT_V8(6); BAR8; MMA8(1, 1, At, B1); BAR8;
;   }
	s_waitcnt lgkmcnt(0)
	v_mfma_f32_16x16x32_f16 v[128:131], v[190:193], v[174:177], v[128:131]
	v_mfma_f32_16x16x32_f16 v[124:127], v[190:193], v[182:185], v[124:127]
	v_mfma_f32_16x16x32_f16 v[120:123], v[198:201], v[174:177], v[120:123]
	v_mfma_f32_16x16x32_f16 v[116:119], v[198:201], v[182:185], v[116:119]
	v_mfma_f32_16x16x32_f16 v[112:115], v[206:209], v[174:177], v[112:115]
	v_mfma_f32_16x16x32_f16 v[108:111], v[206:209], v[182:185], v[108:111]
	v_mfma_f32_16x16x32_f16 v[104:107], v[214:217], v[174:177], v[104:107]
	v_mfma_f32_16x16x32_f16 v[100:103], v[214:217], v[182:185], v[100:103]
	v_mfma_f32_16x16x32_f16 v[128:131], v[194:197], v[178:181], v[128:131]
	v_mfma_f32_16x16x32_f16 v[124:127], v[194:197], v[186:189], v[124:127]
	v_mfma_f32_16x16x32_f16 v[120:123], v[202:205], v[178:181], v[120:123]
	v_mfma_f32_16x16x32_f16 v[116:119], v[202:205], v[186:189], v[116:119]
	v_mfma_f32_16x16x32_f16 v[112:115], v[210:213], v[178:181], v[112:115]
	v_mfma_f32_16x16x32_f16 v[108:111], v[210:213], v[186:189], v[108:111]
	v_mfma_f32_16x16x32_f16 v[104:107], v[218:221], v[178:181], v[104:107]
	v_mfma_f32_16x16x32_f16 v[100:103], v[218:221], v[186:189], v[100:103]
	s_barrier
	v_lshl_add_u64 v[250:251], v[228:229], 0, s[64:65]
	s_or_b32 m0, s100, 0x18000
	ds_read_b128 v[230:233], v158
	ds_read_b128 v[238:241], v158 offset:1024
	ds_read_b128 v[242:245], v158 offset:2048
	ds_read_b128 v[246:249], v158 offset:3072
	global_load_lds_dwordx4 v[250:251], off
	s_or_b32 m0, s100, 0x1a000
	v_lshl_add_u64 v[250:251], v[236:237], 0, s[64:65]
	global_load_lds_dwordx4 v[250:251], off
	s_barrier
	s_waitcnt lgkmcnt(0)
	v_mfma_f32_16x16x32_f16 v[96:99], v[190:193], v[230:233], v[96:99]
	v_mfma_f32_16x16x32_f16 v[92:95], v[190:193], v[242:245], v[92:95]
	v_mfma_f32_16x16x32_f16 v[88:91], v[198:201], v[230:233], v[88:91]
	v_mfma_f32_16x16x32_f16 v[84:87], v[198:201], v[242:245], v[84:87]
	v_mfma_f32_16x16x32_f16 v[80:83], v[206:209], v[230:233], v[80:83]
	v_mfma_f32_16x16x32_f16 v[76:79], v[206:209], v[242:245], v[76:79]
	v_mfma_f32_16x16x32_f16 v[72:75], v[214:217], v[230:233], v[72:75]
	v_mfma_f32_16x16x32_f16 v[68:71], v[214:217], v[242:245], v[68:71]
	v_mfma_f32_16x16x32_f16 v[96:99], v[194:197], v[238:241], v[96:99]
	v_mfma_f32_16x16x32_f16 v[92:95], v[194:197], v[246:249], v[92:95]
	v_mfma_f32_16x16x32_f16 v[88:91], v[202:205], v[238:241], v[88:91]
	v_mfma_f32_16x16x32_f16 v[84:87], v[202:205], v[246:249], v[84:87]
	v_mfma_f32_16x16x32_f16 v[80:83], v[210:213], v[238:241], v[80:83]
	v_mfma_f32_16x16x32_f16 v[76:79], v[210:213], v[246:249], v[76:79]
	v_mfma_f32_16x16x32_f16 v[72:75], v[218:221], v[238:241], v[72:75]
	v_mfma_f32_16x16x32_f16 v[68:71], v[218:221], v[246:249], v[68:71]
	v_lshl_add_u64 v[222:223], v[222:223], 0, s[22:23]
	s_or_b32 m0, s100, 0x8000
	s_barrier
	ds_read_b128 v[190:193], v156 offset:49152
	ds_read_b128 v[194:197], v156 offset:50176
	ds_read_b128 v[198:201], v154 offset:49152
	ds_read_b128 v[202:205], v154 offset:50176
	ds_read_b128 v[206:209], v153 offset:49152
	ds_read_b128 v[210:213], v153 offset:50176
	ds_read_b128 v[214:217], v152 offset:49152
	ds_read_b128 v[218:221], v152 offset:50176
	global_load_lds_dwordx4 v[222:223], off
	s_or_b32 m0, s100, 0xa000
	v_lshl_add_u64 v[222:223], v[226:227], 0, s[22:23]
	global_load_lds_dwordx4 v[222:223], off
	s_barrier
	s_waitcnt lgkmcnt(0)
	v_mfma_f32_16x16x32_f16 v[64:67], v[190:193], v[174:177], v[64:67]
	v_mfma_f32_16x16x32_f16 v[60:63], v[190:193], v[182:185], v[60:63]
	v_mfma_f32_16x16x32_f16 v[56:59], v[198:201], v[174:177], v[56:59]
	v_mfma_f32_16x16x32_f16 v[52:55], v[198:201], v[182:185], v[52:55]
	v_mfma_f32_16x16x32_f16 v[48:51], v[206:209], v[174:177], v[48:51]
	v_mfma_f32_16x16x32_f16 v[44:47], v[206:209], v[182:185], v[44:47]
	v_mfma_f32_16x16x32_f16 v[40:43], v[214:217], v[174:177], v[40:43]
	v_mfma_f32_16x16x32_f16 v[36:39], v[214:217], v[182:185], v[36:39]
	v_mfma_f32_16x16x32_f16 v[64:67], v[194:197], v[178:181], v[64:67]
	v_mfma_f32_16x16x32_f16 v[60:63], v[194:197], v[186:189], v[60:63]
	v_mfma_f32_16x16x32_f16 v[56:59], v[202:205], v[178:181], v[56:59]
	v_mfma_f32_16x16x32_f16 v[52:55], v[202:205], v[186:189], v[52:55]
	v_mfma_f32_16x16x32_f16 v[48:51], v[210:213], v[178:181], v[48:51]
	v_mfma_f32_16x16x32_f16 v[44:47], v[210:213], v[186:189], v[44:47]
	v_mfma_f32_16x16x32_f16 v[40:43], v[218:221], v[178:181], v[40:43]
	v_mfma_f32_16x16x32_f16 v[36:39], v[218:221], v[186:189], v[36:39]
	s_barrier
	s_or_b32 m0, s100, 0x1c000
	v_lshl_add_u64 v[174:175], v[228:229], 0, s[66:67]
	global_load_lds_dwordx4 v[174:175], off
	s_or_b32 m0, s100, 0x1e000
	v_lshl_add_u64 v[174:175], v[236:237], 0, s[66:67]
	global_load_lds_dwordx4 v[174:175], off
	s_waitcnt vmcnt(6)
	s_barrier
	v_mfma_f32_16x16x32_f16 v[32:35], v[190:193], v[230:233], v[32:35]
	v_mfma_f32_16x16x32_f16 v[28:31], v[190:193], v[242:245], v[28:31]
	v_mfma_f32_16x16x32_f16 v[24:27], v[198:201], v[230:233], v[24:27]
	v_mfma_f32_16x16x32_f16 v[20:23], v[198:201], v[242:245], v[20:23]
	v_mfma_f32_16x16x32_f16 v[16:19], v[206:209], v[230:233], v[16:19]
	v_mfma_f32_16x16x32_f16 v[12:15], v[206:209], v[242:245], v[12:15]
	v_mfma_f32_16x16x32_f16 v[8:11], v[214:217], v[230:233], v[8:11]
	v_mfma_f32_16x16x32_f16 v[4:7], v[214:217], v[242:245], v[4:7]
	v_mfma_f32_16x16x32_f16 v[32:35], v[194:197], v[238:241], v[32:35]
	v_mfma_f32_16x16x32_f16 v[28:31], v[194:197], v[246:249], v[28:31]
	v_mfma_f32_16x16x32_f16 v[24:27], v[202:205], v[238:241], v[24:27]
	v_mfma_f32_16x16x32_f16 v[20:23], v[202:205], v[246:249], v[20:23]
	v_mfma_f32_16x16x32_f16 v[16:19], v[210:213], v[238:241], v[16:19]
	v_mfma_f32_16x16x32_f16 v[12:15], v[210:213], v[246:249], v[12:15]
	v_mfma_f32_16x16x32_f16 v[8:11], v[218:221], v[238:241], v[8:11]
	v_mfma_f32_16x16x32_f16 v[4:7], v[218:221], v[246:249], v[4:7]
	s_add_i32 s14, s14, 2
	s_add_u32 s12, s12, 0x100
	s_addc_u32 s13, s13, 0
	s_cmp_lt_u32 s14, 12
	s_cbranch_scc0 .Lpk_exitb_0

; DI int tid_opaque() { int t = threadIdx.x; asm volatile("" : "+v"(t)); return t; }
; #define LDA8(dst, b, h) _Pragma("unroll") for (int m = 0; m < 4; ++m) _Pragma("unroll") for (int k = 0; k < 2; ++k) \
;     dst[m][k] = *(const bf16x8*)((const char*)SA8(b, h) + lds_byte8(wr * 64 + m * 16 + fr, k * 32 + fq * 8))
; #define LDB8(dst, b, h) _Pragma("unroll") for (int n = 0; n < 2; ++n) _Pragma("unroll") for (int k = 0; k < 2; ++k) \
;     dst[n][k] = *(const bf16x8*)((const char*)SB8(b, h) + lds_byte8(wc * 32 + n * 16 + fr, k * 32 + fq * 8))
; #define WAIT_V8(n) asm volatile("s_waitcnt vmcnt(" #n ")" ::: "memory")
; #define BAR8 __builtin_amdgcn_s_barrier()
; #define SCHED8 __builtin_amdgcn_sched_barrier(0)
;   constexpr int HT = 128 * 64;
;   bf16_t* shm = (bf16_t*)smem;
;   const int t = tid_opaque();
;     ...
;   const int nt = K / 64;
;   if (!pre) {
;     STAGE8(SB8(0, 0), Bt, K, bcol, 0); STAGE8(SA8(0, 0), A, lda, brow, 0);
;     STAGE8(SB8(0, 1), Bt, K, bcol + 128, 0); STAGE8(SA8(0, 1), A, lda, brow + 128, 0);
;   }
;   if (wr == 1) BAR8;
;   WAIT_V8(4); BAR8;
;   STAGE8(SB8(1, 0), Bt, K, bcol, 1); STAGE8(SA8(1, 0), A, lda, brow, 1); STAGE8(SB8(1, 1), Bt, K, bcol + 128, 1);
;   WAIT_V8(6); BAR8;
;   for (int tt = 0; tt < nt - 2; tt += 2) {
;     LDB8(B0, 0, 0); SCHED8; LDA8(At, 0, 0); STAGE8(SA8(1, 1), A, lda, brow + 128, tt + 1);
.LBB0_238:
	s_and_b64 vcc, exec, s[0:1]
	s_cbranch_vccz .LBB0_187
	s_mov_b32 s0, 25
	s_ashr_i32 s1, s0, 31
	s_lshl_b64 s[0:1], s[0:1], 3
	s_add_u32 s0, s70, s0
	s_addc_u32 s1, s71, s1
	v_readlane_b32 s2, v255, 60
	v_readlane_b32 s3, v255, 61
	s_nop 4
	s_mov_b32 s0, 25
	s_ashr_i32 s1, s0, 31
	s_lshl_b64 s[0:1], s[0:1], 3
	s_add_u32 s0, s70, s0
	s_addc_u32 s1, s71, s1
	v_readlane_b32 s4, v255, 60
	v_readlane_b32 s5, v255, 61
	s_nop 4
	s_mov_b32 s0, 25
	s_ashr_i32 s1, s0, 31
	s_lshl_b64 s[0:1], s[0:1], 3
	s_add_u32 s0, s70, s0
	s_addc_u32 s1, s71, s1
	v_mov_b32_e32 v3, v224
	v_readlane_b32 s14, v255, 60
	v_readlane_b32 s15, v255, 61
	s_nop 4
	s_ashr_i32 s53, s52, 31
	v_bfe_i32 v1, v3, 27, 1
	s_waitcnt vmcnt(10)
	v_lshlrev_b32_e32 v150, 4, v3
	s_nop 0
	v_readfirstlane_b32 s100, v150
	v_lshrrev_b32_e32 v1, 22, v1
	v_add_u32_e32 v1, v150, v1
	v_and_b32_e32 v1, 0xfffffc00, v1
	v_ashrrev_i32_e32 v0, 31, v3
	v_sub_u32_e32 v1, v150, v1
	v_lshrrev_b32_e32 v0, 26, v0
	v_lshrrev_b32_e32 v5, 4, v1
	v_add_u32_e32 v0, v3, v0
	v_bitop3_b32 v5, v5, v1, 32 bitop3:0x6c
	v_ashrrev_i32_e32 v1, 31, v1
	v_ashrrev_i32_e32 v0, 6, v0
	v_lshrrev_b32_e32 v1, 26, v1
	v_lshlrev_b32_e32 v6, 3, v0
	v_add_u32_e32 v1, v5, v1
	v_and_b32_e32 v6, -16, v6
	v_ashrrev_i32_e32 v1, 6, v1
	v_add_u32_e32 v6, v1, v6
	v_mul_i32_i24_e32 v1, 64, v1
	v_lshlrev_b32_e32 v0, 5, v0
	v_sub_u32_e32 v1, v5, v1
	v_mov_b32_e32 v14, 1
	s_waitcnt vmcnt(9)
	s_lshl_b64 s[0:1], s[52:53], 11
	v_readlane_b32 s27, v254, 44
	v_and_b32_e32 v0, 32, v0
	v_ashrrev_i16_sdwa v1, v14, sext(v1) dst_sel:DWORD dst_unused:UNUSED_PAD src0_sel:DWORD src1_sel:BYTE_0
	s_add_u32 s0, s27, s0
	v_readlane_b32 s29, v254, 45
	v_add_u32_sdwa v0, v0, sext(v1) dst_sel:DWORD dst_unused:UNUSED_PAD src0_sel:DWORD src1_sel:WORD_0
	v_ashrrev_i32_e32 v7, 31, v6
	s_addc_u32 s1, s29, s1
	v_lshlrev_b64 v[132:133], 11, v[6:7]
	v_ashrrev_i32_e32 v1, 31, v0
	v_lshl_add_u64 v[8:9], s[0:1], 0, v[132:133]
	v_lshlrev_b64 v[6:7], 1, v[0:1]
	v_lshl_add_u64 v[10:11], v[8:9], 0, v[6:7]
	v_lshrrev_b32_e32 v134, 1, v6
	v_add_u32_e32 v136, 0x20000, v132
	v_mov_b32_e32 v137, v133
	s_waitcnt vmcnt(8)
	s_or_b32 m0, s100, 0x10000
	v_lshl_add_u64 v[12:13], s[0:1], 0, v[136:137]
	global_load_lds_dwordx4 v[10:11], off
	s_or_b32 m0, s100, 0x12000
	s_lshl_b32 s0, s20, 19
	v_mov_b32_e32 v135, v7
	s_waitcnt lgkmcnt(0)
	s_add_u32 s12, s14, s0
	v_mov_b64_e32 v[8:9], v[6:7]
	s_addc_u32 s13, s15, 0
	v_lshl_add_u64 v[12:13], v[12:13], 0, v[8:9]
	v_lshl_add_u64 v[14:15], s[12:13], 0, v[132:133]
	global_load_lds_dwordx4 v[12:13], off
	s_mov_b32 m0, s100
	v_lshl_add_u64 v[14:15], v[14:15], 0, v[6:7]
	global_load_lds_dwordx4 v[14:15], off
	s_or_b32 m0, s100, 0x2000
	s_or_b32 s0, s52, 0x80
	s_ashr_i32 s1, s0, 31
	s_lshl_b64 s[20:21], s[0:1], 11
	s_add_u32 s20, s27, s20
	v_lshl_add_u64 v[16:17], s[12:13], 0, v[136:137]
	s_addc_u32 s21, s29, s21
	v_lshl_add_u64 v[16:17], v[16:17], 0, v[8:9]
	v_lshl_add_u64 v[18:19], s[20:21], 0, v[132:133]
	v_lshl_add_u64 v[20:21], s[20:21], 0, v[136:137]
	s_add_u32 s20, s12, 0x40000
	global_load_lds_dwordx4 v[16:17], off
	v_lshl_add_u64 v[18:19], v[18:19], 0, v[6:7]
	s_addc_u32 s21, s13, 0
	s_or_b32 m0, s100, 0x14000
	s_nop 0
	global_load_lds_dwordx4 v[18:19], off
	v_lshl_add_u64 v[20:21], v[20:21], 0, v[8:9]
	s_or_b32 m0, s100, 0x16000
	v_lshl_add_u64 v[22:23], s[20:21], 0, v[132:133]
	global_load_lds_dwordx4 v[20:21], off
	v_lshl_add_u64 v[22:23], v[22:23], 0, v[6:7]
	s_or_b32 m0, s100, 0x4000
	s_nop 0
	global_load_lds_dwordx4 v[22:23], off
	v_lshl_add_u64 v[22:23], s[20:21], 0, v[136:137]
	v_lshl_add_u64 v[22:23], v[22:23], 0, v[8:9]
	s_or_b32 m0, s100, 0x6000
	v_ashrrev_i32_e32 v5, 8, v3
	global_load_lds_dwordx4 v[22:23], off
	v_cmp_eq_u32_e32 vcc, 1, v5
	s_and_saveexec_b64 s[20:21], vcc
	s_cbranch_execz .LBB0_241
	s_barrier
.LBB0_241:
	s_or_b64 exec, exec, s[20:21]
	s_mov_b64 s[20:21], 0x80
	v_lshl_add_u64 v[10:11], v[10:11], 0, s[20:21]
	s_or_b32 m0, s100, 0x18000
	s_waitcnt vmcnt(4)
	s_barrier
	global_load_lds_dwordx4 v[10:11], off
	v_lshl_add_u64 v[10:11], v[12:13], 0, s[20:21]
	s_or_b32 m0, s100, 0x1a000
	s_nop 0
	global_load_lds_dwordx4 v[10:11], off
	v_lshl_add_u64 v[10:11], v[14:15], 0, s[20:21]
	s_or_b32 m0, s100, 0x8000
	s_nop 0
	global_load_lds_dwordx4 v[10:11], off
	v_lshl_add_u64 v[10:11], v[16:17], 0, s[20:21]
	s_or_b32 m0, s100, 0xa000
	s_nop 0
	global_load_lds_dwordx4 v[10:11], off
	s_or_b32 m0, s100, 0x1c000
	v_lshl_add_u64 v[10:11], v[18:19], 0, s[20:21]
	global_load_lds_dwordx4 v[10:11], off
	v_lshl_add_u64 v[10:11], v[20:21], 0, s[20:21]
	s_or_b32 m0, s100, 0x1e000
	v_and_b32_e32 v147, 15, v3
	global_load_lds_dwordx4 v[10:11], off
	v_bfe_u32 v148, v3, 4, 2
	v_lshlrev_b32_e32 v10, 4, v148
	v_lshlrev_b32_e32 v11, 6, v147
	v_lshlrev_b32_e32 v14, 2, v3
	v_or_b32_e32 v13, v10, v11
	v_and_b32_e32 v14, 32, v14
	s_mov_b32 s1, 0x10000
	v_bitop3_b32 v16, v13, s1, v14 bitop3:0xde
	s_mov_b32 s1, 0x14000
	v_bitop3_b32 v15, v10, v14, v11 bitop3:0x36
	v_bitop3_b32 v17, v13, s1, v14 bitop3:0xde
	s_mov_b32 s1, 0x18000
	v_lshlrev_b32_e32 v11, 6, v3
	v_bitop3_b32 v18, v13, s1, v14 bitop3:0xde
	s_mov_b32 s1, 0x1c000
	v_and_b32_e32 v11, 0x3c0, v11
	v_bitop3_b32 v13, v13, s1, v14 bitop3:0xde
	v_bitop3_b32 v14, v11, v14, v10 bitop3:0x36
	v_lshl_add_u64 v[10:11], s[30:31], 0, v[136:137]
	v_lshl_add_u64 v[10:11], v[10:11], 0, v[8:9]
	v_lshl_add_u64 v[138:139], s[14:15], 0, v[10:11]
	v_lshl_add_u64 v[10:11], s[30:31], 0, v[132:133]
	v_lshl_add_u64 v[10:11], v[10:11], 0, v[6:7]
	v_lshl_add_u64 v[140:141], s[14:15], 0, v[10:11]
	v_lshl_add_u64 v[10:11], s[56:57], 0, v[132:133]
	v_lshl_add_u64 v[6:7], v[10:11], 0, v[6:7]
	v_bfe_u32 v146, v3, 6, 2
	s_waitcnt vmcnt(6)
	v_lshlrev_b32_e32 v149, 6, v5
	v_lshlrev_b32_e32 v5, 13, v5
	v_lshl_add_u64 v[142:143], s[46:47], 0, v[6:7]
	v_lshl_add_u64 v[6:7], s[56:57], 0, v[136:137]
	v_lshlrev_b32_e32 v12, 12, v146
	v_or_b32_e32 v19, 0x800, v5
	v_or_b32_e32 v20, 0x1000, v5
	v_or_b32_e32 v21, 0x1800, v5
	v_lshl_add_u64 v[6:7], v[6:7], 0, v[8:9]
	v_lshl_add_u64 v[144:145], s[46:47], 0, v[6:7]
	s_mov_b32 s1, -2
	s_mov_b64 s[14:15], 0
	v_add_u32_e32 v171, v16, v12
	v_add_u32_e32 v156, v15, v5
	v_add_u32_e32 v154, v14, v19
	v_add_u32_e32 v153, v14, v20
	v_add_u32_e32 v152, v14, v21
	v_add_u32_e32 v168, v17, v12
	v_add_u32_e32 v159, v18, v12
	v_add_u32_e32 v157, v13, v12
	s_mov_b64 s[30:31], 0xc000100
	s_mov_b64 s[56:57], 0xc040100
	s_mov_b64 s[58:59], 0xc000180
	s_mov_b64 s[60:61], 0xc040180
	s_barrier
; #define LDA8(dst, b, h) _Pragma("unroll") for (int m = 0; m < 4; ++m) _Pragma("unroll") for (int k = 0; k < 2; ++k) \
;     dst[m][k] = *(const bf16x8*)((const char*)SA8(b, h) + lds_byte8(wr * 64 + m * 16 + fr, k * 32 + fq * 8))
; #define LDB8(dst, b, h) _Pragma("unroll") for (int n = 0; n < 2; ++n) _Pragma("unroll") for (int k = 0; k < 2; ++k) \
;     dst[n][k] = *(const bf16x8*)((const char*)SB8(b, h) + lds_byte8(wc * 32 + n * 16 + fr, k * 32 + fq * 8))
; #define WAIT_V8(n) asm volatile("s_waitcnt vmcnt(" #n ")" ::: "memory")
; #define WAIT_L8(n) asm volatile("s_waitcnt lgkmcnt(" #n ")" ::: "memory")
; #define BAR8 __builtin_amdgcn_s_barrier()
; #define SCHED8 __builtin_amdgcn_sched_barrier(0)
;     ...
;   for (int tt = 0; tt < nt - 2; tt += 2) {
;     LDB8(B0, 0, 0); SCHED8; LDA8(At, 0, 0); STAGE8(SA8(1, 1), A, lda, brow + 128, tt + 1);
;     WAIT_L8(8); BAR8; WAIT_L8(0); MMA8(0, 0, At, B0); BAR8; SCHED8;
;     LDB8(B1, 0, 1); STAGE8(SB8(0, 0), Bt, K, bcol, tt + 2);
;     BAR8; WAIT_L8(0); MMA8(0, 1, At, B1); BAR8;
;     LDA8(At, 0, 1); STAGE8(SA8(0, 0), A, lda, brow, tt + 2);
;     BAR8; WAIT_L8(0); MMA8(1, 0, At, B0); BAR8; SCHED8;
;     STAGE8(SB8(0, 1), Bt, K, bcol + 128, tt + 2);
;     WAIT_V8(6); BAR8; MMA8(1, 1, At, B1); BAR8;
	ds_read_b128 v[174:177], v171
	ds_read_b128 v[178:181], v171 offset:1024
	ds_read_b128 v[182:185], v171 offset:2048
	ds_read_b128 v[186:189], v171 offset:3072
	v_lshl_add_u64 v[222:223], v[140:141], 0, s[14:15]
	v_lshl_add_u64 v[226:227], v[222:223], 0, s[34:35]
	s_or_b32 m0, s100, 0xc000
	ds_read_b128 v[190:193], v156
	ds_read_b128 v[194:197], v156 offset:1024
	ds_read_b128 v[198:201], v154
	ds_read_b128 v[202:205], v154 offset:1024
	ds_read_b128 v[206:209], v153
	ds_read_b128 v[210:213], v153 offset:1024
	ds_read_b128 v[214:217], v152
	ds_read_b128 v[218:221], v152 offset:1024
	global_load_lds_dwordx4 v[226:227], off
	v_lshl_add_u64 v[226:227], v[138:139], 0, s[14:15]
	s_or_b32 m0, s100, 0xe000
	v_lshl_add_u64 v[228:229], v[226:227], 0, s[34:35]
	global_load_lds_dwordx4 v[228:229], off
	s_waitcnt lgkmcnt(8)
	s_barrier
	s_waitcnt lgkmcnt(0)
	v_mfma_f32_16x16x32_f16 v[128:131], v[190:193], v[174:177], 0
	v_mfma_f32_16x16x32_f16 v[124:127], v[190:193], v[182:185], 0
	v_mfma_f32_16x16x32_f16 v[120:123], v[198:201], v[174:177], 0
	v_mfma_f32_16x16x32_f16 v[116:119], v[198:201], v[182:185], 0
	v_mfma_f32_16x16x32_f16 v[112:115], v[206:209], v[174:177], 0
	v_mfma_f32_16x16x32_f16 v[108:111], v[206:209], v[182:185], 0
	v_mfma_f32_16x16x32_f16 v[104:107], v[214:217], v[174:177], 0
	v_mfma_f32_16x16x32_f16 v[100:103], v[214:217], v[182:185], 0
	v_mfma_f32_16x16x32_f16 v[128:131], v[194:197], v[178:181], v[128:131]
	v_mfma_f32_16x16x32_f16 v[124:127], v[194:197], v[186:189], v[124:127]
	v_mfma_f32_16x16x32_f16 v[120:123], v[202:205], v[178:181], v[120:123]
	v_mfma_f32_16x16x32_f16 v[116:119], v[202:205], v[186:189], v[116:119]
	v_mfma_f32_16x16x32_f16 v[112:115], v[210:213], v[178:181], v[112:115]
	v_mfma_f32_16x16x32_f16 v[108:111], v[210:213], v[186:189], v[108:111]
	v_mfma_f32_16x16x32_f16 v[104:107], v[218:221], v[178:181], v[104:107]
	v_mfma_f32_16x16x32_f16 v[100:103], v[218:221], v[186:189], v[100:103]
	s_barrier
	v_lshl_add_u64 v[228:229], v[142:143], 0, s[14:15]
	v_lshl_add_u64 v[236:237], v[228:229], 0, s[30:31]
	s_or_b32 m0, s100, 0x10000
	ds_read_b128 v[230:233], v168
	ds_read_b128 v[238:241], v168 offset:1024
	ds_read_b128 v[242:245], v168 offset:2048
	ds_read_b128 v[246:249], v168 offset:3072
	global_load_lds_dwordx4 v[236:237], off
	v_lshl_add_u64 v[236:237], v[144:145], 0, s[14:15]
	s_or_b32 m0, s100, 0x12000
	v_lshl_add_u64 v[250:251], v[236:237], 0, s[30:31]
	global_load_lds_dwordx4 v[250:251], off
	s_barrier
	s_waitcnt lgkmcnt(0)
	v_mfma_f32_16x16x32_f16 v[96:99], v[190:193], v[230:233], 0
	v_mfma_f32_16x16x32_f16 v[92:95], v[190:193], v[242:245], 0
	v_mfma_f32_16x16x32_f16 v[88:91], v[198:201], v[230:233], 0
	v_mfma_f32_16x16x32_f16 v[84:87], v[198:201], v[242:245], 0
	v_mfma_f32_16x16x32_f16 v[80:83], v[206:209], v[230:233], 0
	v_mfma_f32_16x16x32_f16 v[76:79], v[206:209], v[242:245], 0
	v_mfma_f32_16x16x32_f16 v[72:75], v[214:217], v[230:233], 0
	v_mfma_f32_16x16x32_f16 v[68:71], v[214:217], v[242:245], 0
	v_mfma_f32_16x16x32_f16 v[96:99], v[194:197], v[238:241], v[96:99]
	v_mfma_f32_16x16x32_f16 v[92:95], v[194:197], v[246:249], v[92:95]
	v_mfma_f32_16x16x32_f16 v[88:91], v[202:205], v[238:241], v[88:91]
	v_mfma_f32_16x16x32_f16 v[84:87], v[202:205], v[246:249], v[84:87]
	v_mfma_f32_16x16x32_f16 v[80:83], v[210:213], v[238:241], v[80:83]
	v_mfma_f32_16x16x32_f16 v[76:79], v[210:213], v[246:249], v[76:79]
	v_mfma_f32_16x16x32_f16 v[72:75], v[218:221], v[238:241], v[72:75]
	v_mfma_f32_16x16x32_f16 v[68:71], v[218:221], v[246:249], v[68:71]
	v_lshl_add_u64 v[250:251], v[222:223], 0, s[10:11]
	s_mov_b32 m0, s100
	s_barrier
	ds_read_b128 v[190:193], v156 offset:16384
	ds_read_b128 v[194:197], v156 offset:17408
	ds_read_b128 v[198:201], v154 offset:16384
	ds_read_b128 v[202:205], v154 offset:17408
	ds_read_b128 v[206:209], v153 offset:16384
	ds_read_b128 v[210:213], v153 offset:17408
	ds_read_b128 v[214:217], v152 offset:16384
	ds_read_b128 v[218:221], v152 offset:17408
	global_load_lds_dwordx4 v[250:251], off
	s_or_b32 m0, s100, 0x2000
	v_lshl_add_u64 v[250:251], v[226:227], 0, s[10:11]
	global_load_lds_dwordx4 v[250:251], off
	s_barrier
	s_waitcnt lgkmcnt(0)
	v_mfma_f32_16x16x32_f16 v[64:67], v[190:193], v[174:177], 0
	v_mfma_f32_16x16x32_f16 v[60:63], v[190:193], v[182:185], 0
	v_mfma_f32_16x16x32_f16 v[56:59], v[198:201], v[174:177], 0
	v_mfma_f32_16x16x32_f16 v[52:55], v[198:201], v[182:185], 0
	v_mfma_f32_16x16x32_f16 v[48:51], v[206:209], v[174:177], 0
	v_mfma_f32_16x16x32_f16 v[44:47], v[206:209], v[182:185], 0
	v_mfma_f32_16x16x32_f16 v[40:43], v[214:217], v[174:177], 0
	v_mfma_f32_16x16x32_f16 v[36:39], v[214:217], v[182:185], 0
	v_mfma_f32_16x16x32_f16 v[64:67], v[194:197], v[178:181], v[64:67]
	v_mfma_f32_16x16x32_f16 v[60:63], v[194:197], v[186:189], v[60:63]
	v_mfma_f32_16x16x32_f16 v[56:59], v[202:205], v[178:181], v[56:59]
	v_mfma_f32_16x16x32_f16 v[52:55], v[202:205], v[186:189], v[52:55]
	v_mfma_f32_16x16x32_f16 v[48:51], v[210:213], v[178:181], v[48:51]
	v_mfma_f32_16x16x32_f16 v[44:47], v[210:213], v[186:189], v[44:47]
	v_mfma_f32_16x16x32_f16 v[40:43], v[218:221], v[178:181], v[40:43]
	v_mfma_f32_16x16x32_f16 v[36:39], v[218:221], v[186:189], v[36:39]
	s_barrier
	s_or_b32 m0, s100, 0x14000
	v_lshl_add_u64 v[174:175], v[228:229], 0, s[56:57]
	global_load_lds_dwordx4 v[174:175], off
	s_or_b32 m0, s100, 0x16000
	v_lshl_add_u64 v[174:175], v[236:237], 0, s[56:57]
	global_load_lds_dwordx4 v[174:175], off
	s_waitcnt vmcnt(6)
	s_barrier
; #define LDA8(dst, b, h) _Pragma("unroll") for (int m = 0; m < 4; ++m) _Pragma("unroll") for (int k = 0; k < 2; ++k) \
;     dst[m][k] = *(const bf16x8*)((const char*)SA8(b, h) + lds_byte8(wr * 64 + m * 16 + fr, k * 32 + fq * 8))
; #define LDB8(dst, b, h) _Pragma("unroll") for (int n = 0; n < 2; ++n) _Pragma("unroll") for (int k = 0; k < 2; ++k) \
;     dst[n][k] = *(const bf16x8*)((const char*)SB8(b, h) + lds_byte8(wc * 32 + n * 16 + fr, k * 32 + fq * 8))
; #define WAIT_V8(n) asm volatile("s_waitcnt vmcnt(" #n ")" ::: "memory")
; #define WAIT_L8(n) asm volatile("s_waitcnt lgkmcnt(" #n ")" ::: "memory")
; #define BAR8 __builtin_amdgcn_s_barrier()
; #define SCHED8 __builtin_amdgcn_sched_barrier(0)
;     ...
;     WAIT_V8(6); BAR8; MMA8(1, 1, At, B1); BAR8;
;     LDB8(B0, 1, 0); SCHED8; LDA8(At, 1, 0); STAGE8(SA8(0, 1), A, lda, brow + 128, tt + 2);
;     WAIT_L8(8); BAR8; WAIT_L8(0); MMA8(0, 0, At, B0); BAR8; SCHED8;
;     LDB8(B1, 1, 1); STAGE8(SB8(1, 0), Bt, K, bcol, tt + 3);
;     BAR8; WAIT_L8(0); MMA8(0, 1, At, B1); BAR8;
	v_mfma_f32_16x16x32_f16 v[32:35], v[190:193], v[230:233], 0
	v_mfma_f32_16x16x32_f16 v[28:31], v[190:193], v[242:245], 0
	v_mfma_f32_16x16x32_f16 v[24:27], v[198:201], v[230:233], 0
	v_mfma_f32_16x16x32_f16 v[20:23], v[198:201], v[242:245], 0
	v_mfma_f32_16x16x32_f16 v[16:19], v[206:209], v[230:233], 0
	v_mfma_f32_16x16x32_f16 v[12:15], v[206:209], v[242:245], 0
	v_mfma_f32_16x16x32_f16 v[8:11], v[214:217], v[230:233], 0
	v_mfma_f32_16x16x32_f16 v[4:7], v[214:217], v[242:245], 0
	v_mfma_f32_16x16x32_f16 v[32:35], v[194:197], v[238:241], v[32:35]
	v_mfma_f32_16x16x32_f16 v[28:31], v[194:197], v[246:249], v[28:31]
	v_mfma_f32_16x16x32_f16 v[24:27], v[202:205], v[238:241], v[24:27]
	v_mfma_f32_16x16x32_f16 v[20:23], v[202:205], v[246:249], v[20:23]
	v_mfma_f32_16x16x32_f16 v[16:19], v[210:213], v[238:241], v[16:19]
	v_mfma_f32_16x16x32_f16 v[12:15], v[210:213], v[246:249], v[12:15]
	v_mfma_f32_16x16x32_f16 v[8:11], v[218:221], v[238:241], v[8:11]
	v_mfma_f32_16x16x32_f16 v[4:7], v[218:221], v[246:249], v[4:7]
	s_barrier
	ds_read_b128 v[174:177], v159
	ds_read_b128 v[178:181], v159 offset:1024
	ds_read_b128 v[182:185], v159 offset:2048
	ds_read_b128 v[186:189], v159 offset:3072
	v_lshl_add_u64 v[230:231], v[222:223], 0, s[18:19]
	s_or_b32 m0, s100, 0x4000
	ds_read_b128 v[190:193], v156 offset:32768
	ds_read_b128 v[194:197], v156 offset:33792
	ds_read_b128 v[198:201], v154 offset:32768
	ds_read_b128 v[202:205], v154 offset:33792
	ds_read_b128 v[206:209], v153 offset:32768
	ds_read_b128 v[210:213], v153 offset:33792
	ds_read_b128 v[214:217], v152 offset:32768
	ds_read_b128 v[218:221], v152 offset:33792
	global_load_lds_dwordx4 v[230:231], off
	s_or_b32 m0, s100, 0x6000
	v_lshl_add_u64 v[230:231], v[226:227], 0, s[18:19]
	global_load_lds_dwordx4 v[230:231], off
	s_waitcnt lgkmcnt(8)
	s_barrier
	s_waitcnt lgkmcnt(0)
	v_mfma_f32_16x16x32_f16 v[128:131], v[190:193], v[174:177], v[128:131]
	v_mfma_f32_16x16x32_f16 v[124:127], v[190:193], v[182:185], v[124:127]
	v_mfma_f32_16x16x32_f16 v[120:123], v[198:201], v[174:177], v[120:123]
	v_mfma_f32_16x16x32_f16 v[116:119], v[198:201], v[182:185], v[116:119]
	v_mfma_f32_16x16x32_f16 v[112:115], v[206:209], v[174:177], v[112:115]
	v_mfma_f32_16x16x32_f16 v[108:111], v[206:209], v[182:185], v[108:111]
	v_mfma_f32_16x16x32_f16 v[104:107], v[214:217], v[174:177], v[104:107]
	v_mfma_f32_16x16x32_f16 v[100:103], v[214:217], v[182:185], v[100:103]
	v_mfma_f32_16x16x32_f16 v[128:131], v[194:197], v[178:181], v[128:131]
	v_mfma_f32_16x16x32_f16 v[124:127], v[194:197], v[186:189], v[124:127]
	v_mfma_f32_16x16x32_f16 v[120:123], v[202:205], v[178:181], v[120:123]
	v_mfma_f32_16x16x32_f16 v[116:119], v[202:205], v[186:189], v[116:119]
	v_mfma_f32_16x16x32_f16 v[112:115], v[210:213], v[178:181], v[112:115]
	v_mfma_f32_16x16x32_f16 v[108:111], v[210:213], v[186:189], v[108:111]
	v_mfma_f32_16x16x32_f16 v[104:107], v[218:221], v[178:181], v[104:107]
	v_mfma_f32_16x16x32_f16 v[100:103], v[218:221], v[186:189], v[100:103]
	s_barrier
	v_lshl_add_u64 v[250:251], v[228:229], 0, s[58:59]
	s_or_b32 m0, s100, 0x18000
	ds_read_b128 v[230:233], v157
	ds_read_b128 v[238:241], v157 offset:1024
	ds_read_b128 v[242:245], v157 offset:2048
	ds_read_b128 v[246:249], v157 offset:3072
	global_load_lds_dwordx4 v[250:251], off
	s_or_b32 m0, s100, 0x1a000
	v_lshl_add_u64 v[250:251], v[236:237], 0, s[58:59]
	global_load_lds_dwordx4 v[250:251], off
	s_barrier
; #define LDA8(dst, b, h) _Pragma("unroll") for (int m = 0; m < 4; ++m) _Pragma("unroll") for (int k = 0; k < 2; ++k) \
;     dst[m][k] = *(const bf16x8*)((const char*)SA8(b, h) + lds_byte8(wr * 64 + m * 16 + fr, k * 32 + fq * 8))
; #define WAIT_V8(n) asm volatile("s_waitcnt vmcnt(" #n ")" ::: "memory")
; #define WAIT_L8(n) asm volatile("s_waitcnt lgkmcnt(" #n ")" ::: "memory")
; #define BAR8 __builtin_amdgcn_s_barrier()
; #define SCHED8 __builtin_amdgcn_sched_barrier(0)
;     ...
;     BAR8; WAIT_L8(0); MMA8(0, 1, At, B1); BAR8;
;     LDA8(At, 1, 1); STAGE8(SA8(1, 0), A, lda, brow, tt + 3);
;     BAR8; WAIT_L8(0); MMA8(1, 0, At, B0); BAR8; SCHED8;
;     STAGE8(SB8(1, 1), Bt, K, bcol + 128, tt + 3);
;     WAIT_V8(6); BAR8; MMA8(1, 1, At, B1); BAR8;
;   }
	s_waitcnt lgkmcnt(0)
	v_mfma_f32_16x16x32_f16 v[96:99], v[190:193], v[230:233], v[96:99]
	v_mfma_f32_16x16x32_f16 v[92:95], v[190:193], v[242:245], v[92:95]
	v_mfma_f32_16x16x32_f16 v[88:91], v[198:201], v[230:233], v[88:91]
	v_mfma_f32_16x16x32_f16 v[84:87], v[198:201], v[242:245], v[84:87]
	v_mfma_f32_16x16x32_f16 v[80:83], v[206:209], v[230:233], v[80:83]
	v_mfma_f32_16x16x32_f16 v[76:79], v[206:209], v[242:245], v[76:79]
	v_mfma_f32_16x16x32_f16 v[72:75], v[214:217], v[230:233], v[72:75]
	v_mfma_f32_16x16x32_f16 v[68:71], v[214:217], v[242:245], v[68:71]
	v_mfma_f32_16x16x32_f16 v[96:99], v[194:197], v[238:241], v[96:99]
	v_mfma_f32_16x16x32_f16 v[92:95], v[194:197], v[246:249], v[92:95]
	v_mfma_f32_16x16x32_f16 v[88:91], v[202:205], v[238:241], v[88:91]
	v_mfma_f32_16x16x32_f16 v[84:87], v[202:205], v[246:249], v[84:87]
	v_mfma_f32_16x16x32_f16 v[80:83], v[210:213], v[238:241], v[80:83]
	v_mfma_f32_16x16x32_f16 v[76:79], v[210:213], v[246:249], v[76:79]
	v_mfma_f32_16x16x32_f16 v[72:75], v[218:221], v[238:241], v[72:75]
	v_mfma_f32_16x16x32_f16 v[68:71], v[218:221], v[246:249], v[68:71]
	v_lshl_add_u64 v[222:223], v[222:223], 0, s[22:23]
	s_or_b32 m0, s100, 0x8000
	s_barrier
	ds_read_b128 v[190:193], v156 offset:49152
	ds_read_b128 v[194:197], v156 offset:50176
	ds_read_b128 v[198:201], v154 offset:49152
	ds_read_b128 v[202:205], v154 offset:50176
	ds_read_b128 v[206:209], v153 offset:49152
	ds_read_b128 v[210:213], v153 offset:50176
	ds_read_b128 v[214:217], v152 offset:49152
	ds_read_b128 v[218:221], v152 offset:50176
	global_load_lds_dwordx4 v[222:223], off
	s_or_b32 m0, s100, 0xa000
	v_lshl_add_u64 v[222:223], v[226:227], 0, s[22:23]
	global_load_lds_dwordx4 v[222:223], off
	s_barrier
	s_waitcnt lgkmcnt(0)
	v_mfma_f32_16x16x32_f16 v[64:67], v[190:193], v[174:177], v[64:67]
	v_mfma_f32_16x16x32_f16 v[60:63], v[190:193], v[182:185], v[60:63]
	v_mfma_f32_16x16x32_f16 v[56:59], v[198:201], v[174:177], v[56:59]
	v_mfma_f32_16x16x32_f16 v[52:55], v[198:201], v[182:185], v[52:55]
	v_mfma_f32_16x16x32_f16 v[48:51], v[206:209], v[174:177], v[48:51]
	v_mfma_f32_16x16x32_f16 v[44:47], v[206:209], v[182:185], v[44:47]
	v_mfma_f32_16x16x32_f16 v[40:43], v[214:217], v[174:177], v[40:43]
	v_mfma_f32_16x16x32_f16 v[36:39], v[214:217], v[182:185], v[36:39]
	v_mfma_f32_16x16x32_f16 v[64:67], v[194:197], v[178:181], v[64:67]
	v_mfma_f32_16x16x32_f16 v[60:63], v[194:197], v[186:189], v[60:63]
	v_mfma_f32_16x16x32_f16 v[56:59], v[202:205], v[178:181], v[56:59]
	v_mfma_f32_16x16x32_f16 v[52:55], v[202:205], v[186:189], v[52:55]
	v_mfma_f32_16x16x32_f16 v[48:51], v[210:213], v[178:181], v[48:51]
	v_mfma_f32_16x16x32_f16 v[44:47], v[210:213], v[186:189], v[44:47]
	v_mfma_f32_16x16x32_f16 v[40:43], v[218:221], v[178:181], v[40:43]
	v_mfma_f32_16x16x32_f16 v[36:39], v[218:221], v[186:189], v[36:39]
	s_barrier
	s_or_b32 m0, s100, 0x1c000
	v_lshl_add_u64 v[174:175], v[228:229], 0, s[60:61]
	global_load_lds_dwordx4 v[174:175], off
	s_or_b32 m0, s100, 0x1e000
	v_lshl_add_u64 v[174:175], v[236:237], 0, s[60:61]
	global_load_lds_dwordx4 v[174:175], off
	s_waitcnt vmcnt(6)
	s_barrier
	v_mfma_f32_16x16x32_f16 v[32:35], v[190:193], v[230:233], v[32:35]
	v_mfma_f32_16x16x32_f16 v[28:31], v[190:193], v[242:245], v[28:31]
	v_mfma_f32_16x16x32_f16 v[24:27], v[198:201], v[230:233], v[24:27]
	v_mfma_f32_16x16x32_f16 v[20:23], v[198:201], v[242:245], v[20:23]
	v_mfma_f32_16x16x32_f16 v[16:19], v[206:209], v[230:233], v[16:19]
	v_mfma_f32_16x16x32_f16 v[12:15], v[206:209], v[242:245], v[12:15]
	v_mfma_f32_16x16x32_f16 v[8:11], v[214:217], v[230:233], v[8:11]
	v_mfma_f32_16x16x32_f16 v[4:7], v[214:217], v[242:245], v[4:7]
	v_mfma_f32_16x16x32_f16 v[32:35], v[194:197], v[238:241], v[32:35]
	v_mfma_f32_16x16x32_f16 v[28:31], v[194:197], v[246:249], v[28:31]
	v_mfma_f32_16x16x32_f16 v[24:27], v[202:205], v[238:241], v[24:27]
	v_mfma_f32_16x16x32_f16 v[20:23], v[202:205], v[246:249], v[20:23]
	v_mfma_f32_16x16x32_f16 v[16:19], v[210:213], v[238:241], v[16:19]
	v_mfma_f32_16x16x32_f16 v[12:15], v[210:213], v[246:249], v[12:15]
	v_mfma_f32_16x16x32_f16 v[8:11], v[218:221], v[238:241], v[8:11]
	v_mfma_f32_16x16x32_f16 v[4:7], v[218:221], v[246:249], v[4:7]
	s_add_i32 s1, s1, 2
	s_add_u32 s14, s14, 0x100
	s_addc_u32 s15, s15, 0
	s_cmp_lt_u32 s1, 12
	s_cbranch_scc0 .Lpk_exitb_1

; #define BAR8 __builtin_amdgcn_s_barrier()
; #define G_XF (outp())
; #define G_SS ((float*)(wsp() + OFF_SS))
;     ...
;   const int nt = K / 64;
;   if (!pre) {
;     STAGE8(SB8(0, 0), Bt, K, bcol, 0); STAGE8(SA8(0, 0), A, lda, brow, 0);
;     STAGE8(SB8(0, 1), Bt, K, bcol + 128, 0); STAGE8(SA8(0, 1), A, lda, brow + 128, 0);
;   }
;   if (wr == 1) BAR8;
; __global__ void __launch_bounds__(512, 2) mega(Params p) {
;     ...
;     for (int item = bid; item < 4 * 64; item += nb) {
;       const int nt = item >> 6, mt = item & 63;
;       e.ss = nullptr; e.xf = G_XF; e.xb = G_XB; e.ss_out = G_SS;
;       gemm_tile<EPI_RESID, 256, false>(G_OB, DM, wb + W_OUT, DM, mt * 256, nt * 256, e);
.LBB0_905:
	s_mov_b32 s0, 24
	s_mov_b32 s0, 25
	s_ashr_i32 s1, s0, 31
	s_lshl_b64 s[0:1], s[0:1], 3
	s_add_u32 s0, s70, s0
	s_addc_u32 s1, s71, s1
	v_readlane_b32 s6, v255, 60
	v_readlane_b32 s7, v255, 61
	s_nop 4
	s_mov_b32 s0, 25
	s_ashr_i32 s1, s0, 31
	s_lshl_b64 s[0:1], s[0:1], 3
	s_add_u32 s0, s70, s0
	s_addc_u32 s1, s71, s1
	s_mov_b32 s2, 25
	v_readlane_b32 s0, v255, 60
	v_readlane_b32 s1, v255, 61
	s_nop 4
	s_ashr_i32 s3, s2, 31
	s_lshl_b64 s[2:3], s[2:3], 3
	s_add_u32 s2, s70, s2
	s_addc_u32 s3, s71, s3
	v_mov_b32_e32 v3, v224
	v_readlane_b32 s2, v255, 60
	v_readlane_b32 s3, v255, 61
	s_nop 4
	v_mov_b32_e32 v18, 1
	v_bfe_i32 v1, v3, 27, 1
	s_waitcnt vmcnt(10)
	v_lshlrev_b32_e32 v150, 4, v3
	s_nop 0
	v_readfirstlane_b32 s100, v150
	v_lshrrev_b32_e32 v1, 22, v1
	v_add_u32_e32 v1, v150, v1
	v_and_b32_e32 v1, 0xfffffc00, v1
	v_ashrrev_i32_e32 v0, 31, v3
	v_sub_u32_e32 v1, v150, v1
	v_lshrrev_b32_e32 v0, 26, v0
	v_lshrrev_b32_e32 v5, 4, v1
	v_add_u32_e32 v0, v3, v0
	v_bitop3_b32 v5, v5, v1, 32 bitop3:0x6c
	v_ashrrev_i32_e32 v1, 31, v1
	s_waitcnt lgkmcnt(0)
	s_add_u32 s29, s2, 0x6000000
	v_ashrrev_i32_e32 v0, 6, v0
	v_lshrrev_b32_e32 v1, 26, v1
	s_addc_u32 s33, s3, 0
	s_lshl_b32 s8, s24, 8
	v_lshlrev_b32_e32 v6, 3, v0
	v_add_u32_e32 v1, v5, v1
	s_and_b32 s25, s8, 0x3f00
	s_lshl_b32 s8, s24, 2
	v_and_b32_e32 v6, -16, v6
	v_ashrrev_i32_e32 v1, 6, v1
	s_and_b32 s8, s8, 0xffffff00
	v_add_u32_e32 v16, v1, v6
	v_mul_i32_i24_e32 v1, 64, v1
	s_ashr_i32 s9, s8, 31
	v_lshlrev_b32_e32 v0, 5, v0
	v_sub_u32_e32 v1, v5, v1
	s_waitcnt vmcnt(9)
	v_add_u32_e32 v152, 0x2000, v150
	s_lshl_b64 s[12:13], s[8:9], 11
	v_and_b32_e32 v0, 32, v0
	v_ashrrev_i16_sdwa v1, v18, sext(v1) dst_sel:DWORD dst_unused:UNUSED_PAD src0_sel:DWORD src1_sel:BYTE_0
	v_ashrrev_i32_e32 v5, 31, v152
	s_add_u32 s12, s14, s12
	v_add_u32_sdwa v0, v0, sext(v1) dst_sel:DWORD dst_unused:UNUSED_PAD src0_sel:DWORD src1_sel:WORD_0
	v_ashrrev_i32_e32 v17, 31, v16
	v_lshrrev_b32_e32 v5, 22, v5
	s_addc_u32 s13, s15, s13
	v_lshlrev_b64 v[6:7], 11, v[16:17]
	v_ashrrev_i32_e32 v1, 31, v0
	v_add_u32_e32 v5, v152, v5
	v_lshl_add_u64 v[10:11], s[12:13], 0, v[6:7]
	v_lshlrev_b64 v[8:9], 1, v[0:1]
	v_ashrrev_i32_e32 v5, 10, v5
	v_lshl_add_u64 v[14:15], v[10:11], 0, v[8:9]
	v_mul_i32_i24_e32 v10, 0x400, v5
	v_sub_u32_e32 v10, v152, v10
	v_lshrrev_b32_e32 v11, 4, v10
	v_bitop3_b32 v10, v11, v10, 32 bitop3:0x6c
	v_ashrrev_i32_e32 v12, 31, v10
	v_lshrrev_b32_e32 v12, 26, v12
	v_lshlrev_b32_e32 v11, 3, v5
	v_add_u32_e32 v12, v10, v12
	v_and_b32_e32 v11, -16, v11
	v_ashrrev_i32_e32 v13, 6, v12
	v_add_u32_e32 v24, v13, v11
	v_ashrrev_i32_e32 v25, 31, v24
	v_lshrrev_b32_e32 v132, 1, v8
	v_add_u32_e32 v10, 0x20000, v6
	v_mov_b32_e32 v11, v7
	s_waitcnt vmcnt(8)
	s_or_b32 m0, s100, 0x10000
	v_lshl_add_u64 v[18:19], s[12:13], 0, v[10:11]
	global_load_lds_dwordx4 v[14:15], off
	v_mov_b32_e32 v133, v9
	s_or_b32 m0, s100, 0x12000
	s_lshl_b32 s27, s25, 10
	s_lshl_b32 s12, s25, 11
	v_mov_b64_e32 v[12:13], v[8:9]
	s_add_u32 s12, s29, s12
	v_lshl_add_u64 v[18:19], v[18:19], 0, v[12:13]
	s_addc_u32 s13, s33, 0
	global_load_lds_dwordx4 v[18:19], off
	v_lshl_add_u64 v[20:21], s[12:13], 0, v[6:7]
	s_mov_b32 m0, s100
	s_or_b32 s30, s8, 0x80
	v_lshl_add_u64 v[20:21], v[20:21], 0, v[8:9]
	v_lshl_add_u64 v[22:23], s[12:13], 0, v[10:11]
	s_ashr_i32 s31, s30, 31
	global_load_lds_dwordx4 v[20:21], off
	s_or_b32 m0, s100, 0x2000
	s_lshl_b64 s[12:13], s[30:31], 11
	s_add_u32 s12, s14, s12
	s_addc_u32 s13, s15, s13
	v_lshl_add_u64 v[22:23], v[22:23], 0, v[12:13]
	v_lshl_add_u64 v[26:27], s[12:13], 0, v[6:7]
	s_bitset1_b32 s27, 17
	global_load_lds_dwordx4 v[22:23], off
	v_lshl_add_u64 v[26:27], v[26:27], 0, v[8:9]
	s_or_b32 m0, s100, 0x14000
	v_lshl_add_u64 v[28:29], s[12:13], 0, v[10:11]
	s_lshl_b32 s27, s27, 1
	global_load_lds_dwordx4 v[26:27], off
	s_or_b32 m0, s100, 0x16000
	s_add_u32 s12, s29, s27
	s_addc_u32 s13, s33, 0
	v_lshl_add_u64 v[28:29], v[28:29], 0, v[12:13]
	v_lshl_add_u64 v[30:31], s[12:13], 0, v[6:7]
	global_load_lds_dwordx4 v[28:29], off
	v_lshl_add_u64 v[30:31], v[30:31], 0, v[8:9]
	s_or_b32 m0, s100, 0x4000
	s_nop 0
	global_load_lds_dwordx4 v[30:31], off
	v_lshl_add_u64 v[30:31], s[12:13], 0, v[10:11]
	v_lshl_add_u64 v[30:31], v[30:31], 0, v[12:13]
	s_or_b32 m0, s100, 0x6000
	v_ashrrev_i32_e32 v5, 8, v3
	global_load_lds_dwordx4 v[30:31], off
	v_cmp_eq_u32_e32 vcc, 1, v5
	s_and_saveexec_b64 s[12:13], vcc
	s_cbranch_execz .LBB0_907
	s_barrier
; #define LDA8(dst, b, h) _Pragma("unroll") for (int m = 0; m < 4; ++m) _Pragma("unroll") for (int k = 0; k < 2; ++k) \
;     dst[m][k] = *(const bf16x8*)((const char*)SA8(b, h) + lds_byte8(wr * 64 + m * 16 + fr, k * 32 + fq * 8))
; #define LDB8(dst, b, h) _Pragma("unroll") for (int n = 0; n < 2; ++n) _Pragma("unroll") for (int k = 0; k < 2; ++k) \
;     dst[n][k] = *(const bf16x8*)((const char*)SB8(b, h) + lds_byte8(wc * 32 + n * 16 + fr, k * 32 + fq * 8))
; #define WAIT_V8(n) asm volatile("s_waitcnt vmcnt(" #n ")" ::: "memory")
; #define WAIT_L8(n) asm volatile("s_waitcnt lgkmcnt(" #n ")" ::: "memory")
; #define BAR8 __builtin_amdgcn_s_barrier()
; #define SCHED8 __builtin_amdgcn_sched_barrier(0)
;     ...
;   if (wr == 1) BAR8;
;   WAIT_V8(4); BAR8;
;   STAGE8(SB8(1, 0), Bt, K, bcol, 1); STAGE8(SA8(1, 0), A, lda, brow, 1); STAGE8(SB8(1, 1), Bt, K, bcol + 128, 1);
;   WAIT_V8(6); BAR8;
;   for (int tt = 0; tt < nt - 2; tt += 2) {
;     LDB8(B0, 0, 0); SCHED8; LDA8(At, 0, 0); STAGE8(SA8(1, 1), A, lda, brow + 128, tt + 1);
;     WAIT_L8(8); BAR8; WAIT_L8(0); MMA8(0, 0, At, B0); BAR8; SCHED8;
;     LDB8(B1, 0, 1); STAGE8(SB8(0, 0), Bt, K, bcol, tt + 2);
;     BAR8; WAIT_L8(0); MMA8(0, 1, At, B1); BAR8;
.LBB0_907:
	s_or_b64 exec, exec, s[12:13]
	s_lshl_b32 s29, s20, 11
	s_waitcnt vmcnt(0)
	s_and_b32 s36, s29, 0x1f80000
	s_mov_b64 s[38:39], 0x80
	v_lshl_add_u64 v[14:15], v[14:15], 0, s[38:39]
	s_or_b32 m0, s100, 0x18000
	s_waitcnt vmcnt(4)
	s_barrier
	global_load_lds_dwordx4 v[14:15], off
	v_lshl_add_u64 v[14:15], v[18:19], 0, s[38:39]
	s_or_b32 m0, s100, 0x1a000
	s_nop 0
	global_load_lds_dwordx4 v[14:15], off
	v_lshl_add_u64 v[14:15], v[20:21], 0, s[38:39]
	s_or_b32 m0, s100, 0x8000
	s_nop 0
	global_load_lds_dwordx4 v[14:15], off
	v_lshl_add_u64 v[14:15], v[22:23], 0, s[38:39]
	s_or_b32 m0, s100, 0xa000
	s_nop 0
	global_load_lds_dwordx4 v[14:15], off
	s_or_b32 m0, s100, 0x1c000
	v_lshl_add_u64 v[14:15], v[26:27], 0, s[38:39]
	global_load_lds_dwordx4 v[14:15], off
	v_lshl_add_u64 v[14:15], v[28:29], 0, s[38:39]
	s_or_b32 m0, s100, 0x1e000
	v_and_b32_e32 v147, 15, v3
	global_load_lds_dwordx4 v[14:15], off
	v_bfe_u32 v148, v3, 4, 2
	v_lshlrev_b32_e32 v14, 4, v148
	v_lshlrev_b32_e32 v15, 6, v147
	v_lshlrev_b32_e32 v18, 2, v3
	v_lshlrev_b64 v[136:137], 10, v[16:17]
	v_or_b32_e32 v17, v14, v15
	v_and_b32_e32 v18, 32, v18
	s_mov_b32 s29, 0x10000
	s_and_b32 s12, s21, 0xffffff00
	v_bitop3_b32 v20, v17, s29, v18 bitop3:0xde
	s_mov_b32 s29, 0x14000
	s_ashr_i32 s13, s12, 31
	v_readlane_b32 s40, v254, 35
	v_bitop3_b32 v19, v14, v18, v15 bitop3:0x36
	v_bitop3_b32 v21, v17, s29, v18 bitop3:0xde
	s_mov_b32 s29, 0x18000
	v_lshlrev_b32_e32 v15, 6, v3
	s_lshl_b64 s[12:13], s[12:13], 11
	s_mov_b32 s37, s40
	v_bitop3_b32 v22, v17, s29, v18 bitop3:0xde
	s_mov_b32 s29, 0x1c000
	v_and_b32_e32 v15, 0x3c0, v15
	v_bitop3_b32 v17, v17, s29, v18 bitop3:0xde
	v_bitop3_b32 v18, v15, v18, v14 bitop3:0x36
	v_lshl_add_u64 v[14:15], s[12:13], 0, v[6:7]
	v_lshl_add_u64 v[6:7], s[36:37], 0, v[6:7]
	v_lshl_add_u64 v[14:15], v[14:15], 0, v[8:9]
	v_lshl_add_u64 v[6:7], v[6:7], 0, v[8:9]
	v_bfe_u32 v146, v3, 6, 2
	s_waitcnt vmcnt(6)
	v_lshlrev_b32_e32 v149, 6, v5
	v_lshlrev_b32_e32 v5, 13, v5
	v_lshl_add_u64 v[138:139], s[4:5], 0, v[14:15]
	v_lshl_add_u64 v[14:15], s[12:13], 0, v[10:11]
	v_lshl_add_u64 v[142:143], s[2:3], 0, v[6:7]
	v_lshl_add_u64 v[6:7], s[36:37], 0, v[10:11]
	v_lshlrev_b64 v[134:135], 10, v[24:25]
	v_readlane_b32 s41, v254, 36
	v_readlane_b32 s42, v254, 37
	v_readlane_b32 s43, v254, 38
	v_lshlrev_b32_e32 v16, 12, v146
	v_or_b32_e32 v23, 0x800, v5
	v_or_b32_e32 v24, 0x1000, v5
	v_or_b32_e32 v25, 0x1800, v5
	v_lshl_add_u64 v[14:15], v[14:15], 0, v[12:13]
	v_lshl_add_u64 v[6:7], v[6:7], 0, v[12:13]
	v_lshl_add_u64 v[140:141], s[4:5], 0, v[14:15]
	v_lshl_add_u64 v[144:145], s[2:3], 0, v[6:7]
	s_mov_b32 s29, -2
	s_mov_b64 s[12:13], 0
	v_add_u32_e32 v171, v20, v16
	v_add_u32_e32 v156, v19, v5
	v_add_u32_e32 v155, v18, v23
	v_add_u32_e32 v154, v18, v24
	v_add_u32_e32 v153, v18, v25
	v_add_u32_e32 v167, v21, v16
	v_add_u32_e32 v160, v22, v16
	v_add_u32_e32 v158, v17, v16
	s_mov_b64 s[36:37], 0x6040080
	s_mov_b64 s[38:39], 0xc4a0100
	s_mov_b64 s[40:41], 0x6000100
	s_mov_b64 s[42:43], 0xc4e0100
	s_mov_b64 s[44:45], 0x6040100
	s_mov_b64 s[46:47], 0xc4a0180
	s_mov_b64 s[48:49], 0x6000180
	s_mov_b64 s[50:51], 0xc4e0180
	s_barrier
	ds_read_b128 v[174:177], v171
	ds_read_b128 v[178:181], v171 offset:1024
	ds_read_b128 v[182:185], v171 offset:2048
	ds_read_b128 v[186:189], v171 offset:3072
	v_lshl_add_u64 v[222:223], v[142:143], 0, s[12:13]
	v_lshl_add_u64 v[226:227], v[222:223], 0, s[36:37]
	s_or_b32 m0, s100, 0xc000
	ds_read_b128 v[190:193], v156
	ds_read_b128 v[194:197], v156 offset:1024
	ds_read_b128 v[198:201], v155
	ds_read_b128 v[202:205], v155 offset:1024
	ds_read_b128 v[206:209], v154
	ds_read_b128 v[210:213], v154 offset:1024
	ds_read_b128 v[214:217], v153
	ds_read_b128 v[218:221], v153 offset:1024
	global_load_lds_dwordx4 v[226:227], off
	v_lshl_add_u64 v[226:227], v[144:145], 0, s[12:13]
	s_or_b32 m0, s100, 0xe000
	v_lshl_add_u64 v[228:229], v[226:227], 0, s[36:37]
	global_load_lds_dwordx4 v[228:229], off
	s_waitcnt lgkmcnt(8)
	s_barrier
	s_waitcnt lgkmcnt(0)
	v_mfma_f32_16x16x32_bf16 v[128:131], v[190:193], v[174:177], 0
	v_mfma_f32_16x16x32_bf16 v[124:127], v[190:193], v[182:185], 0
	v_mfma_f32_16x16x32_bf16 v[120:123], v[198:201], v[174:177], 0
	v_mfma_f32_16x16x32_bf16 v[116:119], v[198:201], v[182:185], 0
	v_mfma_f32_16x16x32_bf16 v[112:115], v[206:209], v[174:177], 0
	v_mfma_f32_16x16x32_bf16 v[108:111], v[206:209], v[182:185], 0
	v_mfma_f32_16x16x32_bf16 v[104:107], v[214:217], v[174:177], 0
	v_mfma_f32_16x16x32_bf16 v[100:103], v[214:217], v[182:185], 0
	v_mfma_f32_16x16x32_bf16 v[128:131], v[194:197], v[178:181], v[128:131]
	v_mfma_f32_16x16x32_bf16 v[124:127], v[194:197], v[186:189], v[124:127]
	v_mfma_f32_16x16x32_bf16 v[120:123], v[202:205], v[178:181], v[120:123]
	v_mfma_f32_16x16x32_bf16 v[116:119], v[202:205], v[186:189], v[116:119]
	v_mfma_f32_16x16x32_bf16 v[112:115], v[210:213], v[178:181], v[112:115]
	v_mfma_f32_16x16x32_bf16 v[108:111], v[210:213], v[186:189], v[108:111]
	v_mfma_f32_16x16x32_bf16 v[104:107], v[218:221], v[178:181], v[104:107]
	v_mfma_f32_16x16x32_bf16 v[100:103], v[218:221], v[186:189], v[100:103]
	s_barrier
	v_lshl_add_u64 v[228:229], v[138:139], 0, s[12:13]
	v_lshl_add_u64 v[236:237], v[228:229], 0, s[38:39]
	s_or_b32 m0, s100, 0x10000
	ds_read_b128 v[230:233], v167
	ds_read_b128 v[238:241], v167 offset:1024
	ds_read_b128 v[242:245], v167 offset:2048
	ds_read_b128 v[246:249], v167 offset:3072
	global_load_lds_dwordx4 v[236:237], off
	v_lshl_add_u64 v[236:237], v[140:141], 0, s[12:13]
	s_or_b32 m0, s100, 0x12000
	v_lshl_add_u64 v[250:251], v[236:237], 0, s[38:39]
	global_load_lds_dwordx4 v[250:251], off
	s_barrier
; #define LDA8(dst, b, h) _Pragma("unroll") for (int m = 0; m < 4; ++m) _Pragma("unroll") for (int k = 0; k < 2; ++k) \
;     dst[m][k] = *(const bf16x8*)((const char*)SA8(b, h) + lds_byte8(wr * 64 + m * 16 + fr, k * 32 + fq * 8))
; #define LDB8(dst, b, h) _Pragma("unroll") for (int n = 0; n < 2; ++n) _Pragma("unroll") for (int k = 0; k < 2; ++k) \
;     dst[n][k] = *(const bf16x8*)((const char*)SB8(b, h) + lds_byte8(wc * 32 + n * 16 + fr, k * 32 + fq * 8))
; #define WAIT_V8(n) asm volatile("s_waitcnt vmcnt(" #n ")" ::: "memory")
; #define WAIT_L8(n) asm volatile("s_waitcnt lgkmcnt(" #n ")" ::: "memory")
; #define BAR8 __builtin_amdgcn_s_barrier()
; #define SCHED8 __builtin_amdgcn_sched_barrier(0)
;     ...
;     BAR8; WAIT_L8(0); MMA8(0, 1, At, B1); BAR8;
;     LDA8(At, 0, 1); STAGE8(SA8(0, 0), A, lda, brow, tt + 2);
;     BAR8; WAIT_L8(0); MMA8(1, 0, At, B0); BAR8; SCHED8;
;     STAGE8(SB8(0, 1), Bt, K, bcol + 128, tt + 2);
;     WAIT_V8(6); BAR8; MMA8(1, 1, At, B1); BAR8;
;     LDB8(B0, 1, 0); SCHED8; LDA8(At, 1, 0); STAGE8(SA8(0, 1), A, lda, brow + 128, tt + 2);
;     WAIT_L8(8); BAR8; WAIT_L8(0); MMA8(0, 0, At, B0); BAR8; SCHED8;
	s_waitcnt lgkmcnt(0)
	v_mfma_f32_16x16x32_bf16 v[96:99], v[190:193], v[230:233], 0
	v_mfma_f32_16x16x32_bf16 v[92:95], v[190:193], v[242:245], 0
	v_mfma_f32_16x16x32_bf16 v[88:91], v[198:201], v[230:233], 0
	v_mfma_f32_16x16x32_bf16 v[84:87], v[198:201], v[242:245], 0
	v_mfma_f32_16x16x32_bf16 v[80:83], v[206:209], v[230:233], 0
	v_mfma_f32_16x16x32_bf16 v[76:79], v[206:209], v[242:245], 0
	v_mfma_f32_16x16x32_bf16 v[72:75], v[214:217], v[230:233], 0
	v_mfma_f32_16x16x32_bf16 v[68:71], v[214:217], v[242:245], 0
	v_mfma_f32_16x16x32_bf16 v[96:99], v[194:197], v[238:241], v[96:99]
	v_mfma_f32_16x16x32_bf16 v[92:95], v[194:197], v[246:249], v[92:95]
	v_mfma_f32_16x16x32_bf16 v[88:91], v[202:205], v[238:241], v[88:91]
	v_mfma_f32_16x16x32_bf16 v[84:87], v[202:205], v[246:249], v[84:87]
	v_mfma_f32_16x16x32_bf16 v[80:83], v[210:213], v[238:241], v[80:83]
	v_mfma_f32_16x16x32_bf16 v[76:79], v[210:213], v[246:249], v[76:79]
	v_mfma_f32_16x16x32_bf16 v[72:75], v[218:221], v[238:241], v[72:75]
	v_mfma_f32_16x16x32_bf16 v[68:71], v[218:221], v[246:249], v[68:71]
	v_lshl_add_u64 v[250:251], v[222:223], 0, s[40:41]
	s_mov_b32 m0, s100
	s_barrier
	ds_read_b128 v[190:193], v156 offset:16384
	ds_read_b128 v[194:197], v156 offset:17408
	ds_read_b128 v[198:201], v155 offset:16384
	ds_read_b128 v[202:205], v155 offset:17408
	ds_read_b128 v[206:209], v154 offset:16384
	ds_read_b128 v[210:213], v154 offset:17408
	ds_read_b128 v[214:217], v153 offset:16384
	ds_read_b128 v[218:221], v153 offset:17408
	global_load_lds_dwordx4 v[250:251], off
	s_or_b32 m0, s100, 0x2000
	v_lshl_add_u64 v[250:251], v[226:227], 0, s[40:41]
	global_load_lds_dwordx4 v[250:251], off
	s_barrier
	s_waitcnt lgkmcnt(0)
	v_mfma_f32_16x16x32_bf16 v[64:67], v[190:193], v[174:177], 0
	v_mfma_f32_16x16x32_bf16 v[60:63], v[190:193], v[182:185], 0
	v_mfma_f32_16x16x32_bf16 v[56:59], v[198:201], v[174:177], 0
	v_mfma_f32_16x16x32_bf16 v[52:55], v[198:201], v[182:185], 0
	v_mfma_f32_16x16x32_bf16 v[48:51], v[206:209], v[174:177], 0
	v_mfma_f32_16x16x32_bf16 v[44:47], v[206:209], v[182:185], 0
	v_mfma_f32_16x16x32_bf16 v[40:43], v[214:217], v[174:177], 0
	v_mfma_f32_16x16x32_bf16 v[36:39], v[214:217], v[182:185], 0
	v_mfma_f32_16x16x32_bf16 v[64:67], v[194:197], v[178:181], v[64:67]
	v_mfma_f32_16x16x32_bf16 v[60:63], v[194:197], v[186:189], v[60:63]
	v_mfma_f32_16x16x32_bf16 v[56:59], v[202:205], v[178:181], v[56:59]
	v_mfma_f32_16x16x32_bf16 v[52:55], v[202:205], v[186:189], v[52:55]
	v_mfma_f32_16x16x32_bf16 v[48:51], v[210:213], v[178:181], v[48:51]
	v_mfma_f32_16x16x32_bf16 v[44:47], v[210:213], v[186:189], v[44:47]
	v_mfma_f32_16x16x32_bf16 v[40:43], v[218:221], v[178:181], v[40:43]
	v_mfma_f32_16x16x32_bf16 v[36:39], v[218:221], v[186:189], v[36:39]
	s_barrier
	s_or_b32 m0, s100, 0x14000
	v_lshl_add_u64 v[174:175], v[228:229], 0, s[42:43]
	global_load_lds_dwordx4 v[174:175], off
	s_or_b32 m0, s100, 0x16000
	v_lshl_add_u64 v[174:175], v[236:237], 0, s[42:43]
	global_load_lds_dwordx4 v[174:175], off
	s_waitcnt vmcnt(6)
	s_barrier
	v_mfma_f32_16x16x32_bf16 v[32:35], v[190:193], v[230:233], 0
	v_mfma_f32_16x16x32_bf16 v[28:31], v[190:193], v[242:245], 0
	v_mfma_f32_16x16x32_bf16 v[24:27], v[198:201], v[230:233], 0
	v_mfma_f32_16x16x32_bf16 v[20:23], v[198:201], v[242:245], 0
	v_mfma_f32_16x16x32_bf16 v[16:19], v[206:209], v[230:233], 0
	v_mfma_f32_16x16x32_bf16 v[12:15], v[206:209], v[242:245], 0
	v_mfma_f32_16x16x32_bf16 v[8:11], v[214:217], v[230:233], 0
	v_mfma_f32_16x16x32_bf16 v[4:7], v[214:217], v[242:245], 0
	v_mfma_f32_16x16x32_bf16 v[32:35], v[194:197], v[238:241], v[32:35]
	v_mfma_f32_16x16x32_bf16 v[28:31], v[194:197], v[246:249], v[28:31]
	v_mfma_f32_16x16x32_bf16 v[24:27], v[202:205], v[238:241], v[24:27]
	v_mfma_f32_16x16x32_bf16 v[20:23], v[202:205], v[246:249], v[20:23]
	v_mfma_f32_16x16x32_bf16 v[16:19], v[210:213], v[238:241], v[16:19]
	v_mfma_f32_16x16x32_bf16 v[12:15], v[210:213], v[246:249], v[12:15]
	v_mfma_f32_16x16x32_bf16 v[8:11], v[218:221], v[238:241], v[8:11]
	v_mfma_f32_16x16x32_bf16 v[4:7], v[218:221], v[246:249], v[4:7]
	s_barrier
	ds_read_b128 v[174:177], v160
	ds_read_b128 v[178:181], v160 offset:1024
	ds_read_b128 v[182:185], v160 offset:2048
	ds_read_b128 v[186:189], v160 offset:3072
	v_lshl_add_u64 v[230:231], v[222:223], 0, s[44:45]
	s_or_b32 m0, s100, 0x4000
	ds_read_b128 v[190:193], v156 offset:32768
	ds_read_b128 v[194:197], v156 offset:33792
	ds_read_b128 v[198:201], v155 offset:32768
	ds_read_b128 v[202:205], v155 offset:33792
	ds_read_b128 v[206:209], v154 offset:32768
	ds_read_b128 v[210:213], v154 offset:33792
	ds_read_b128 v[214:217], v153 offset:32768
	ds_read_b128 v[218:221], v153 offset:33792
	global_load_lds_dwordx4 v[230:231], off
	s_or_b32 m0, s100, 0x6000
	v_lshl_add_u64 v[230:231], v[226:227], 0, s[44:45]
	global_load_lds_dwordx4 v[230:231], off
	s_waitcnt lgkmcnt(8)
	s_barrier
; #define LDA8(dst, b, h) _Pragma("unroll") for (int m = 0; m < 4; ++m) _Pragma("unroll") for (int k = 0; k < 2; ++k) \
;     dst[m][k] = *(const bf16x8*)((const char*)SA8(b, h) + lds_byte8(wr * 64 + m * 16 + fr, k * 32 + fq * 8))
; #define LDB8(dst, b, h) _Pragma("unroll") for (int n = 0; n < 2; ++n) _Pragma("unroll") for (int k = 0; k < 2; ++k) \
;     dst[n][k] = *(const bf16x8*)((const char*)SB8(b, h) + lds_byte8(wc * 32 + n * 16 + fr, k * 32 + fq * 8))
; #define WAIT_V8(n) asm volatile("s_waitcnt vmcnt(" #n ")" ::: "memory")
; #define WAIT_L8(n) asm volatile("s_waitcnt lgkmcnt(" #n ")" ::: "memory")
; #define BAR8 __builtin_amdgcn_s_barrier()
; #define SCHED8 __builtin_amdgcn_sched_barrier(0)
;     ...
;     WAIT_L8(8); BAR8; WAIT_L8(0); MMA8(0, 0, At, B0); BAR8; SCHED8;
;     LDB8(B1, 1, 1); STAGE8(SB8(1, 0), Bt, K, bcol, tt + 3);
;     BAR8; WAIT_L8(0); MMA8(0, 1, At, B1); BAR8;
;     LDA8(At, 1, 1); STAGE8(SA8(1, 0), A, lda, brow, tt + 3);
;     BAR8; WAIT_L8(0); MMA8(1, 0, At, B0); BAR8; SCHED8;
;     STAGE8(SB8(1, 1), Bt, K, bcol + 128, tt + 3);
;     WAIT_V8(6); BAR8; MMA8(1, 1, At, B1); BAR8;
;   }
	s_waitcnt lgkmcnt(0)
	v_mfma_f32_16x16x32_bf16 v[128:131], v[190:193], v[174:177], v[128:131]
	v_mfma_f32_16x16x32_bf16 v[124:127], v[190:193], v[182:185], v[124:127]
	v_mfma_f32_16x16x32_bf16 v[120:123], v[198:201], v[174:177], v[120:123]
	v_mfma_f32_16x16x32_bf16 v[116:119], v[198:201], v[182:185], v[116:119]
	v_mfma_f32_16x16x32_bf16 v[112:115], v[206:209], v[174:177], v[112:115]
	v_mfma_f32_16x16x32_bf16 v[108:111], v[206:209], v[182:185], v[108:111]
	v_mfma_f32_16x16x32_bf16 v[104:107], v[214:217], v[174:177], v[104:107]
	v_mfma_f32_16x16x32_bf16 v[100:103], v[214:217], v[182:185], v[100:103]
	v_mfma_f32_16x16x32_bf16 v[128:131], v[194:197], v[178:181], v[128:131]
	v_mfma_f32_16x16x32_bf16 v[124:127], v[194:197], v[186:189], v[124:127]
	v_mfma_f32_16x16x32_bf16 v[120:123], v[202:205], v[178:181], v[120:123]
	v_mfma_f32_16x16x32_bf16 v[116:119], v[202:205], v[186:189], v[116:119]
	v_mfma_f32_16x16x32_bf16 v[112:115], v[210:213], v[178:181], v[112:115]
	v_mfma_f32_16x16x32_bf16 v[108:111], v[210:213], v[186:189], v[108:111]
	v_mfma_f32_16x16x32_bf16 v[104:107], v[218:221], v[178:181], v[104:107]
	v_mfma_f32_16x16x32_bf16 v[100:103], v[218:221], v[186:189], v[100:103]
	s_barrier
	v_lshl_add_u64 v[250:251], v[228:229], 0, s[46:47]
	s_or_b32 m0, s100, 0x18000
	ds_read_b128 v[230:233], v158
	ds_read_b128 v[238:241], v158 offset:1024
	ds_read_b128 v[242:245], v158 offset:2048
	ds_read_b128 v[246:249], v158 offset:3072
	global_load_lds_dwordx4 v[250:251], off
	s_or_b32 m0, s100, 0x1a000
	v_lshl_add_u64 v[250:251], v[236:237], 0, s[46:47]
	global_load_lds_dwordx4 v[250:251], off
	s_barrier
	s_waitcnt lgkmcnt(0)
	v_mfma_f32_16x16x32_bf16 v[96:99], v[190:193], v[230:233], v[96:99]
	v_mfma_f32_16x16x32_bf16 v[92:95], v[190:193], v[242:245], v[92:95]
	v_mfma_f32_16x16x32_bf16 v[88:91], v[198:201], v[230:233], v[88:91]
	v_mfma_f32_16x16x32_bf16 v[84:87], v[198:201], v[242:245], v[84:87]
	v_mfma_f32_16x16x32_bf16 v[80:83], v[206:209], v[230:233], v[80:83]
	v_mfma_f32_16x16x32_bf16 v[76:79], v[206:209], v[242:245], v[76:79]
	v_mfma_f32_16x16x32_bf16 v[72:75], v[214:217], v[230:233], v[72:75]
	v_mfma_f32_16x16x32_bf16 v[68:71], v[214:217], v[242:245], v[68:71]
	v_mfma_f32_16x16x32_bf16 v[96:99], v[194:197], v[238:241], v[96:99]
	v_mfma_f32_16x16x32_bf16 v[92:95], v[194:197], v[246:249], v[92:95]
	v_mfma_f32_16x16x32_bf16 v[88:91], v[202:205], v[238:241], v[88:91]
	v_mfma_f32_16x16x32_bf16 v[84:87], v[202:205], v[246:249], v[84:87]
	v_mfma_f32_16x16x32_bf16 v[80:83], v[210:213], v[238:241], v[80:83]
	v_mfma_f32_16x16x32_bf16 v[76:79], v[210:213], v[246:249], v[76:79]
	v_mfma_f32_16x16x32_bf16 v[72:75], v[218:221], v[238:241], v[72:75]
	v_mfma_f32_16x16x32_bf16 v[68:71], v[218:221], v[246:249], v[68:71]
	v_lshl_add_u64 v[222:223], v[222:223], 0, s[48:49]
	s_or_b32 m0, s100, 0x8000
	s_barrier
	ds_read_b128 v[190:193], v156 offset:49152
	ds_read_b128 v[194:197], v156 offset:50176
	ds_read_b128 v[198:201], v155 offset:49152
	ds_read_b128 v[202:205], v155 offset:50176
	ds_read_b128 v[206:209], v154 offset:49152
	ds_read_b128 v[210:213], v154 offset:50176
	ds_read_b128 v[214:217], v153 offset:49152
	ds_read_b128 v[218:221], v153 offset:50176
	global_load_lds_dwordx4 v[222:223], off
	s_or_b32 m0, s100, 0xa000
	v_lshl_add_u64 v[222:223], v[226:227], 0, s[48:49]
	global_load_lds_dwordx4 v[222:223], off
	s_barrier
	s_waitcnt lgkmcnt(0)
	v_mfma_f32_16x16x32_bf16 v[64:67], v[190:193], v[174:177], v[64:67]
	v_mfma_f32_16x16x32_bf16 v[60:63], v[190:193], v[182:185], v[60:63]
	v_mfma_f32_16x16x32_bf16 v[56:59], v[198:201], v[174:177], v[56:59]
	v_mfma_f32_16x16x32_bf16 v[52:55], v[198:201], v[182:185], v[52:55]
	v_mfma_f32_16x16x32_bf16 v[48:51], v[206:209], v[174:177], v[48:51]
	v_mfma_f32_16x16x32_bf16 v[44:47], v[206:209], v[182:185], v[44:47]
	v_mfma_f32_16x16x32_bf16 v[40:43], v[214:217], v[174:177], v[40:43]
	v_mfma_f32_16x16x32_bf16 v[36:39], v[214:217], v[182:185], v[36:39]
	v_mfma_f32_16x16x32_bf16 v[64:67], v[194:197], v[178:181], v[64:67]
	v_mfma_f32_16x16x32_bf16 v[60:63], v[194:197], v[186:189], v[60:63]
	v_mfma_f32_16x16x32_bf16 v[56:59], v[202:205], v[178:181], v[56:59]
	v_mfma_f32_16x16x32_bf16 v[52:55], v[202:205], v[186:189], v[52:55]
	v_mfma_f32_16x16x32_bf16 v[48:51], v[210:213], v[178:181], v[48:51]
	v_mfma_f32_16x16x32_bf16 v[44:47], v[210:213], v[186:189], v[44:47]
	v_mfma_f32_16x16x32_bf16 v[40:43], v[218:221], v[178:181], v[40:43]
	v_mfma_f32_16x16x32_bf16 v[36:39], v[218:221], v[186:189], v[36:39]
	s_barrier
	s_or_b32 m0, s100, 0x1c000
	v_lshl_add_u64 v[174:175], v[228:229], 0, s[50:51]
	global_load_lds_dwordx4 v[174:175], off
	s_or_b32 m0, s100, 0x1e000
	v_lshl_add_u64 v[174:175], v[236:237], 0, s[50:51]
	global_load_lds_dwordx4 v[174:175], off
	s_waitcnt vmcnt(6)
	s_barrier
	v_mfma_f32_16x16x32_bf16 v[32:35], v[190:193], v[230:233], v[32:35]
	v_mfma_f32_16x16x32_bf16 v[28:31], v[190:193], v[242:245], v[28:31]
	v_mfma_f32_16x16x32_bf16 v[24:27], v[198:201], v[230:233], v[24:27]
	v_mfma_f32_16x16x32_bf16 v[20:23], v[198:201], v[242:245], v[20:23]
	v_mfma_f32_16x16x32_bf16 v[16:19], v[206:209], v[230:233], v[16:19]
	v_mfma_f32_16x16x32_bf16 v[12:15], v[206:209], v[242:245], v[12:15]
	v_mfma_f32_16x16x32_bf16 v[8:11], v[214:217], v[230:233], v[8:11]
	v_mfma_f32_16x16x32_bf16 v[4:7], v[214:217], v[242:245], v[4:7]
	v_mfma_f32_16x16x32_bf16 v[32:35], v[194:197], v[238:241], v[32:35]
	v_mfma_f32_16x16x32_bf16 v[28:31], v[194:197], v[246:249], v[28:31]
	v_mfma_f32_16x16x32_bf16 v[24:27], v[202:205], v[238:241], v[24:27]
	v_mfma_f32_16x16x32_bf16 v[20:23], v[202:205], v[246:249], v[20:23]
	v_mfma_f32_16x16x32_bf16 v[16:19], v[210:213], v[238:241], v[16:19]
	v_mfma_f32_16x16x32_bf16 v[12:15], v[210:213], v[246:249], v[12:15]
	v_mfma_f32_16x16x32_bf16 v[8:11], v[218:221], v[238:241], v[8:11]
	v_mfma_f32_16x16x32_bf16 v[4:7], v[218:221], v[246:249], v[4:7]
	s_add_i32 s29, s29, 2
	s_add_u32 s12, s12, 0x100
	s_addc_u32 s13, s13, 0
	s_cmp_lt_u32 s29, 12
	s_cbranch_scc0 .Lpk_exitb_2

; #define WAIT_V8(n) asm volatile("s_waitcnt vmcnt(" #n ")" ::: "memory")
; #define BAR8 __builtin_amdgcn_s_barrier()
; #define G_SSMEM ((float*)(wsp() + OFF_SSMEM))
;     ...
;   const int nt = K / 64;
;   if (!pre) {
;     STAGE8(SB8(0, 0), Bt, K, bcol, 0); STAGE8(SA8(0, 0), A, lda, brow, 0);
;     STAGE8(SB8(0, 1), Bt, K, bcol + 128, 0); STAGE8(SA8(0, 1), A, lda, brow + 128, 0);
;   }
;   if (wr == 1) BAR8;
;   WAIT_V8(4); BAR8;
;   STAGE8(SB8(1, 0), Bt, K, bcol, 1); STAGE8(SA8(1, 0), A, lda, brow, 1); STAGE8(SB8(1, 1), Bt, K, bcol + 128, 1);
; __global__ void __launch_bounds__(512, 2) mega(Params p) {
;     ...
;       } else {
;         const int it = item - 128;
;         const int nt = it >> 3, mt = it & 7;
;         e.ss = G_SSMEM; e.nss = 1; e.inv_n = 1.f / 1024.f; e.out = G_MEMKV; e.ldo = 1024;
;         gemm_tile<EPI_PLAIN, 256, false>(G_MEMB, DM, wb + W_XKV, DM, mt * 256, nt * 256, e);
.LBB0_1001:
	s_lshr_b32 s27, s37, 8
	s_cmpk_gt_i32 s38, 0x7f
	s_mov_b64 s[0:1], -1
	s_cbranch_scc0 .LBB0_1011
	s_mov_b32 s0, 25
	s_ashr_i32 s1, s0, 31
	s_lshl_b64 s[0:1], s[0:1], 3
	s_add_u32 s0, s70, s0
	s_addc_u32 s1, s71, s1
	v_readlane_b32 s6, v255, 60
	v_readlane_b32 s7, v255, 61
	s_nop 4
	s_mov_b32 s0, 25
	s_ashr_i32 s1, s0, 31
	s_lshl_b64 s[0:1], s[0:1], 3
	s_add_u32 s0, s70, s0
	s_addc_u32 s1, s71, s1
	v_readlane_b32 s2, v255, 60
	v_readlane_b32 s3, v255, 61
	s_nop 4
	s_mov_b32 s0, 25
	s_ashr_i32 s1, s0, 31
	s_lshl_b64 s[0:1], s[0:1], 3
	s_add_u32 s0, s70, s0
	s_addc_u32 s1, s71, s1
	v_mov_b32_e32 v3, v224
	v_readlane_b32 s12, v255, 60
	v_readlane_b32 s13, v255, 61
	s_nop 4
	s_lshl_b32 s0, s38, 8
	v_bfe_i32 v1, v3, 27, 1
	s_waitcnt vmcnt(10)
	v_lshlrev_b32_e32 v150, 4, v3
	s_nop 0
	v_readfirstlane_b32 s100, v150
	v_lshrrev_b32_e32 v1, 22, v1
	v_add_u32_e32 v1, v150, v1
	v_and_b32_e32 v1, 0xfffffc00, v1
	v_ashrrev_i32_e32 v0, 31, v3
	v_sub_u32_e32 v1, v150, v1
	v_lshrrev_b32_e32 v0, 26, v0
	v_lshrrev_b32_e32 v5, 4, v1
	v_add_u32_e32 v0, v3, v0
	v_bitop3_b32 v5, v5, v1, 32 bitop3:0x6c
	v_ashrrev_i32_e32 v1, 31, v1
	v_ashrrev_i32_e32 v0, 6, v0
	v_lshrrev_b32_e32 v1, 26, v1
	v_lshlrev_b32_e32 v6, 3, v0
	v_add_u32_e32 v1, v5, v1
	s_and_b32 s29, s0, 0x700
	s_lshl_b32 s0, s38, 5
	v_and_b32_e32 v6, -16, v6
	v_ashrrev_i32_e32 v1, 6, v1
	s_and_b32 s39, s0, 0x7fffff00
	v_add_u32_e32 v6, v1, v6
	v_mul_i32_i24_e32 v1, 64, v1
	s_add_i32 s0, s39, 0xfffff000
	v_lshlrev_b32_e32 v0, 5, v0
	v_sub_u32_e32 v1, v5, v1
	v_mov_b32_e32 v14, 1
	s_waitcnt vmcnt(9)
	s_lshl_b32 s1, s0, 11
	v_and_b32_e32 v0, 32, v0
	v_ashrrev_i16_sdwa v1, v14, sext(v1) dst_sel:DWORD dst_unused:UNUSED_PAD src0_sel:DWORD src1_sel:BYTE_0
	s_add_u32 s14, s24, s1
	v_add_u32_sdwa v0, v0, sext(v1) dst_sel:DWORD dst_unused:UNUSED_PAD src0_sel:DWORD src1_sel:WORD_0
	v_ashrrev_i32_e32 v7, 31, v6
	s_addc_u32 s15, s25, 0
	v_lshlrev_b64 v[132:133], 11, v[6:7]
	v_ashrrev_i32_e32 v1, 31, v0
	v_lshl_add_u64 v[8:9], s[14:15], 0, v[132:133]
	v_lshlrev_b64 v[6:7], 1, v[0:1]
	v_lshl_add_u64 v[10:11], v[8:9], 0, v[6:7]
	s_waitcnt vmcnt(8)
	s_or_b32 m0, s100, 0x10000
	s_nop 0
	global_load_lds_dwordx4 v[10:11], off
	s_or_b32 m0, s100, 0x12000
	s_lshl_b32 s1, s29, 11
	s_waitcnt lgkmcnt(0)
	s_add_u32 s1, s12, s1
	v_lshrrev_b32_e32 v134, 1, v6
	s_addc_u32 s40, s13, 0
	v_add_u32_e32 v136, 0x20000, v132
	v_mov_b32_e32 v137, v133
	v_mov_b32_e32 v135, v7
	s_add_u32 s8, s1, 0xb800000
	v_lshl_add_u64 v[12:13], s[14:15], 0, v[136:137]
	v_mov_b64_e32 v[8:9], v[6:7]
	s_addc_u32 s9, s40, 0
	v_lshl_add_u64 v[12:13], v[12:13], 0, v[8:9]
	v_lshl_add_u64 v[14:15], s[8:9], 0, v[132:133]
	global_load_lds_dwordx4 v[12:13], off
	s_mov_b32 m0, s100
	v_lshl_add_u64 v[16:17], v[14:15], 0, v[6:7]
	global_load_lds_dwordx4 v[16:17], off
	s_or_b32 m0, s100, 0x2000
	s_add_u32 s20, s14, 0x40000
	v_lshl_add_u64 v[14:15], s[8:9], 0, v[136:137]
	s_addc_u32 s21, s15, 0
	v_lshl_add_u64 v[14:15], v[14:15], 0, v[8:9]
	v_lshl_add_u64 v[18:19], s[20:21], 0, v[132:133]
	global_load_lds_dwordx4 v[14:15], off
	v_lshl_add_u64 v[18:19], v[18:19], 0, v[6:7]
	s_or_b32 m0, s100, 0x14000
	s_nop 0
	global_load_lds_dwordx4 v[18:19], off
	v_lshl_add_u64 v[18:19], s[20:21], 0, v[136:137]
	s_or_b32 m0, s100, 0x16000
	s_add_u32 s20, s1, 0xb840000
	v_lshl_add_u64 v[18:19], v[18:19], 0, v[8:9]
	s_addc_u32 s21, s40, 0
	global_load_lds_dwordx4 v[18:19], off
	v_lshl_add_u64 v[18:19], s[20:21], 0, v[132:133]
	v_lshl_add_u64 v[18:19], v[18:19], 0, v[6:7]
	s_or_b32 m0, s100, 0x4000
	s_nop 0
	global_load_lds_dwordx4 v[18:19], off
	v_lshl_add_u64 v[18:19], s[20:21], 0, v[136:137]
	v_lshl_add_u64 v[18:19], v[18:19], 0, v[8:9]
	s_or_b32 m0, s100, 0x6000
	v_ashrrev_i32_e32 v5, 8, v3
	global_load_lds_dwordx4 v[18:19], off
	v_cmp_eq_u32_e32 vcc, 1, v5
	s_and_saveexec_b64 s[20:21], vcc
	s_cbranch_execz .LBB0_1004
	s_barrier
.LBB0_1004:
	s_or_b64 exec, exec, s[20:21]
	v_readlane_b32 s40, v254, 35
	s_lshl_b32 s20, s36, 10
	v_readlane_b32 s42, v254, 37
	v_readlane_b32 s43, v254, 38
	s_waitcnt vmcnt(0)
	s_and_b32 s20, s20, 0xfffc0000
	s_mov_b32 s21, s40
	s_mov_b64 s[42:43], 0x80
	s_and_b32 s1, s27, 7
	s_add_i32 s20, s20, 0xffc00000
	v_lshl_add_u64 v[10:11], v[10:11], 0, s[42:43]
	s_or_b32 m0, s100, 0x18000
	s_lshl_b32 s1, s1, 19
	s_lshl_b64 s[20:21], s[20:21], 1
	s_waitcnt vmcnt(4)
	s_barrier
	global_load_lds_dwordx4 v[10:11], off
	v_lshl_add_u64 v[10:11], v[12:13], 0, s[42:43]
	s_or_b32 m0, s100, 0x1a000
	s_nop 0
	global_load_lds_dwordx4 v[10:11], off
	v_lshl_add_u64 v[10:11], v[16:17], 0, s[42:43]
	s_or_b32 m0, s100, 0x8000
	s_add_u32 s14, s14, 0x40080
	global_load_lds_dwordx4 v[10:11], off
	v_lshl_add_u64 v[10:11], v[14:15], 0, s[42:43]
	s_addc_u32 s15, s15, 0
	s_or_b32 m0, s100, 0xa000
	s_nop 0
	global_load_lds_dwordx4 v[10:11], off
	v_lshl_add_u64 v[10:11], s[14:15], 0, v[132:133]
	v_lshl_add_u64 v[10:11], v[10:11], 0, v[6:7]
	s_or_b32 m0, s100, 0x1c000
	s_nop 0
	global_load_lds_dwordx4 v[10:11], off
	v_lshl_add_u64 v[10:11], s[14:15], 0, v[136:137]
	v_lshl_add_u64 v[10:11], v[10:11], 0, v[8:9]
	s_or_b32 m0, s100, 0x1e000
	v_and_b32_e32 v147, 15, v3
	global_load_lds_dwordx4 v[10:11], off
	v_bfe_u32 v148, v3, 4, 2
	v_lshlrev_b32_e32 v11, 4, v148
	v_lshlrev_b32_e32 v12, 6, v147
	v_lshlrev_b32_e32 v14, 2, v3
	v_or_b32_e32 v13, v11, v12
	v_and_b32_e32 v14, 32, v14
	s_mov_b32 s14, 0x10000
	v_bitop3_b32 v15, v13, s14, v14 bitop3:0xde
	s_mov_b32 s14, 0x14000
	s_add_u32 s12, s12, s1
	v_bitop3_b32 v16, v13, s14, v14 bitop3:0xde
	s_mov_b32 s14, 0x18000
	v_lshlrev_b32_e32 v18, 6, v3
	s_addc_u32 s13, s13, 0
	v_lshl_add_u64 v[8:9], v[136:137], 0, v[8:9]
	v_lshl_add_u64 v[6:7], v[132:133], 0, v[6:7]
	v_bfe_u32 v146, v3, 6, 2
	s_waitcnt vmcnt(6)
	v_lshlrev_b32_e32 v149, 6, v5
	v_bitop3_b32 v17, v13, s14, v14 bitop3:0xde
	s_mov_b32 s14, 0x1c000
	v_lshlrev_b32_e32 v5, 13, v5
	v_and_b32_e32 v18, 0x3c0, v18
	v_lshl_add_u64 v[138:139], s[12:13], 0, v[8:9]
	v_lshl_add_u64 v[140:141], s[12:13], 0, v[6:7]
	s_add_u32 s12, s4, s20
	v_readlane_b32 s41, v254, 36
	v_lshlrev_b32_e32 v10, 12, v146
	v_bitop3_b32 v12, v11, v14, v12 bitop3:0x36
	v_bitop3_b32 v13, v13, s14, v14 bitop3:0xde
	v_bitop3_b32 v11, v18, v14, v11 bitop3:0x36
	v_or_b32_e32 v14, 0x800, v5
	v_or_b32_e32 v18, 0x1000, v5
	v_or_b32_e32 v19, 0x1800, v5
	s_addc_u32 s13, s5, s21
	v_lshl_add_u64 v[142:143], s[12:13], 0, v[6:7]
	v_lshl_add_u64 v[144:145], s[12:13], 0, v[8:9]
	s_mov_b32 s1, -2
	s_mov_b64 s[12:13], 0
	v_add_u32_e32 v171, v15, v10
	v_add_u32_e32 v156, v12, v5
	v_add_u32_e32 v155, v11, v14
	v_add_u32_e32 v154, v11, v18
	v_add_u32_e32 v153, v11, v19
	v_add_u32_e32 v168, v16, v10
	v_add_u32_e32 v161, v17, v10
	v_add_u32_e32 v158, v13, v10
	s_mov_b64 s[20:21], 0xb840080
	s_mov_b64 s[40:41], 0xc7a0100
	s_mov_b64 s[42:43], 0xb800100
	s_mov_b64 s[44:45], 0xc7e0100
	s_mov_b64 s[46:47], 0xb840100
	s_mov_b64 s[48:49], 0xc7a0180
	s_mov_b64 s[50:51], 0xb800180
	s_mov_b64 s[52:53], 0xc7e0180
	s_barrier
; #define LDA8(dst, b, h) _Pragma("unroll") for (int m = 0; m < 4; ++m) _Pragma("unroll") for (int k = 0; k < 2; ++k) \
;     dst[m][k] = *(const bf16x8*)((const char*)SA8(b, h) + lds_byte8(wr * 64 + m * 16 + fr, k * 32 + fq * 8))
; #define LDB8(dst, b, h) _Pragma("unroll") for (int n = 0; n < 2; ++n) _Pragma("unroll") for (int k = 0; k < 2; ++k) \
;     dst[n][k] = *(const bf16x8*)((const char*)SB8(b, h) + lds_byte8(wc * 32 + n * 16 + fr, k * 32 + fq * 8))
; #define WAIT_V8(n) asm volatile("s_waitcnt vmcnt(" #n ")" ::: "memory")
; #define WAIT_L8(n) asm volatile("s_waitcnt lgkmcnt(" #n ")" ::: "memory")
; #define BAR8 __builtin_amdgcn_s_barrier()
; #define SCHED8 __builtin_amdgcn_sched_barrier(0)
;     ...
;   for (int tt = 0; tt < nt - 2; tt += 2) {
;     LDB8(B0, 0, 0); SCHED8; LDA8(At, 0, 0); STAGE8(SA8(1, 1), A, lda, brow + 128, tt + 1);
;     WAIT_L8(8); BAR8; WAIT_L8(0); MMA8(0, 0, At, B0); BAR8; SCHED8;
;     LDB8(B1, 0, 1); STAGE8(SB8(0, 0), Bt, K, bcol, tt + 2);
;     BAR8; WAIT_L8(0); MMA8(0, 1, At, B1); BAR8;
;     LDA8(At, 0, 1); STAGE8(SA8(0, 0), A, lda, brow, tt + 2);
;     BAR8; WAIT_L8(0); MMA8(1, 0, At, B0); BAR8; SCHED8;
;     STAGE8(SB8(0, 1), Bt, K, bcol + 128, tt + 2);
;     WAIT_V8(6); BAR8; MMA8(1, 1, At, B1); BAR8;
	ds_read_b128 v[174:177], v171
	ds_read_b128 v[178:181], v171 offset:1024
	ds_read_b128 v[182:185], v171 offset:2048
	ds_read_b128 v[186:189], v171 offset:3072
	v_lshl_add_u64 v[222:223], v[140:141], 0, s[12:13]
	v_lshl_add_u64 v[226:227], v[222:223], 0, s[20:21]
	s_or_b32 m0, s100, 0xc000
	v_lshl_add_u64 v[236:237], v[138:139], 0, s[12:13]
	ds_read_b128 v[190:193], v156
	ds_read_b128 v[194:197], v156 offset:1024
	ds_read_b128 v[198:201], v155
	ds_read_b128 v[202:205], v155 offset:1024
	ds_read_b128 v[206:209], v154
	ds_read_b128 v[210:213], v154 offset:1024
	ds_read_b128 v[214:217], v153
	ds_read_b128 v[218:221], v153 offset:1024
	global_load_lds_dwordx4 v[226:227], off
	s_or_b32 m0, s100, 0xe000
	v_lshl_add_u64 v[226:227], v[236:237], 0, s[20:21]
	global_load_lds_dwordx4 v[226:227], off
	s_waitcnt lgkmcnt(8)
	s_barrier
	s_waitcnt lgkmcnt(0)
	v_mfma_f32_16x16x32_bf16 v[128:131], v[190:193], v[174:177], 0
	v_mfma_f32_16x16x32_bf16 v[124:127], v[190:193], v[182:185], 0
	v_mfma_f32_16x16x32_bf16 v[120:123], v[198:201], v[174:177], 0
	v_mfma_f32_16x16x32_bf16 v[116:119], v[198:201], v[182:185], 0
	v_mfma_f32_16x16x32_bf16 v[112:115], v[206:209], v[174:177], 0
	v_mfma_f32_16x16x32_bf16 v[108:111], v[206:209], v[182:185], 0
	v_mfma_f32_16x16x32_bf16 v[104:107], v[214:217], v[174:177], 0
	v_mfma_f32_16x16x32_bf16 v[100:103], v[214:217], v[182:185], 0
	v_mfma_f32_16x16x32_bf16 v[128:131], v[194:197], v[178:181], v[128:131]
	v_mfma_f32_16x16x32_bf16 v[124:127], v[194:197], v[186:189], v[124:127]
	v_mfma_f32_16x16x32_bf16 v[120:123], v[202:205], v[178:181], v[120:123]
	v_mfma_f32_16x16x32_bf16 v[116:119], v[202:205], v[186:189], v[116:119]
	v_mfma_f32_16x16x32_bf16 v[112:115], v[210:213], v[178:181], v[112:115]
	v_mfma_f32_16x16x32_bf16 v[108:111], v[210:213], v[186:189], v[108:111]
	v_mfma_f32_16x16x32_bf16 v[104:107], v[218:221], v[178:181], v[104:107]
	v_mfma_f32_16x16x32_bf16 v[100:103], v[218:221], v[186:189], v[100:103]
	s_barrier
	v_lshl_add_u64 v[246:247], v[142:143], 0, s[12:13]
	v_lshl_add_u64 v[248:249], v[246:247], 0, s[40:41]
	s_or_b32 m0, s100, 0x10000
	ds_read_b128 v[226:229], v168
	ds_read_b128 v[230:233], v168 offset:1024
	ds_read_b128 v[238:241], v168 offset:2048
	ds_read_b128 v[242:245], v168 offset:3072
	global_load_lds_dwordx4 v[248:249], off
	v_lshl_add_u64 v[248:249], v[144:145], 0, s[12:13]
	s_or_b32 m0, s100, 0x12000
	v_lshl_add_u64 v[250:251], v[248:249], 0, s[40:41]
	global_load_lds_dwordx4 v[250:251], off
	s_barrier
	s_waitcnt lgkmcnt(0)
	v_mfma_f32_16x16x32_bf16 v[96:99], v[190:193], v[226:229], 0
	v_mfma_f32_16x16x32_bf16 v[92:95], v[190:193], v[238:241], 0
	v_mfma_f32_16x16x32_bf16 v[88:91], v[198:201], v[226:229], 0
	v_mfma_f32_16x16x32_bf16 v[84:87], v[198:201], v[238:241], 0
	v_mfma_f32_16x16x32_bf16 v[80:83], v[206:209], v[226:229], 0
	v_mfma_f32_16x16x32_bf16 v[76:79], v[206:209], v[238:241], 0
	v_mfma_f32_16x16x32_bf16 v[72:75], v[214:217], v[226:229], 0
	v_mfma_f32_16x16x32_bf16 v[68:71], v[214:217], v[238:241], 0
	v_mfma_f32_16x16x32_bf16 v[96:99], v[194:197], v[230:233], v[96:99]
	v_mfma_f32_16x16x32_bf16 v[92:95], v[194:197], v[242:245], v[92:95]
	v_mfma_f32_16x16x32_bf16 v[88:91], v[202:205], v[230:233], v[88:91]
	v_mfma_f32_16x16x32_bf16 v[84:87], v[202:205], v[242:245], v[84:87]
	v_mfma_f32_16x16x32_bf16 v[80:83], v[210:213], v[230:233], v[80:83]
	v_mfma_f32_16x16x32_bf16 v[76:79], v[210:213], v[242:245], v[76:79]
	v_mfma_f32_16x16x32_bf16 v[72:75], v[218:221], v[230:233], v[72:75]
	v_mfma_f32_16x16x32_bf16 v[68:71], v[218:221], v[242:245], v[68:71]
	v_lshl_add_u64 v[250:251], v[222:223], 0, s[42:43]
	s_mov_b32 m0, s100
	s_barrier
	ds_read_b128 v[190:193], v156 offset:16384
	ds_read_b128 v[194:197], v156 offset:17408
	ds_read_b128 v[198:201], v155 offset:16384
	ds_read_b128 v[202:205], v155 offset:17408
	ds_read_b128 v[206:209], v154 offset:16384
	ds_read_b128 v[210:213], v154 offset:17408
	ds_read_b128 v[214:217], v153 offset:16384
	ds_read_b128 v[218:221], v153 offset:17408
	global_load_lds_dwordx4 v[250:251], off
	s_or_b32 m0, s100, 0x2000
	v_lshl_add_u64 v[250:251], v[236:237], 0, s[42:43]
	global_load_lds_dwordx4 v[250:251], off
	s_barrier
	s_waitcnt lgkmcnt(0)
	v_mfma_f32_16x16x32_bf16 v[64:67], v[190:193], v[174:177], 0
	v_mfma_f32_16x16x32_bf16 v[60:63], v[190:193], v[182:185], 0
	v_mfma_f32_16x16x32_bf16 v[56:59], v[198:201], v[174:177], 0
	v_mfma_f32_16x16x32_bf16 v[52:55], v[198:201], v[182:185], 0
	v_mfma_f32_16x16x32_bf16 v[48:51], v[206:209], v[174:177], 0
	v_mfma_f32_16x16x32_bf16 v[44:47], v[206:209], v[182:185], 0
	v_mfma_f32_16x16x32_bf16 v[40:43], v[214:217], v[174:177], 0
	v_mfma_f32_16x16x32_bf16 v[36:39], v[214:217], v[182:185], 0
	v_mfma_f32_16x16x32_bf16 v[64:67], v[194:197], v[178:181], v[64:67]
	v_mfma_f32_16x16x32_bf16 v[60:63], v[194:197], v[186:189], v[60:63]
	v_mfma_f32_16x16x32_bf16 v[56:59], v[202:205], v[178:181], v[56:59]
	v_mfma_f32_16x16x32_bf16 v[52:55], v[202:205], v[186:189], v[52:55]
	v_mfma_f32_16x16x32_bf16 v[48:51], v[210:213], v[178:181], v[48:51]
	v_mfma_f32_16x16x32_bf16 v[44:47], v[210:213], v[186:189], v[44:47]
	v_mfma_f32_16x16x32_bf16 v[40:43], v[218:221], v[178:181], v[40:43]
	v_mfma_f32_16x16x32_bf16 v[36:39], v[218:221], v[186:189], v[36:39]
	s_barrier
	s_or_b32 m0, s100, 0x14000
	v_lshl_add_u64 v[174:175], v[246:247], 0, s[44:45]
	global_load_lds_dwordx4 v[174:175], off
	s_or_b32 m0, s100, 0x16000
	v_lshl_add_u64 v[174:175], v[248:249], 0, s[44:45]
	global_load_lds_dwordx4 v[174:175], off
	s_waitcnt vmcnt(6)
	s_barrier
; #define LDA8(dst, b, h) _Pragma("unroll") for (int m = 0; m < 4; ++m) _Pragma("unroll") for (int k = 0; k < 2; ++k) \
;     dst[m][k] = *(const bf16x8*)((const char*)SA8(b, h) + lds_byte8(wr * 64 + m * 16 + fr, k * 32 + fq * 8))
; #define LDB8(dst, b, h) _Pragma("unroll") for (int n = 0; n < 2; ++n) _Pragma("unroll") for (int k = 0; k < 2; ++k) \
;     dst[n][k] = *(const bf16x8*)((const char*)SB8(b, h) + lds_byte8(wc * 32 + n * 16 + fr, k * 32 + fq * 8))
; #define WAIT_V8(n) asm volatile("s_waitcnt vmcnt(" #n ")" ::: "memory")
; #define WAIT_L8(n) asm volatile("s_waitcnt lgkmcnt(" #n ")" ::: "memory")
; #define BAR8 __builtin_amdgcn_s_barrier()
; #define SCHED8 __builtin_amdgcn_sched_barrier(0)
;     ...
;     WAIT_V8(6); BAR8; MMA8(1, 1, At, B1); BAR8;
;     LDB8(B0, 1, 0); SCHED8; LDA8(At, 1, 0); STAGE8(SA8(0, 1), A, lda, brow + 128, tt + 2);
;     WAIT_L8(8); BAR8; WAIT_L8(0); MMA8(0, 0, At, B0); BAR8; SCHED8;
;     LDB8(B1, 1, 1); STAGE8(SB8(1, 0), Bt, K, bcol, tt + 3);
;     BAR8; WAIT_L8(0); MMA8(0, 1, At, B1); BAR8;
	v_mfma_f32_16x16x32_bf16 v[32:35], v[190:193], v[226:229], 0
	v_mfma_f32_16x16x32_bf16 v[28:31], v[190:193], v[238:241], 0
	v_mfma_f32_16x16x32_bf16 v[24:27], v[198:201], v[226:229], 0
	v_mfma_f32_16x16x32_bf16 v[20:23], v[198:201], v[238:241], 0
	v_mfma_f32_16x16x32_bf16 v[16:19], v[206:209], v[226:229], 0
	v_mfma_f32_16x16x32_bf16 v[12:15], v[206:209], v[238:241], 0
	v_mfma_f32_16x16x32_bf16 v[8:11], v[214:217], v[226:229], 0
	v_mfma_f32_16x16x32_bf16 v[4:7], v[214:217], v[238:241], 0
	v_mfma_f32_16x16x32_bf16 v[32:35], v[194:197], v[230:233], v[32:35]
	v_mfma_f32_16x16x32_bf16 v[28:31], v[194:197], v[242:245], v[28:31]
	v_mfma_f32_16x16x32_bf16 v[24:27], v[202:205], v[230:233], v[24:27]
	v_mfma_f32_16x16x32_bf16 v[20:23], v[202:205], v[242:245], v[20:23]
	v_mfma_f32_16x16x32_bf16 v[16:19], v[210:213], v[230:233], v[16:19]
	v_mfma_f32_16x16x32_bf16 v[12:15], v[210:213], v[242:245], v[12:15]
	v_mfma_f32_16x16x32_bf16 v[8:11], v[218:221], v[230:233], v[8:11]
	v_mfma_f32_16x16x32_bf16 v[4:7], v[218:221], v[242:245], v[4:7]
	s_barrier
	ds_read_b128 v[174:177], v161
	ds_read_b128 v[178:181], v161 offset:1024
	ds_read_b128 v[182:185], v161 offset:2048
	ds_read_b128 v[186:189], v161 offset:3072
	v_lshl_add_u64 v[226:227], v[222:223], 0, s[46:47]
	s_or_b32 m0, s100, 0x4000
	ds_read_b128 v[190:193], v156 offset:32768
	ds_read_b128 v[194:197], v156 offset:33792
	ds_read_b128 v[198:201], v155 offset:32768
	ds_read_b128 v[202:205], v155 offset:33792
	ds_read_b128 v[206:209], v154 offset:32768
	ds_read_b128 v[210:213], v154 offset:33792
	ds_read_b128 v[214:217], v153 offset:32768
	ds_read_b128 v[218:221], v153 offset:33792
	global_load_lds_dwordx4 v[226:227], off
	s_or_b32 m0, s100, 0x6000
	v_lshl_add_u64 v[226:227], v[236:237], 0, s[46:47]
	global_load_lds_dwordx4 v[226:227], off
	s_waitcnt lgkmcnt(8)
	s_barrier
	s_waitcnt lgkmcnt(0)
	v_mfma_f32_16x16x32_bf16 v[128:131], v[190:193], v[174:177], v[128:131]
	v_mfma_f32_16x16x32_bf16 v[124:127], v[190:193], v[182:185], v[124:127]
	v_mfma_f32_16x16x32_bf16 v[120:123], v[198:201], v[174:177], v[120:123]
	v_mfma_f32_16x16x32_bf16 v[116:119], v[198:201], v[182:185], v[116:119]
	v_mfma_f32_16x16x32_bf16 v[112:115], v[206:209], v[174:177], v[112:115]
	v_mfma_f32_16x16x32_bf16 v[108:111], v[206:209], v[182:185], v[108:111]
	v_mfma_f32_16x16x32_bf16 v[104:107], v[214:217], v[174:177], v[104:107]
	v_mfma_f32_16x16x32_bf16 v[100:103], v[214:217], v[182:185], v[100:103]
	v_mfma_f32_16x16x32_bf16 v[128:131], v[194:197], v[178:181], v[128:131]
	v_mfma_f32_16x16x32_bf16 v[124:127], v[194:197], v[186:189], v[124:127]
	v_mfma_f32_16x16x32_bf16 v[120:123], v[202:205], v[178:181], v[120:123]
	v_mfma_f32_16x16x32_bf16 v[116:119], v[202:205], v[186:189], v[116:119]
	v_mfma_f32_16x16x32_bf16 v[112:115], v[210:213], v[178:181], v[112:115]
	v_mfma_f32_16x16x32_bf16 v[108:111], v[210:213], v[186:189], v[108:111]
	v_mfma_f32_16x16x32_bf16 v[104:107], v[218:221], v[178:181], v[104:107]
	v_mfma_f32_16x16x32_bf16 v[100:103], v[218:221], v[186:189], v[100:103]
	s_barrier
	v_lshl_add_u64 v[250:251], v[246:247], 0, s[48:49]
	s_or_b32 m0, s100, 0x18000
	ds_read_b128 v[226:229], v158
	ds_read_b128 v[230:233], v158 offset:1024
	ds_read_b128 v[238:241], v158 offset:2048
	ds_read_b128 v[242:245], v158 offset:3072
	global_load_lds_dwordx4 v[250:251], off
	s_or_b32 m0, s100, 0x1a000
	v_lshl_add_u64 v[250:251], v[248:249], 0, s[48:49]
	global_load_lds_dwordx4 v[250:251], off
	s_barrier
; #define LDA8(dst, b, h) _Pragma("unroll") for (int m = 0; m < 4; ++m) _Pragma("unroll") for (int k = 0; k < 2; ++k) \
;     dst[m][k] = *(const bf16x8*)((const char*)SA8(b, h) + lds_byte8(wr * 64 + m * 16 + fr, k * 32 + fq * 8))
; #define WAIT_V8(n) asm volatile("s_waitcnt vmcnt(" #n ")" ::: "memory")
; #define WAIT_L8(n) asm volatile("s_waitcnt lgkmcnt(" #n ")" ::: "memory")
; #define BAR8 __builtin_amdgcn_s_barrier()
; #define SCHED8 __builtin_amdgcn_sched_barrier(0)
;     ...
;     BAR8; WAIT_L8(0); MMA8(0, 1, At, B1); BAR8;
;     LDA8(At, 1, 1); STAGE8(SA8(1, 0), A, lda, brow, tt + 3);
;     BAR8; WAIT_L8(0); MMA8(1, 0, At, B0); BAR8; SCHED8;
;     STAGE8(SB8(1, 1), Bt, K, bcol + 128, tt + 3);
;     WAIT_V8(6); BAR8; MMA8(1, 1, At, B1); BAR8;
;   }
	s_waitcnt lgkmcnt(0)
	v_mfma_f32_16x16x32_bf16 v[96:99], v[190:193], v[226:229], v[96:99]
	v_mfma_f32_16x16x32_bf16 v[92:95], v[190:193], v[238:241], v[92:95]
	v_mfma_f32_16x16x32_bf16 v[88:91], v[198:201], v[226:229], v[88:91]
	v_mfma_f32_16x16x32_bf16 v[84:87], v[198:201], v[238:241], v[84:87]
	v_mfma_f32_16x16x32_bf16 v[80:83], v[206:209], v[226:229], v[80:83]
	v_mfma_f32_16x16x32_bf16 v[76:79], v[206:209], v[238:241], v[76:79]
	v_mfma_f32_16x16x32_bf16 v[72:75], v[214:217], v[226:229], v[72:75]
	v_mfma_f32_16x16x32_bf16 v[68:71], v[214:217], v[238:241], v[68:71]
	v_mfma_f32_16x16x32_bf16 v[96:99], v[194:197], v[230:233], v[96:99]
	v_mfma_f32_16x16x32_bf16 v[92:95], v[194:197], v[242:245], v[92:95]
	v_mfma_f32_16x16x32_bf16 v[88:91], v[202:205], v[230:233], v[88:91]
	v_mfma_f32_16x16x32_bf16 v[84:87], v[202:205], v[242:245], v[84:87]
	v_mfma_f32_16x16x32_bf16 v[80:83], v[210:213], v[230:233], v[80:83]
	v_mfma_f32_16x16x32_bf16 v[76:79], v[210:213], v[242:245], v[76:79]
	v_mfma_f32_16x16x32_bf16 v[72:75], v[218:221], v[230:233], v[72:75]
	v_mfma_f32_16x16x32_bf16 v[68:71], v[218:221], v[242:245], v[68:71]
	v_lshl_add_u64 v[222:223], v[222:223], 0, s[50:51]
	s_or_b32 m0, s100, 0x8000
	s_barrier
	ds_read_b128 v[190:193], v156 offset:49152
	ds_read_b128 v[194:197], v156 offset:50176
	ds_read_b128 v[198:201], v155 offset:49152
	ds_read_b128 v[202:205], v155 offset:50176
	ds_read_b128 v[206:209], v154 offset:49152
	ds_read_b128 v[210:213], v154 offset:50176
	ds_read_b128 v[214:217], v153 offset:49152
	ds_read_b128 v[218:221], v153 offset:50176
	global_load_lds_dwordx4 v[222:223], off
	s_or_b32 m0, s100, 0xa000
	v_lshl_add_u64 v[222:223], v[236:237], 0, s[50:51]
	global_load_lds_dwordx4 v[222:223], off
	s_barrier
	s_waitcnt lgkmcnt(0)
	v_mfma_f32_16x16x32_bf16 v[64:67], v[190:193], v[174:177], v[64:67]
	v_mfma_f32_16x16x32_bf16 v[60:63], v[190:193], v[182:185], v[60:63]
	v_mfma_f32_16x16x32_bf16 v[56:59], v[198:201], v[174:177], v[56:59]
	v_mfma_f32_16x16x32_bf16 v[52:55], v[198:201], v[182:185], v[52:55]
	v_mfma_f32_16x16x32_bf16 v[48:51], v[206:209], v[174:177], v[48:51]
	v_mfma_f32_16x16x32_bf16 v[44:47], v[206:209], v[182:185], v[44:47]
	v_mfma_f32_16x16x32_bf16 v[40:43], v[214:217], v[174:177], v[40:43]
	v_mfma_f32_16x16x32_bf16 v[36:39], v[214:217], v[182:185], v[36:39]
	v_mfma_f32_16x16x32_bf16 v[64:67], v[194:197], v[178:181], v[64:67]
	v_mfma_f32_16x16x32_bf16 v[60:63], v[194:197], v[186:189], v[60:63]
	v_mfma_f32_16x16x32_bf16 v[56:59], v[202:205], v[178:181], v[56:59]
	v_mfma_f32_16x16x32_bf16 v[52:55], v[202:205], v[186:189], v[52:55]
	v_mfma_f32_16x16x32_bf16 v[48:51], v[210:213], v[178:181], v[48:51]
	v_mfma_f32_16x16x32_bf16 v[44:47], v[210:213], v[186:189], v[44:47]
	v_mfma_f32_16x16x32_bf16 v[40:43], v[218:221], v[178:181], v[40:43]
	v_mfma_f32_16x16x32_bf16 v[36:39], v[218:221], v[186:189], v[36:39]
	s_barrier
	s_or_b32 m0, s100, 0x1c000
	v_lshl_add_u64 v[174:175], v[246:247], 0, s[52:53]
	global_load_lds_dwordx4 v[174:175], off
	s_or_b32 m0, s100, 0x1e000
	v_lshl_add_u64 v[174:175], v[248:249], 0, s[52:53]
	global_load_lds_dwordx4 v[174:175], off
	s_waitcnt vmcnt(6)
	s_barrier
	v_mfma_f32_16x16x32_bf16 v[32:35], v[190:193], v[226:229], v[32:35]
	v_mfma_f32_16x16x32_bf16 v[28:31], v[190:193], v[238:241], v[28:31]
	v_mfma_f32_16x16x32_bf16 v[24:27], v[198:201], v[226:229], v[24:27]
	v_mfma_f32_16x16x32_bf16 v[20:23], v[198:201], v[238:241], v[20:23]
	v_mfma_f32_16x16x32_bf16 v[16:19], v[206:209], v[226:229], v[16:19]
	v_mfma_f32_16x16x32_bf16 v[12:15], v[206:209], v[238:241], v[12:15]
	v_mfma_f32_16x16x32_bf16 v[8:11], v[214:217], v[226:229], v[8:11]
	v_mfma_f32_16x16x32_bf16 v[4:7], v[214:217], v[238:241], v[4:7]
	v_mfma_f32_16x16x32_bf16 v[32:35], v[194:197], v[230:233], v[32:35]
	v_mfma_f32_16x16x32_bf16 v[28:31], v[194:197], v[242:245], v[28:31]
	v_mfma_f32_16x16x32_bf16 v[24:27], v[202:205], v[230:233], v[24:27]
	v_mfma_f32_16x16x32_bf16 v[20:23], v[202:205], v[242:245], v[20:23]
	v_mfma_f32_16x16x32_bf16 v[16:19], v[210:213], v[230:233], v[16:19]
	v_mfma_f32_16x16x32_bf16 v[12:15], v[210:213], v[242:245], v[12:15]
	v_mfma_f32_16x16x32_bf16 v[8:11], v[218:221], v[230:233], v[8:11]
	v_mfma_f32_16x16x32_bf16 v[4:7], v[218:221], v[242:245], v[4:7]
	s_add_i32 s1, s1, 2
	s_add_u32 s12, s12, 0x100
	s_addc_u32 s13, s13, 0
	s_cmp_lt_u32 s1, 12
	s_cbranch_scc0 .Lpk_exitb_3

; #define WAIT_V8(n) asm volatile("s_waitcnt vmcnt(" #n ")" ::: "memory")
; #define BAR8 __builtin_amdgcn_s_barrier()
; #define G_SS ((float*)(wsp() + OFF_SS))
;     ...
;   const int nt = K / 64;
;   if (!pre) {
;     STAGE8(SB8(0, 0), Bt, K, bcol, 0); STAGE8(SA8(0, 0), A, lda, brow, 0);
;     STAGE8(SB8(0, 1), Bt, K, bcol + 128, 0); STAGE8(SA8(0, 1), A, lda, brow + 128, 0);
;   }
;   if (wr == 1) BAR8;
;   WAIT_V8(4); BAR8;
;   STAGE8(SB8(1, 0), Bt, K, bcol, 1); STAGE8(SA8(1, 0), A, lda, brow, 1); STAGE8(SB8(1, 1), Bt, K, bcol + 128, 1);
; __global__ void __launch_bounds__(512, 2) mega(Params p) {
;     ...
;       if (item < 128) {
;         const int nt = item >> 6, mt = item & 63;
;         e.ss = G_SS; e.nss = 16; e.inv_n = 1.f / 1024.f; e.out = G_XQ; e.ldo = 512;
;         gemm_tile<EPI_PLAIN, 256, true>(G_XB, DM, wb + W_XQ, DM, mt * 256, nt * 256, e);
.LBB0_1011:
	s_and_b64 vcc, exec, s[0:1]
	s_cbranch_vccz .LBB0_1000
	s_mov_b32 s0, 25
	s_ashr_i32 s1, s0, 31
	s_lshl_b64 s[0:1], s[0:1], 3
	s_add_u32 s0, s70, s0
	s_addc_u32 s1, s71, s1
	v_readlane_b32 s6, v255, 60
	v_readlane_b32 s7, v255, 61
	s_nop 4
	s_mov_b32 s0, 25
	s_ashr_i32 s1, s0, 31
	s_lshl_b64 s[0:1], s[0:1], 3
	s_add_u32 s0, s70, s0
	s_addc_u32 s1, s71, s1
	v_readlane_b32 s2, v255, 60
	v_readlane_b32 s3, v255, 61
	s_nop 4
	s_mov_b32 s0, 25
	s_ashr_i32 s1, s0, 31
	s_lshl_b64 s[0:1], s[0:1], 3
	s_add_u32 s0, s70, s0
	s_addc_u32 s1, s71, s1
	v_mov_b32_e32 v3, v224
	v_readlane_b32 s12, v255, 60
	v_readlane_b32 s13, v255, 61
	s_nop 4
	s_lshl_b32 s0, s38, 8
	v_bfe_i32 v1, v3, 27, 1
	s_waitcnt vmcnt(10)
	v_lshlrev_b32_e32 v150, 4, v3
	s_nop 0
	v_readfirstlane_b32 s100, v150
	v_lshrrev_b32_e32 v1, 22, v1
	v_add_u32_e32 v1, v150, v1
	v_and_b32_e32 v1, 0xfffffc00, v1
	v_ashrrev_i32_e32 v0, 31, v3
	v_sub_u32_e32 v1, v150, v1
	v_lshrrev_b32_e32 v0, 26, v0
	v_lshrrev_b32_e32 v5, 4, v1
	v_add_u32_e32 v0, v3, v0
	v_bitop3_b32 v5, v5, v1, 32 bitop3:0x6c
	v_ashrrev_i32_e32 v1, 31, v1
	v_ashrrev_i32_e32 v0, 6, v0
	v_lshrrev_b32_e32 v1, 26, v1
	v_lshlrev_b32_e32 v6, 3, v0
	v_add_u32_e32 v1, v5, v1
	s_and_b32 s20, s0, 0x3f00
	s_lshl_b32 s0, s38, 2
	v_and_b32_e32 v6, -16, v6
	v_ashrrev_i32_e32 v1, 6, v1
	s_and_b32 s0, s0, 0xffffff00
	v_add_u32_e32 v6, v1, v6
	v_mul_i32_i24_e32 v1, 64, v1
	s_ashr_i32 s1, s0, 31
	v_lshlrev_b32_e32 v0, 5, v0
	v_sub_u32_e32 v1, v5, v1
	v_mov_b32_e32 v14, 1
	s_waitcnt vmcnt(9)
	s_lshl_b64 s[8:9], s[0:1], 11
	v_and_b32_e32 v0, 32, v0
	v_ashrrev_i16_sdwa v1, v14, sext(v1) dst_sel:DWORD dst_unused:UNUSED_PAD src0_sel:DWORD src1_sel:BYTE_0
	s_add_u32 s8, s30, s8
	v_add_u32_sdwa v0, v0, sext(v1) dst_sel:DWORD dst_unused:UNUSED_PAD src0_sel:DWORD src1_sel:WORD_0
	v_ashrrev_i32_e32 v7, 31, v6
	s_addc_u32 s9, s31, s9
	v_lshlrev_b64 v[132:133], 11, v[6:7]
	v_ashrrev_i32_e32 v1, 31, v0
	v_lshl_add_u64 v[8:9], s[8:9], 0, v[132:133]
	v_lshlrev_b64 v[6:7], 1, v[0:1]
	v_lshl_add_u64 v[10:11], v[8:9], 0, v[6:7]
	v_lshrrev_b32_e32 v134, 1, v6
	v_add_u32_e32 v136, 0x20000, v132
	v_mov_b32_e32 v137, v133
	s_waitcnt vmcnt(8)
	s_or_b32 m0, s100, 0x10000
	v_lshl_add_u64 v[12:13], s[8:9], 0, v[136:137]
	global_load_lds_dwordx4 v[10:11], off
	s_or_b32 m0, s100, 0x12000
	s_lshl_b32 s8, s20, 11
	v_mov_b32_e32 v135, v7
	s_waitcnt lgkmcnt(0)
	s_add_u32 s8, s12, s8
	v_mov_b64_e32 v[8:9], v[6:7]
	s_addc_u32 s9, s13, 0
	v_lshl_add_u64 v[12:13], v[12:13], 0, v[8:9]
	v_lshl_add_u64 v[14:15], s[8:9], 0, v[132:133]
	global_load_lds_dwordx4 v[12:13], off
	s_mov_b32 m0, s100
	v_lshl_add_u64 v[14:15], v[14:15], 0, v[6:7]
	global_load_lds_dwordx4 v[14:15], off
	s_or_b32 m0, s100, 0x2000
	s_or_b32 s14, s0, 0x80
	s_ashr_i32 s15, s14, 31
	s_lshl_b64 s[14:15], s[14:15], 11
	s_add_u32 s14, s30, s14
	v_lshl_add_u64 v[16:17], s[8:9], 0, v[136:137]
	s_addc_u32 s15, s31, s15
	v_lshl_add_u64 v[16:17], v[16:17], 0, v[8:9]
	v_lshl_add_u64 v[18:19], s[14:15], 0, v[132:133]
	global_load_lds_dwordx4 v[16:17], off
	v_lshl_add_u64 v[18:19], v[18:19], 0, v[6:7]
	s_or_b32 m0, s100, 0x14000
	v_lshl_add_u64 v[20:21], s[14:15], 0, v[136:137]
	global_load_lds_dwordx4 v[18:19], off
	s_or_b32 m0, s100, 0x16000
	s_add_u32 s14, s8, 0x40000
	s_addc_u32 s15, s9, 0
	v_lshl_add_u64 v[20:21], v[20:21], 0, v[8:9]
	v_lshl_add_u64 v[22:23], s[14:15], 0, v[132:133]
	global_load_lds_dwordx4 v[20:21], off
	v_lshl_add_u64 v[22:23], v[22:23], 0, v[6:7]
	s_or_b32 m0, s100, 0x4000
	s_nop 0
	global_load_lds_dwordx4 v[22:23], off
	v_lshl_add_u64 v[22:23], s[14:15], 0, v[136:137]
	v_lshl_add_u64 v[22:23], v[22:23], 0, v[8:9]
	s_or_b32 m0, s100, 0x6000
	v_ashrrev_i32_e32 v5, 8, v3
	global_load_lds_dwordx4 v[22:23], off
	v_cmp_eq_u32_e32 vcc, 1, v5
	s_and_saveexec_b64 s[14:15], vcc
	s_cbranch_execz .LBB0_1014
	s_barrier
.LBB0_1014:
	s_or_b64 exec, exec, s[14:15]
	v_readlane_b32 s40, v254, 35
	v_readlane_b32 s42, v254, 37
	v_readlane_b32 s43, v254, 38
	s_waitcnt vmcnt(0)
	s_mov_b64 s[42:43], 0x80
	v_lshl_add_u64 v[10:11], v[10:11], 0, s[42:43]
	s_or_b32 m0, s100, 0x18000
	s_waitcnt vmcnt(4)
	s_barrier
	global_load_lds_dwordx4 v[10:11], off
	v_lshl_add_u64 v[10:11], v[12:13], 0, s[42:43]
	s_or_b32 m0, s100, 0x1a000
	s_nop 0
	global_load_lds_dwordx4 v[10:11], off
	v_lshl_add_u64 v[10:11], v[14:15], 0, s[42:43]
	s_or_b32 m0, s100, 0x8000
	s_nop 0
	global_load_lds_dwordx4 v[10:11], off
	v_lshl_add_u64 v[10:11], v[16:17], 0, s[42:43]
	s_or_b32 m0, s100, 0xa000
	s_nop 0
	global_load_lds_dwordx4 v[10:11], off
	s_or_b32 m0, s100, 0x1c000
	v_lshl_add_u64 v[10:11], v[18:19], 0, s[42:43]
	global_load_lds_dwordx4 v[10:11], off
	v_lshl_add_u64 v[10:11], v[20:21], 0, s[42:43]
	s_or_b32 m0, s100, 0x1e000
	v_and_b32_e32 v147, 15, v3
	global_load_lds_dwordx4 v[10:11], off
	v_bfe_u32 v148, v3, 4, 2
	v_lshlrev_b32_e32 v10, 4, v148
	v_lshlrev_b32_e32 v11, 6, v147
	v_lshlrev_b32_e32 v14, 2, v3
	v_or_b32_e32 v13, v10, v11
	v_and_b32_e32 v14, 32, v14
	s_mov_b32 s21, 0x10000
	v_bitop3_b32 v16, v13, s21, v14 bitop3:0xde
	s_mov_b32 s21, 0x14000
	s_and_b32 s14, s27, 63
	v_bitop3_b32 v15, v10, v14, v11 bitop3:0x36
	v_bitop3_b32 v17, v13, s21, v14 bitop3:0xde
	s_mov_b32 s21, 0x18000
	v_lshlrev_b32_e32 v11, 6, v3
	s_lshl_b32 s14, s14, 19
	s_mov_b32 s15, s40
	v_bitop3_b32 v18, v13, s21, v14 bitop3:0xde
	s_mov_b32 s21, 0x1c000
	v_and_b32_e32 v11, 0x3c0, v11
	v_bitop3_b32 v13, v13, s21, v14 bitop3:0xde
	v_bitop3_b32 v14, v11, v14, v10 bitop3:0x36
	v_lshl_add_u64 v[10:11], s[14:15], 0, v[136:137]
	v_readlane_b32 s41, v254, 36
	s_and_b32 s40, s33, 0xffffff00
	v_lshl_add_u64 v[10:11], v[10:11], 0, v[8:9]
	s_ashr_i32 s41, s40, 31
	v_lshl_add_u64 v[138:139], s[12:13], 0, v[10:11]
	v_lshl_add_u64 v[10:11], s[14:15], 0, v[132:133]
	s_lshl_b64 s[40:41], s[40:41], 11
	v_lshl_add_u64 v[10:11], v[10:11], 0, v[6:7]
	v_lshl_add_u64 v[140:141], s[12:13], 0, v[10:11]
	v_lshl_add_u64 v[10:11], s[40:41], 0, v[132:133]
	v_lshl_add_u64 v[6:7], v[10:11], 0, v[6:7]
	v_bfe_u32 v146, v3, 6, 2
	s_waitcnt vmcnt(6)
	v_lshlrev_b32_e32 v149, 6, v5
	v_lshlrev_b32_e32 v5, 13, v5
	v_lshl_add_u64 v[142:143], s[4:5], 0, v[6:7]
	v_lshl_add_u64 v[6:7], s[40:41], 0, v[136:137]
	v_lshlrev_b32_e32 v12, 12, v146
	v_or_b32_e32 v19, 0x800, v5
	v_or_b32_e32 v20, 0x1000, v5
	v_or_b32_e32 v21, 0x1800, v5
	v_lshl_add_u64 v[6:7], v[6:7], 0, v[8:9]
	v_lshl_add_u64 v[144:145], s[4:5], 0, v[6:7]
	s_mov_b32 s14, -2
	s_mov_b64 s[12:13], 0
	v_add_u32_e32 v171, v16, v12
	v_add_u32_e32 v156, v15, v5
	v_add_u32_e32 v155, v14, v19
	v_add_u32_e32 v154, v14, v20
	v_add_u32_e32 v153, v14, v21
	v_add_u32_e32 v168, v17, v12
	v_add_u32_e32 v161, v18, v12
	v_add_u32_e32 v158, v13, v12
	s_mov_b64 s[40:41], 0xc6a0100
	s_mov_b64 s[42:43], 0xc6e0100
	s_mov_b64 s[44:45], 0xc6a0180
	s_mov_b64 s[46:47], 0xc6e0180
	s_barrier
; #define LDA8(dst, b, h) _Pragma("unroll") for (int m = 0; m < 4; ++m) _Pragma("unroll") for (int k = 0; k < 2; ++k) \
;     dst[m][k] = *(const bf16x8*)((const char*)SA8(b, h) + lds_byte8(wr * 64 + m * 16 + fr, k * 32 + fq * 8))
; #define LDB8(dst, b, h) _Pragma("unroll") for (int n = 0; n < 2; ++n) _Pragma("unroll") for (int k = 0; k < 2; ++k) \
;     dst[n][k] = *(const bf16x8*)((const char*)SB8(b, h) + lds_byte8(wc * 32 + n * 16 + fr, k * 32 + fq * 8))
; #define WAIT_V8(n) asm volatile("s_waitcnt vmcnt(" #n ")" ::: "memory")
; #define WAIT_L8(n) asm volatile("s_waitcnt lgkmcnt(" #n ")" ::: "memory")
; #define BAR8 __builtin_amdgcn_s_barrier()
; #define SCHED8 __builtin_amdgcn_sched_barrier(0)
;     ...
;   for (int tt = 0; tt < nt - 2; tt += 2) {
;     LDB8(B0, 0, 0); SCHED8; LDA8(At, 0, 0); STAGE8(SA8(1, 1), A, lda, brow + 128, tt + 1);
;     WAIT_L8(8); BAR8; WAIT_L8(0); MMA8(0, 0, At, B0); BAR8; SCHED8;
;     LDB8(B1, 0, 1); STAGE8(SB8(0, 0), Bt, K, bcol, tt + 2);
;     BAR8; WAIT_L8(0); MMA8(0, 1, At, B1); BAR8;
;     LDA8(At, 0, 1); STAGE8(SA8(0, 0), A, lda, brow, tt + 2);
;     BAR8; WAIT_L8(0); MMA8(1, 0, At, B0); BAR8; SCHED8;
;     STAGE8(SB8(0, 1), Bt, K, bcol + 128, tt + 2);
;     WAIT_V8(6); BAR8; MMA8(1, 1, At, B1); BAR8;
	ds_read_b128 v[174:177], v171
	ds_read_b128 v[178:181], v171 offset:1024
	ds_read_b128 v[182:185], v171 offset:2048
	ds_read_b128 v[186:189], v171 offset:3072
	v_lshl_add_u64 v[222:223], v[140:141], 0, s[12:13]
	v_lshl_add_u64 v[226:227], v[222:223], 0, s[34:35]
	s_or_b32 m0, s100, 0xc000
	v_lshl_add_u64 v[236:237], v[138:139], 0, s[12:13]
	ds_read_b128 v[190:193], v156
	ds_read_b128 v[194:197], v156 offset:1024
	ds_read_b128 v[198:201], v155
	ds_read_b128 v[202:205], v155 offset:1024
	ds_read_b128 v[206:209], v154
	ds_read_b128 v[210:213], v154 offset:1024
	ds_read_b128 v[214:217], v153
	ds_read_b128 v[218:221], v153 offset:1024
	global_load_lds_dwordx4 v[226:227], off
	s_or_b32 m0, s100, 0xe000
	v_lshl_add_u64 v[226:227], v[236:237], 0, s[34:35]
	global_load_lds_dwordx4 v[226:227], off
	s_waitcnt lgkmcnt(8)
	s_barrier
	s_waitcnt lgkmcnt(0)
	v_mfma_f32_16x16x32_f16 v[128:131], v[190:193], v[174:177], 0
	v_mfma_f32_16x16x32_f16 v[124:127], v[190:193], v[182:185], 0
	v_mfma_f32_16x16x32_f16 v[120:123], v[198:201], v[174:177], 0
	v_mfma_f32_16x16x32_f16 v[116:119], v[198:201], v[182:185], 0
	v_mfma_f32_16x16x32_f16 v[112:115], v[206:209], v[174:177], 0
	v_mfma_f32_16x16x32_f16 v[108:111], v[206:209], v[182:185], 0
	v_mfma_f32_16x16x32_f16 v[104:107], v[214:217], v[174:177], 0
	v_mfma_f32_16x16x32_f16 v[100:103], v[214:217], v[182:185], 0
	v_mfma_f32_16x16x32_f16 v[128:131], v[194:197], v[178:181], v[128:131]
	v_mfma_f32_16x16x32_f16 v[124:127], v[194:197], v[186:189], v[124:127]
	v_mfma_f32_16x16x32_f16 v[120:123], v[202:205], v[178:181], v[120:123]
	v_mfma_f32_16x16x32_f16 v[116:119], v[202:205], v[186:189], v[116:119]
	v_mfma_f32_16x16x32_f16 v[112:115], v[210:213], v[178:181], v[112:115]
	v_mfma_f32_16x16x32_f16 v[108:111], v[210:213], v[186:189], v[108:111]
	v_mfma_f32_16x16x32_f16 v[104:107], v[218:221], v[178:181], v[104:107]
	v_mfma_f32_16x16x32_f16 v[100:103], v[218:221], v[186:189], v[100:103]
	s_barrier
	v_lshl_add_u64 v[246:247], v[142:143], 0, s[12:13]
	v_lshl_add_u64 v[248:249], v[246:247], 0, s[40:41]
	s_or_b32 m0, s100, 0x10000
	ds_read_b128 v[226:229], v168
	ds_read_b128 v[230:233], v168 offset:1024
	ds_read_b128 v[238:241], v168 offset:2048
	ds_read_b128 v[242:245], v168 offset:3072
	global_load_lds_dwordx4 v[248:249], off
	v_lshl_add_u64 v[248:249], v[144:145], 0, s[12:13]
	s_or_b32 m0, s100, 0x12000
	v_lshl_add_u64 v[250:251], v[248:249], 0, s[40:41]
	global_load_lds_dwordx4 v[250:251], off
	s_barrier
	s_waitcnt lgkmcnt(0)
	v_mfma_f32_16x16x32_f16 v[96:99], v[190:193], v[226:229], 0
	v_mfma_f32_16x16x32_f16 v[92:95], v[190:193], v[238:241], 0
	v_mfma_f32_16x16x32_f16 v[88:91], v[198:201], v[226:229], 0
	v_mfma_f32_16x16x32_f16 v[84:87], v[198:201], v[238:241], 0
	v_mfma_f32_16x16x32_f16 v[80:83], v[206:209], v[226:229], 0
	v_mfma_f32_16x16x32_f16 v[76:79], v[206:209], v[238:241], 0
	v_mfma_f32_16x16x32_f16 v[72:75], v[214:217], v[226:229], 0
	v_mfma_f32_16x16x32_f16 v[68:71], v[214:217], v[238:241], 0
	v_mfma_f32_16x16x32_f16 v[96:99], v[194:197], v[230:233], v[96:99]
	v_mfma_f32_16x16x32_f16 v[92:95], v[194:197], v[242:245], v[92:95]
	v_mfma_f32_16x16x32_f16 v[88:91], v[202:205], v[230:233], v[88:91]
	v_mfma_f32_16x16x32_f16 v[84:87], v[202:205], v[242:245], v[84:87]
	v_mfma_f32_16x16x32_f16 v[80:83], v[210:213], v[230:233], v[80:83]
	v_mfma_f32_16x16x32_f16 v[76:79], v[210:213], v[242:245], v[76:79]
	v_mfma_f32_16x16x32_f16 v[72:75], v[218:221], v[230:233], v[72:75]
	v_mfma_f32_16x16x32_f16 v[68:71], v[218:221], v[242:245], v[68:71]
	v_lshl_add_u64 v[250:251], v[222:223], 0, s[10:11]
	s_mov_b32 m0, s100
	s_barrier
	ds_read_b128 v[190:193], v156 offset:16384
	ds_read_b128 v[194:197], v156 offset:17408
	ds_read_b128 v[198:201], v155 offset:16384
	ds_read_b128 v[202:205], v155 offset:17408
	ds_read_b128 v[206:209], v154 offset:16384
	ds_read_b128 v[210:213], v154 offset:17408
	ds_read_b128 v[214:217], v153 offset:16384
	ds_read_b128 v[218:221], v153 offset:17408
	global_load_lds_dwordx4 v[250:251], off
	s_or_b32 m0, s100, 0x2000
	v_lshl_add_u64 v[250:251], v[236:237], 0, s[10:11]
	global_load_lds_dwordx4 v[250:251], off
	s_barrier
	s_waitcnt lgkmcnt(0)
	v_mfma_f32_16x16x32_f16 v[64:67], v[190:193], v[174:177], 0
	v_mfma_f32_16x16x32_f16 v[60:63], v[190:193], v[182:185], 0
	v_mfma_f32_16x16x32_f16 v[56:59], v[198:201], v[174:177], 0
	v_mfma_f32_16x16x32_f16 v[52:55], v[198:201], v[182:185], 0
	v_mfma_f32_16x16x32_f16 v[48:51], v[206:209], v[174:177], 0
	v_mfma_f32_16x16x32_f16 v[44:47], v[206:209], v[182:185], 0
	v_mfma_f32_16x16x32_f16 v[40:43], v[214:217], v[174:177], 0
	v_mfma_f32_16x16x32_f16 v[36:39], v[214:217], v[182:185], 0
	v_mfma_f32_16x16x32_f16 v[64:67], v[194:197], v[178:181], v[64:67]
	v_mfma_f32_16x16x32_f16 v[60:63], v[194:197], v[186:189], v[60:63]
	v_mfma_f32_16x16x32_f16 v[56:59], v[202:205], v[178:181], v[56:59]
	v_mfma_f32_16x16x32_f16 v[52:55], v[202:205], v[186:189], v[52:55]
	v_mfma_f32_16x16x32_f16 v[48:51], v[210:213], v[178:181], v[48:51]
	v_mfma_f32_16x16x32_f16 v[44:47], v[210:213], v[186:189], v[44:47]
	v_mfma_f32_16x16x32_f16 v[40:43], v[218:221], v[178:181], v[40:43]
	v_mfma_f32_16x16x32_f16 v[36:39], v[218:221], v[186:189], v[36:39]
	s_barrier
	s_or_b32 m0, s100, 0x14000
	v_lshl_add_u64 v[174:175], v[246:247], 0, s[42:43]
	global_load_lds_dwordx4 v[174:175], off
	s_or_b32 m0, s100, 0x16000
	v_lshl_add_u64 v[174:175], v[248:249], 0, s[42:43]
	global_load_lds_dwordx4 v[174:175], off
	s_waitcnt vmcnt(6)
	s_barrier
; #define LDA8(dst, b, h) _Pragma("unroll") for (int m = 0; m < 4; ++m) _Pragma("unroll") for (int k = 0; k < 2; ++k) \
;     dst[m][k] = *(const bf16x8*)((const char*)SA8(b, h) + lds_byte8(wr * 64 + m * 16 + fr, k * 32 + fq * 8))
; #define LDB8(dst, b, h) _Pragma("unroll") for (int n = 0; n < 2; ++n) _Pragma("unroll") for (int k = 0; k < 2; ++k) \
;     dst[n][k] = *(const bf16x8*)((const char*)SB8(b, h) + lds_byte8(wc * 32 + n * 16 + fr, k * 32 + fq * 8))
; #define WAIT_V8(n) asm volatile("s_waitcnt vmcnt(" #n ")" ::: "memory")
; #define WAIT_L8(n) asm volatile("s_waitcnt lgkmcnt(" #n ")" ::: "memory")
; #define BAR8 __builtin_amdgcn_s_barrier()
; #define SCHED8 __builtin_amdgcn_sched_barrier(0)
;     ...
;     WAIT_V8(6); BAR8; MMA8(1, 1, At, B1); BAR8;
;     LDB8(B0, 1, 0); SCHED8; LDA8(At, 1, 0); STAGE8(SA8(0, 1), A, lda, brow + 128, tt + 2);
;     WAIT_L8(8); BAR8; WAIT_L8(0); MMA8(0, 0, At, B0); BAR8; SCHED8;
;     LDB8(B1, 1, 1); STAGE8(SB8(1, 0), Bt, K, bcol, tt + 3);
;     BAR8; WAIT_L8(0); MMA8(0, 1, At, B1); BAR8;
	v_mfma_f32_16x16x32_f16 v[32:35], v[190:193], v[226:229], 0
	v_mfma_f32_16x16x32_f16 v[28:31], v[190:193], v[238:241], 0
	v_mfma_f32_16x16x32_f16 v[24:27], v[198:201], v[226:229], 0
	v_mfma_f32_16x16x32_f16 v[20:23], v[198:201], v[238:241], 0
	v_mfma_f32_16x16x32_f16 v[16:19], v[206:209], v[226:229], 0
	v_mfma_f32_16x16x32_f16 v[12:15], v[206:209], v[238:241], 0
	v_mfma_f32_16x16x32_f16 v[8:11], v[214:217], v[226:229], 0
	v_mfma_f32_16x16x32_f16 v[4:7], v[214:217], v[238:241], 0
	v_mfma_f32_16x16x32_f16 v[32:35], v[194:197], v[230:233], v[32:35]
	v_mfma_f32_16x16x32_f16 v[28:31], v[194:197], v[242:245], v[28:31]
	v_mfma_f32_16x16x32_f16 v[24:27], v[202:205], v[230:233], v[24:27]
	v_mfma_f32_16x16x32_f16 v[20:23], v[202:205], v[242:245], v[20:23]
	v_mfma_f32_16x16x32_f16 v[16:19], v[210:213], v[230:233], v[16:19]
	v_mfma_f32_16x16x32_f16 v[12:15], v[210:213], v[242:245], v[12:15]
	v_mfma_f32_16x16x32_f16 v[8:11], v[218:221], v[230:233], v[8:11]
	v_mfma_f32_16x16x32_f16 v[4:7], v[218:221], v[242:245], v[4:7]
	s_barrier
	ds_read_b128 v[174:177], v161
	ds_read_b128 v[178:181], v161 offset:1024
	ds_read_b128 v[182:185], v161 offset:2048
	ds_read_b128 v[186:189], v161 offset:3072
	v_lshl_add_u64 v[226:227], v[222:223], 0, s[18:19]
	s_or_b32 m0, s100, 0x4000
	ds_read_b128 v[190:193], v156 offset:32768
	ds_read_b128 v[194:197], v156 offset:33792
	ds_read_b128 v[198:201], v155 offset:32768
	ds_read_b128 v[202:205], v155 offset:33792
	ds_read_b128 v[206:209], v154 offset:32768
	ds_read_b128 v[210:213], v154 offset:33792
	ds_read_b128 v[214:217], v153 offset:32768
	ds_read_b128 v[218:221], v153 offset:33792
	global_load_lds_dwordx4 v[226:227], off
	s_or_b32 m0, s100, 0x6000
	v_lshl_add_u64 v[226:227], v[236:237], 0, s[18:19]
	global_load_lds_dwordx4 v[226:227], off
	s_waitcnt lgkmcnt(8)
	s_barrier
	s_waitcnt lgkmcnt(0)
	v_mfma_f32_16x16x32_f16 v[128:131], v[190:193], v[174:177], v[128:131]
	v_mfma_f32_16x16x32_f16 v[124:127], v[190:193], v[182:185], v[124:127]
	v_mfma_f32_16x16x32_f16 v[120:123], v[198:201], v[174:177], v[120:123]
	v_mfma_f32_16x16x32_f16 v[116:119], v[198:201], v[182:185], v[116:119]
	v_mfma_f32_16x16x32_f16 v[112:115], v[206:209], v[174:177], v[112:115]
	v_mfma_f32_16x16x32_f16 v[108:111], v[206:209], v[182:185], v[108:111]
	v_mfma_f32_16x16x32_f16 v[104:107], v[214:217], v[174:177], v[104:107]
	v_mfma_f32_16x16x32_f16 v[100:103], v[214:217], v[182:185], v[100:103]
	v_mfma_f32_16x16x32_f16 v[128:131], v[194:197], v[178:181], v[128:131]
	v_mfma_f32_16x16x32_f16 v[124:127], v[194:197], v[186:189], v[124:127]
	v_mfma_f32_16x16x32_f16 v[120:123], v[202:205], v[178:181], v[120:123]
	v_mfma_f32_16x16x32_f16 v[116:119], v[202:205], v[186:189], v[116:119]
	v_mfma_f32_16x16x32_f16 v[112:115], v[210:213], v[178:181], v[112:115]
	v_mfma_f32_16x16x32_f16 v[108:111], v[210:213], v[186:189], v[108:111]
	v_mfma_f32_16x16x32_f16 v[104:107], v[218:221], v[178:181], v[104:107]
	v_mfma_f32_16x16x32_f16 v[100:103], v[218:221], v[186:189], v[100:103]
	s_barrier
	v_lshl_add_u64 v[250:251], v[246:247], 0, s[44:45]
	s_or_b32 m0, s100, 0x18000
	ds_read_b128 v[226:229], v158
	ds_read_b128 v[230:233], v158 offset:1024
	ds_read_b128 v[238:241], v158 offset:2048
	ds_read_b128 v[242:245], v158 offset:3072
	global_load_lds_dwordx4 v[250:251], off
	s_or_b32 m0, s100, 0x1a000
	v_lshl_add_u64 v[250:251], v[248:249], 0, s[44:45]
	global_load_lds_dwordx4 v[250:251], off
	s_barrier
; #define LDA8(dst, b, h) _Pragma("unroll") for (int m = 0; m < 4; ++m) _Pragma("unroll") for (int k = 0; k < 2; ++k) \
;     dst[m][k] = *(const bf16x8*)((const char*)SA8(b, h) + lds_byte8(wr * 64 + m * 16 + fr, k * 32 + fq * 8))
; #define LDB8(dst, b, h) _Pragma("unroll") for (int n = 0; n < 2; ++n) _Pragma("unroll") for (int k = 0; k < 2; ++k) \
;     dst[n][k] = *(const bf16x8*)((const char*)SB8(b, h) + lds_byte8(wc * 32 + n * 16 + fr, k * 32 + fq * 8))
; #define WAIT_V8(n) asm volatile("s_waitcnt vmcnt(" #n ")" ::: "memory")
; #define WAIT_L8(n) asm volatile("s_waitcnt lgkmcnt(" #n ")" ::: "memory")
; #define BAR8 __builtin_amdgcn_s_barrier()
; #define SCHED8 __builtin_amdgcn_sched_barrier(0)
;     ...
;     BAR8; WAIT_L8(0); MMA8(1, 0, At, B0); BAR8; SCHED8;
;     STAGE8(SB8(0, 1), Bt, K, bcol + 128, tt + 2);
;     WAIT_V8(6); BAR8; MMA8(1, 1, At, B1); BAR8;
;     LDB8(B0, 1, 0); SCHED8; LDA8(At, 1, 0); STAGE8(SA8(0, 1), A, lda, brow + 128, tt + 2);
;     WAIT_L8(8); BAR8; WAIT_L8(0); MMA8(0, 0, At, B0); BAR8; SCHED8;
;     LDB8(B1, 1, 1); STAGE8(SB8(1, 0), Bt, K, bcol, tt + 3);
;     BAR8; WAIT_L8(0); MMA8(0, 1, At, B1); BAR8;
;     LDA8(At, 1, 1); STAGE8(SA8(1, 0), A, lda, brow, tt + 3);
;     BAR8; WAIT_L8(0); MMA8(1, 0, At, B0); BAR8; SCHED8;
;     STAGE8(SB8(1, 1), Bt, K, bcol + 128, tt + 3);
;     WAIT_V8(6); BAR8; MMA8(1, 1, At, B1); BAR8;
;   }
	s_waitcnt lgkmcnt(0)
	v_mfma_f32_16x16x32_f16 v[96:99], v[190:193], v[226:229], v[96:99]
	v_mfma_f32_16x16x32_f16 v[92:95], v[190:193], v[238:241], v[92:95]
	v_mfma_f32_16x16x32_f16 v[88:91], v[198:201], v[226:229], v[88:91]
	v_mfma_f32_16x16x32_f16 v[84:87], v[198:201], v[238:241], v[84:87]
	v_mfma_f32_16x16x32_f16 v[80:83], v[206:209], v[226:229], v[80:83]
	v_mfma_f32_16x16x32_f16 v[76:79], v[206:209], v[238:241], v[76:79]
	v_mfma_f32_16x16x32_f16 v[72:75], v[214:217], v[226:229], v[72:75]
	v_mfma_f32_16x16x32_f16 v[68:71], v[214:217], v[238:241], v[68:71]
	v_mfma_f32_16x16x32_f16 v[96:99], v[194:197], v[230:233], v[96:99]
	v_mfma_f32_16x16x32_f16 v[92:95], v[194:197], v[242:245], v[92:95]
	v_mfma_f32_16x16x32_f16 v[88:91], v[202:205], v[230:233], v[88:91]
	v_mfma_f32_16x16x32_f16 v[84:87], v[202:205], v[242:245], v[84:87]
	v_mfma_f32_16x16x32_f16 v[80:83], v[210:213], v[230:233], v[80:83]
	v_mfma_f32_16x16x32_f16 v[76:79], v[210:213], v[242:245], v[76:79]
	v_mfma_f32_16x16x32_f16 v[72:75], v[218:221], v[230:233], v[72:75]
	v_mfma_f32_16x16x32_f16 v[68:71], v[218:221], v[242:245], v[68:71]
	v_lshl_add_u64 v[222:223], v[222:223], 0, s[22:23]
	s_or_b32 m0, s100, 0x8000
	s_barrier
	ds_read_b128 v[190:193], v156 offset:49152
	ds_read_b128 v[194:197], v156 offset:50176
	ds_read_b128 v[198:201], v155 offset:49152
	ds_read_b128 v[202:205], v155 offset:50176
	ds_read_b128 v[206:209], v154 offset:49152
	ds_read_b128 v[210:213], v154 offset:50176
	ds_read_b128 v[214:217], v153 offset:49152
	ds_read_b128 v[218:221], v153 offset:50176
	global_load_lds_dwordx4 v[222:223], off
	s_or_b32 m0, s100, 0xa000
	v_lshl_add_u64 v[222:223], v[236:237], 0, s[22:23]
	global_load_lds_dwordx4 v[222:223], off
	s_barrier
	s_waitcnt lgkmcnt(0)
	v_mfma_f32_16x16x32_f16 v[64:67], v[190:193], v[174:177], v[64:67]
	v_mfma_f32_16x16x32_f16 v[60:63], v[190:193], v[182:185], v[60:63]
	v_mfma_f32_16x16x32_f16 v[56:59], v[198:201], v[174:177], v[56:59]
	v_mfma_f32_16x16x32_f16 v[52:55], v[198:201], v[182:185], v[52:55]
	v_mfma_f32_16x16x32_f16 v[48:51], v[206:209], v[174:177], v[48:51]
	v_mfma_f32_16x16x32_f16 v[44:47], v[206:209], v[182:185], v[44:47]
	v_mfma_f32_16x16x32_f16 v[40:43], v[214:217], v[174:177], v[40:43]
	v_mfma_f32_16x16x32_f16 v[36:39], v[214:217], v[182:185], v[36:39]
	v_mfma_f32_16x16x32_f16 v[64:67], v[194:197], v[178:181], v[64:67]
	v_mfma_f32_16x16x32_f16 v[60:63], v[194:197], v[186:189], v[60:63]
	v_mfma_f32_16x16x32_f16 v[56:59], v[202:205], v[178:181], v[56:59]
	v_mfma_f32_16x16x32_f16 v[52:55], v[202:205], v[186:189], v[52:55]
	v_mfma_f32_16x16x32_f16 v[48:51], v[210:213], v[178:181], v[48:51]
	v_mfma_f32_16x16x32_f16 v[44:47], v[210:213], v[186:189], v[44:47]
	v_mfma_f32_16x16x32_f16 v[40:43], v[218:221], v[178:181], v[40:43]
	v_mfma_f32_16x16x32_f16 v[36:39], v[218:221], v[186:189], v[36:39]
	s_barrier
	s_or_b32 m0, s100, 0x1c000
	v_lshl_add_u64 v[174:175], v[246:247], 0, s[46:47]
	global_load_lds_dwordx4 v[174:175], off
	s_or_b32 m0, s100, 0x1e000
	v_lshl_add_u64 v[174:175], v[248:249], 0, s[46:47]
	global_load_lds_dwordx4 v[174:175], off
	s_waitcnt vmcnt(6)
	s_barrier
	v_mfma_f32_16x16x32_f16 v[32:35], v[190:193], v[226:229], v[32:35]
	v_mfma_f32_16x16x32_f16 v[28:31], v[190:193], v[238:241], v[28:31]
	v_mfma_f32_16x16x32_f16 v[24:27], v[198:201], v[226:229], v[24:27]
	v_mfma_f32_16x16x32_f16 v[20:23], v[198:201], v[238:241], v[20:23]
	v_mfma_f32_16x16x32_f16 v[16:19], v[206:209], v[226:229], v[16:19]
	v_mfma_f32_16x16x32_f16 v[12:15], v[206:209], v[238:241], v[12:15]
	v_mfma_f32_16x16x32_f16 v[8:11], v[214:217], v[226:229], v[8:11]
	v_mfma_f32_16x16x32_f16 v[4:7], v[214:217], v[238:241], v[4:7]
	v_mfma_f32_16x16x32_f16 v[32:35], v[194:197], v[230:233], v[32:35]
	v_mfma_f32_16x16x32_f16 v[28:31], v[194:197], v[242:245], v[28:31]
	v_mfma_f32_16x16x32_f16 v[24:27], v[202:205], v[230:233], v[24:27]
	v_mfma_f32_16x16x32_f16 v[20:23], v[202:205], v[242:245], v[20:23]
	v_mfma_f32_16x16x32_f16 v[16:19], v[210:213], v[230:233], v[16:19]
	v_mfma_f32_16x16x32_f16 v[12:15], v[210:213], v[242:245], v[12:15]
	v_mfma_f32_16x16x32_f16 v[8:11], v[218:221], v[230:233], v[8:11]
	v_mfma_f32_16x16x32_f16 v[4:7], v[218:221], v[242:245], v[4:7]
	s_add_i32 s14, s14, 2
	s_add_u32 s12, s12, 0x100
	s_addc_u32 s13, s13, 0
	s_cmp_lt_u32 s14, 12
	s_cbranch_scc0 .Lpk_exitb_4

; #define BAR8 __builtin_amdgcn_s_barrier()
;     ...
;   const int brow = m0, bcol = n0;
;   const int wid = t >> 6, lane = t & 63, wr = wid >> 2, wc = wid & 3, fr = lane & 15, fq = lane >> 4;
;   f32x4 acc[2][2][4][2];
;   {
;     float zinit = 0.f;
;     asm volatile("" : "+v"(zinit));
; #pragma unroll
;     for (int a = 0; a < 2; ++a)
; #pragma unroll
;       for (int b = 0; b < 2; ++b)
; #pragma unroll
;         for (int m = 0; m < 4; ++m)
; #pragma unroll
;           for (int n = 0; n < 2; ++n)
; #pragma unroll
;             for (int j = 0; j < 4; ++j) acc[a][b][m][n][j] = zinit;
;   }
;   bf16x8 At[4][2], B0[2][2], B1[2][2];
;   const int nt = K / 64;
;   if (!pre) {
;     STAGE8(SB8(0, 0), Bt, K, bcol, 0); STAGE8(SA8(0, 0), A, lda, brow, 0);
;     STAGE8(SB8(0, 1), Bt, K, bcol + 128, 0); STAGE8(SA8(0, 1), A, lda, brow + 128, 0);
;   }
;   if (wr == 1) BAR8;
.LBB0_1149:
	s_mov_b32 s0, 24
	s_mov_b32 s0, 25
	s_ashr_i32 s1, s0, 31
	s_lshl_b64 s[0:1], s[0:1], 3
	s_add_u32 s0, s70, s0
	s_addc_u32 s1, s71, s1
	v_readlane_b32 s6, v255, 60
	v_readlane_b32 s7, v255, 61
	s_nop 4
	s_mov_b32 s0, 25
	s_ashr_i32 s1, s0, 31
	s_lshl_b64 s[0:1], s[0:1], 3
	s_add_u32 s0, s70, s0
	s_addc_u32 s1, s71, s1
	s_mov_b32 s2, 25
	v_readlane_b32 s0, v255, 60
	v_readlane_b32 s1, v255, 61
	s_nop 4
	s_ashr_i32 s3, s2, 31
	s_lshl_b64 s[2:3], s[2:3], 3
	s_add_u32 s2, s70, s2
	s_addc_u32 s3, s71, s3
	v_mov_b32_e32 v3, v224
	v_readlane_b32 s2, v255, 60
	v_readlane_b32 s3, v255, 61
	s_nop 4
	v_mov_b32_e32 v18, 1
	v_bfe_i32 v1, v3, 27, 1
	s_waitcnt vmcnt(10)
	v_lshlrev_b32_e32 v150, 4, v3
	s_nop 0
	v_readfirstlane_b32 s100, v150
	v_lshrrev_b32_e32 v1, 22, v1
	v_add_u32_e32 v1, v150, v1
	v_and_b32_e32 v1, 0xfffffc00, v1
	v_ashrrev_i32_e32 v0, 31, v3
	v_sub_u32_e32 v1, v150, v1
	v_lshrrev_b32_e32 v0, 26, v0
	v_lshrrev_b32_e32 v5, 4, v1
	v_add_u32_e32 v0, v3, v0
	v_bitop3_b32 v5, v5, v1, 32 bitop3:0x6c
	v_ashrrev_i32_e32 v1, 31, v1
	s_waitcnt lgkmcnt(0)
	s_add_u32 s29, s2, 0x3000000
	v_ashrrev_i32_e32 v0, 6, v0
	v_lshrrev_b32_e32 v1, 26, v1
	s_addc_u32 s33, s3, 0
	s_lshl_b32 s8, s24, 8
	v_lshlrev_b32_e32 v6, 3, v0
	v_add_u32_e32 v1, v5, v1
	s_and_b32 s25, s8, 0x3f00
	s_lshl_b32 s8, s24, 2
	v_and_b32_e32 v6, -16, v6
	v_ashrrev_i32_e32 v1, 6, v1
	s_and_b32 s8, s8, 0xffffff00
	v_add_u32_e32 v16, v1, v6
	v_mul_i32_i24_e32 v1, 64, v1
	s_ashr_i32 s9, s8, 31
	v_lshlrev_b32_e32 v0, 5, v0
	v_sub_u32_e32 v1, v5, v1
	s_waitcnt vmcnt(9)
	v_add_u32_e32 v152, 0x2000, v150
	s_lshl_b64 s[12:13], s[8:9], 10
	v_and_b32_e32 v0, 32, v0
	v_ashrrev_i16_sdwa v1, v18, sext(v1) dst_sel:DWORD dst_unused:UNUSED_PAD src0_sel:DWORD src1_sel:BYTE_0
	v_ashrrev_i32_e32 v5, 31, v152
	s_add_u32 s12, s14, s12
	v_add_u32_sdwa v0, v0, sext(v1) dst_sel:DWORD dst_unused:UNUSED_PAD src0_sel:DWORD src1_sel:WORD_0
	v_ashrrev_i32_e32 v17, 31, v16
	v_lshrrev_b32_e32 v5, 22, v5
	s_addc_u32 s13, s15, s13
	v_lshlrev_b64 v[6:7], 10, v[16:17]
	v_ashrrev_i32_e32 v1, 31, v0
	v_add_u32_e32 v5, v152, v5
	v_lshl_add_u64 v[10:11], s[12:13], 0, v[6:7]
	v_lshlrev_b64 v[8:9], 1, v[0:1]
	v_ashrrev_i32_e32 v5, 10, v5
	v_lshl_add_u64 v[14:15], v[10:11], 0, v[8:9]
	v_mul_i32_i24_e32 v10, 0x400, v5
	v_sub_u32_e32 v10, v152, v10
	v_lshrrev_b32_e32 v11, 4, v10
	v_bitop3_b32 v10, v11, v10, 32 bitop3:0x6c
	v_ashrrev_i32_e32 v12, 31, v10
	v_lshrrev_b32_e32 v12, 26, v12
	v_lshlrev_b32_e32 v11, 3, v5
	v_add_u32_e32 v12, v10, v12
	v_and_b32_e32 v11, -16, v11
	v_ashrrev_i32_e32 v13, 6, v12
	v_add_u32_e32 v24, v13, v11
	v_ashrrev_i32_e32 v25, 31, v24
	v_lshrrev_b32_e32 v132, 1, v8
	v_add_u32_e32 v10, 0x10000, v6
	v_mov_b32_e32 v11, v7
	s_waitcnt vmcnt(8)
	s_or_b32 m0, s100, 0x10000
	v_lshl_add_u64 v[18:19], s[12:13], 0, v[10:11]
	global_load_lds_dwordx4 v[14:15], off
	v_mov_b32_e32 v133, v9
	s_or_b32 m0, s100, 0x12000
	s_lshl_b32 s27, s25, 9
	s_lshl_b32 s12, s25, 10
	v_mov_b64_e32 v[12:13], v[8:9]
	s_add_u32 s12, s29, s12
	v_lshl_add_u64 v[18:19], v[18:19], 0, v[12:13]
	s_addc_u32 s13, s33, 0
	global_load_lds_dwordx4 v[18:19], off
	v_lshl_add_u64 v[20:21], s[12:13], 0, v[6:7]
	s_mov_b32 m0, s100
	s_or_b32 s30, s8, 0x80
	v_lshl_add_u64 v[20:21], v[20:21], 0, v[8:9]
	v_lshl_add_u64 v[22:23], s[12:13], 0, v[10:11]
	s_ashr_i32 s31, s30, 31
	global_load_lds_dwordx4 v[20:21], off
	s_or_b32 m0, s100, 0x2000
	s_lshl_b64 s[12:13], s[30:31], 10
	s_add_u32 s12, s14, s12
	s_addc_u32 s13, s15, s13
	v_lshl_add_u64 v[22:23], v[22:23], 0, v[12:13]
	v_lshl_add_u64 v[26:27], s[12:13], 0, v[6:7]
	s_bitset1_b32 s27, 16
	global_load_lds_dwordx4 v[22:23], off
	v_lshl_add_u64 v[26:27], v[26:27], 0, v[8:9]
	s_or_b32 m0, s100, 0x14000
	v_lshl_add_u64 v[28:29], s[12:13], 0, v[10:11]
	s_lshl_b32 s27, s27, 1
	global_load_lds_dwordx4 v[26:27], off
	s_or_b32 m0, s100, 0x16000
	s_add_u32 s12, s29, s27
	s_addc_u32 s13, s33, 0
	v_lshl_add_u64 v[28:29], v[28:29], 0, v[12:13]
	v_lshl_add_u64 v[30:31], s[12:13], 0, v[6:7]
	global_load_lds_dwordx4 v[28:29], off
	v_lshl_add_u64 v[30:31], v[30:31], 0, v[8:9]
	s_or_b32 m0, s100, 0x4000
	s_nop 0
	global_load_lds_dwordx4 v[30:31], off
	v_lshl_add_u64 v[30:31], s[12:13], 0, v[10:11]
	v_lshl_add_u64 v[30:31], v[30:31], 0, v[12:13]
	s_or_b32 m0, s100, 0x6000
	v_ashrrev_i32_e32 v5, 8, v3
	global_load_lds_dwordx4 v[30:31], off
	v_cmp_eq_u32_e32 vcc, 1, v5
	s_and_saveexec_b64 s[12:13], vcc
	s_cbranch_execz .LBB0_1151
	s_barrier
; #define LDA8(dst, b, h) _Pragma("unroll") for (int m = 0; m < 4; ++m) _Pragma("unroll") for (int k = 0; k < 2; ++k) \
;     dst[m][k] = *(const bf16x8*)((const char*)SA8(b, h) + lds_byte8(wr * 64 + m * 16 + fr, k * 32 + fq * 8))
; #define LDB8(dst, b, h) _Pragma("unroll") for (int n = 0; n < 2; ++n) _Pragma("unroll") for (int k = 0; k < 2; ++k) \
;     dst[n][k] = *(const bf16x8*)((const char*)SB8(b, h) + lds_byte8(wc * 32 + n * 16 + fr, k * 32 + fq * 8))
; #define WAIT_V8(n) asm volatile("s_waitcnt vmcnt(" #n ")" ::: "memory")
; #define WAIT_L8(n) asm volatile("s_waitcnt lgkmcnt(" #n ")" ::: "memory")
; #define BAR8 __builtin_amdgcn_s_barrier()
; #define SCHED8 __builtin_amdgcn_sched_barrier(0)
;     ...
;   if (wr == 1) BAR8;
;   WAIT_V8(4); BAR8;
;   STAGE8(SB8(1, 0), Bt, K, bcol, 1); STAGE8(SA8(1, 0), A, lda, brow, 1); STAGE8(SB8(1, 1), Bt, K, bcol + 128, 1);
;   WAIT_V8(6); BAR8;
;   for (int tt = 0; tt < nt - 2; tt += 2) {
;     LDB8(B0, 0, 0); SCHED8; LDA8(At, 0, 0); STAGE8(SA8(1, 1), A, lda, brow + 128, tt + 1);
;     WAIT_L8(8); BAR8; WAIT_L8(0); MMA8(0, 0, At, B0); BAR8; SCHED8;
.LBB0_1151:
	s_or_b64 exec, exec, s[12:13]
	s_lshl_b32 s29, s20, 10
	s_and_b32 s36, s29, 0xfc0000
	s_mov_b64 s[38:39], 0x80
	v_lshl_add_u64 v[14:15], v[14:15], 0, s[38:39]
	s_or_b32 m0, s100, 0x18000
	s_waitcnt vmcnt(4)
	s_barrier
	global_load_lds_dwordx4 v[14:15], off
	v_lshl_add_u64 v[14:15], v[18:19], 0, s[38:39]
	s_or_b32 m0, s100, 0x1a000
	s_nop 0
	global_load_lds_dwordx4 v[14:15], off
	v_lshl_add_u64 v[14:15], v[20:21], 0, s[38:39]
	s_or_b32 m0, s100, 0x8000
	s_nop 0
	global_load_lds_dwordx4 v[14:15], off
	v_lshl_add_u64 v[14:15], v[22:23], 0, s[38:39]
	s_or_b32 m0, s100, 0xa000
	s_nop 0
	global_load_lds_dwordx4 v[14:15], off
	s_or_b32 m0, s100, 0x1c000
	v_lshl_add_u64 v[14:15], v[26:27], 0, s[38:39]
	global_load_lds_dwordx4 v[14:15], off
	v_lshl_add_u64 v[14:15], v[28:29], 0, s[38:39]
	s_or_b32 m0, s100, 0x1e000
	v_and_b32_e32 v147, 15, v3
	global_load_lds_dwordx4 v[14:15], off
	v_bfe_u32 v148, v3, 4, 2
	v_lshlrev_b32_e32 v14, 4, v148
	v_lshlrev_b32_e32 v15, 6, v147
	v_lshlrev_b32_e32 v18, 2, v3
	v_lshlrev_b64 v[136:137], 9, v[16:17]
	v_or_b32_e32 v17, v14, v15
	v_and_b32_e32 v18, 32, v18
	s_mov_b32 s29, 0x10000
	s_and_b32 s12, s21, 0xffffff00
	v_bitop3_b32 v20, v17, s29, v18 bitop3:0xde
	s_mov_b32 s29, 0x14000
	s_ashr_i32 s13, s12, 31
	v_readlane_b32 s40, v254, 35
	v_bitop3_b32 v19, v14, v18, v15 bitop3:0x36
	v_bitop3_b32 v21, v17, s29, v18 bitop3:0xde
	s_mov_b32 s29, 0x18000
	v_lshlrev_b32_e32 v15, 6, v3
	s_lshl_b64 s[12:13], s[12:13], 10
	s_mov_b32 s37, s40
	v_bitop3_b32 v22, v17, s29, v18 bitop3:0xde
	s_mov_b32 s29, 0x1c000
	v_and_b32_e32 v15, 0x3c0, v15
	v_bitop3_b32 v17, v17, s29, v18 bitop3:0xde
	v_bitop3_b32 v18, v15, v18, v14 bitop3:0x36
	v_lshl_add_u64 v[14:15], s[12:13], 0, v[6:7]
	v_lshl_add_u64 v[6:7], s[36:37], 0, v[6:7]
	v_lshl_add_u64 v[14:15], v[14:15], 0, v[8:9]
	v_lshl_add_u64 v[6:7], v[6:7], 0, v[8:9]
	v_bfe_u32 v146, v3, 6, 2
	s_waitcnt vmcnt(6)
	v_lshlrev_b32_e32 v149, 6, v5
	v_lshlrev_b32_e32 v5, 13, v5
	v_lshl_add_u64 v[138:139], s[4:5], 0, v[14:15]
	v_lshl_add_u64 v[14:15], s[12:13], 0, v[10:11]
	v_lshl_add_u64 v[142:143], s[2:3], 0, v[6:7]
	v_lshl_add_u64 v[6:7], s[36:37], 0, v[10:11]
	v_lshlrev_b64 v[134:135], 9, v[24:25]
	v_readlane_b32 s41, v254, 36
	v_readlane_b32 s42, v254, 37
	v_readlane_b32 s43, v254, 38
	v_lshlrev_b32_e32 v16, 12, v146
	v_or_b32_e32 v23, 0x800, v5
	v_or_b32_e32 v24, 0x1000, v5
	v_or_b32_e32 v25, 0x1800, v5
	v_lshl_add_u64 v[14:15], v[14:15], 0, v[12:13]
	v_lshl_add_u64 v[6:7], v[6:7], 0, v[12:13]
	v_lshl_add_u64 v[140:141], s[4:5], 0, v[14:15]
	v_lshl_add_u64 v[144:145], s[2:3], 0, v[6:7]
	s_mov_b32 s29, -2
	s_mov_b64 s[12:13], 0
	v_add_u32_e32 v171, v20, v16
	v_add_u32_e32 v156, v19, v5
	v_add_u32_e32 v155, v18, v23
	v_add_u32_e32 v154, v18, v24
	v_add_u32_e32 v153, v18, v25
	v_add_u32_e32 v167, v21, v16
	v_add_u32_e32 v160, v22, v16
	v_add_u32_e32 v158, v17, v16
	s_mov_b64 s[36:37], 0x3020080
	s_mov_b64 s[38:39], 0xc9a0100
	s_mov_b64 s[40:41], 0x3000100
	s_mov_b64 s[42:43], 0xc9c0100
	s_mov_b64 s[44:45], 0x3020100
	s_mov_b64 s[46:47], 0xc9a0180
	s_mov_b64 s[48:49], 0x3000180
	s_mov_b64 s[50:51], 0xc9c0180
	s_barrier
	ds_read_b128 v[174:177], v171
	ds_read_b128 v[178:181], v171 offset:1024
	ds_read_b128 v[182:185], v171 offset:2048
	ds_read_b128 v[186:189], v171 offset:3072
	v_lshl_add_u64 v[222:223], v[142:143], 0, s[12:13]
	v_lshl_add_u64 v[226:227], v[222:223], 0, s[36:37]
	s_or_b32 m0, s100, 0xc000
	v_lshl_add_u64 v[236:237], v[144:145], 0, s[12:13]
	ds_read_b128 v[190:193], v156
	ds_read_b128 v[194:197], v156 offset:1024
	ds_read_b128 v[198:201], v155
	ds_read_b128 v[202:205], v155 offset:1024
	ds_read_b128 v[206:209], v154
	ds_read_b128 v[210:213], v154 offset:1024
	ds_read_b128 v[214:217], v153
	ds_read_b128 v[218:221], v153 offset:1024
	global_load_lds_dwordx4 v[226:227], off
	s_or_b32 m0, s100, 0xe000
	v_lshl_add_u64 v[226:227], v[236:237], 0, s[36:37]
	global_load_lds_dwordx4 v[226:227], off
	s_waitcnt lgkmcnt(8)
	s_barrier
	s_waitcnt lgkmcnt(0)
	v_mfma_f32_16x16x32_bf16 v[128:131], v[190:193], v[174:177], 0
	v_mfma_f32_16x16x32_bf16 v[124:127], v[190:193], v[182:185], 0
	v_mfma_f32_16x16x32_bf16 v[120:123], v[198:201], v[174:177], 0
	v_mfma_f32_16x16x32_bf16 v[116:119], v[198:201], v[182:185], 0
	v_mfma_f32_16x16x32_bf16 v[112:115], v[206:209], v[174:177], 0
	v_mfma_f32_16x16x32_bf16 v[108:111], v[206:209], v[182:185], 0
	v_mfma_f32_16x16x32_bf16 v[104:107], v[214:217], v[174:177], 0
	v_mfma_f32_16x16x32_bf16 v[100:103], v[214:217], v[182:185], 0
	v_mfma_f32_16x16x32_bf16 v[128:131], v[194:197], v[178:181], v[128:131]
	v_mfma_f32_16x16x32_bf16 v[124:127], v[194:197], v[186:189], v[124:127]
	v_mfma_f32_16x16x32_bf16 v[120:123], v[202:205], v[178:181], v[120:123]
	v_mfma_f32_16x16x32_bf16 v[116:119], v[202:205], v[186:189], v[116:119]
	v_mfma_f32_16x16x32_bf16 v[112:115], v[210:213], v[178:181], v[112:115]
	v_mfma_f32_16x16x32_bf16 v[108:111], v[210:213], v[186:189], v[108:111]
	v_mfma_f32_16x16x32_bf16 v[104:107], v[218:221], v[178:181], v[104:107]
	v_mfma_f32_16x16x32_bf16 v[100:103], v[218:221], v[186:189], v[100:103]
	s_barrier
	v_lshl_add_u64 v[246:247], v[138:139], 0, s[12:13]
	v_lshl_add_u64 v[248:249], v[246:247], 0, s[38:39]
	s_or_b32 m0, s100, 0x10000
	ds_read_b128 v[226:229], v167
	ds_read_b128 v[230:233], v167 offset:1024
	ds_read_b128 v[238:241], v167 offset:2048
	ds_read_b128 v[242:245], v167 offset:3072
	global_load_lds_dwordx4 v[248:249], off
	v_lshl_add_u64 v[248:249], v[140:141], 0, s[12:13]
	s_or_b32 m0, s100, 0x12000
	v_lshl_add_u64 v[250:251], v[248:249], 0, s[38:39]
	global_load_lds_dwordx4 v[250:251], off
	s_barrier
; #define LDA8(dst, b, h) _Pragma("unroll") for (int m = 0; m < 4; ++m) _Pragma("unroll") for (int k = 0; k < 2; ++k) \
;     dst[m][k] = *(const bf16x8*)((const char*)SA8(b, h) + lds_byte8(wr * 64 + m * 16 + fr, k * 32 + fq * 8))
; #define LDB8(dst, b, h) _Pragma("unroll") for (int n = 0; n < 2; ++n) _Pragma("unroll") for (int k = 0; k < 2; ++k) \
;     dst[n][k] = *(const bf16x8*)((const char*)SB8(b, h) + lds_byte8(wc * 32 + n * 16 + fr, k * 32 + fq * 8))
; #define WAIT_V8(n) asm volatile("s_waitcnt vmcnt(" #n ")" ::: "memory")
; #define WAIT_L8(n) asm volatile("s_waitcnt lgkmcnt(" #n ")" ::: "memory")
; #define BAR8 __builtin_amdgcn_s_barrier()
; #define SCHED8 __builtin_amdgcn_sched_barrier(0)
;     ...
;     WAIT_L8(8); BAR8; WAIT_L8(0); MMA8(0, 0, At, B0); BAR8; SCHED8;
;     LDB8(B1, 0, 1); STAGE8(SB8(0, 0), Bt, K, bcol, tt + 2);
;     BAR8; WAIT_L8(0); MMA8(0, 1, At, B1); BAR8;
;     LDA8(At, 0, 1); STAGE8(SA8(0, 0), A, lda, brow, tt + 2);
;     BAR8; WAIT_L8(0); MMA8(1, 0, At, B0); BAR8; SCHED8;
;     STAGE8(SB8(0, 1), Bt, K, bcol + 128, tt + 2);
;     WAIT_V8(6); BAR8; MMA8(1, 1, At, B1); BAR8;
	s_waitcnt lgkmcnt(0)
	v_mfma_f32_16x16x32_bf16 v[96:99], v[190:193], v[226:229], 0
	v_mfma_f32_16x16x32_bf16 v[92:95], v[190:193], v[238:241], 0
	v_mfma_f32_16x16x32_bf16 v[88:91], v[198:201], v[226:229], 0
	v_mfma_f32_16x16x32_bf16 v[84:87], v[198:201], v[238:241], 0
	v_mfma_f32_16x16x32_bf16 v[80:83], v[206:209], v[226:229], 0
	v_mfma_f32_16x16x32_bf16 v[76:79], v[206:209], v[238:241], 0
	v_mfma_f32_16x16x32_bf16 v[72:75], v[214:217], v[226:229], 0
	v_mfma_f32_16x16x32_bf16 v[68:71], v[214:217], v[238:241], 0
	v_mfma_f32_16x16x32_bf16 v[96:99], v[194:197], v[230:233], v[96:99]
	v_mfma_f32_16x16x32_bf16 v[92:95], v[194:197], v[242:245], v[92:95]
	v_mfma_f32_16x16x32_bf16 v[88:91], v[202:205], v[230:233], v[88:91]
	v_mfma_f32_16x16x32_bf16 v[84:87], v[202:205], v[242:245], v[84:87]
	v_mfma_f32_16x16x32_bf16 v[80:83], v[210:213], v[230:233], v[80:83]
	v_mfma_f32_16x16x32_bf16 v[76:79], v[210:213], v[242:245], v[76:79]
	v_mfma_f32_16x16x32_bf16 v[72:75], v[218:221], v[230:233], v[72:75]
	v_mfma_f32_16x16x32_bf16 v[68:71], v[218:221], v[242:245], v[68:71]
	v_lshl_add_u64 v[250:251], v[222:223], 0, s[40:41]
	s_mov_b32 m0, s100
	s_barrier
	ds_read_b128 v[190:193], v156 offset:16384
	ds_read_b128 v[194:197], v156 offset:17408
	ds_read_b128 v[198:201], v155 offset:16384
	ds_read_b128 v[202:205], v155 offset:17408
	ds_read_b128 v[206:209], v154 offset:16384
	ds_read_b128 v[210:213], v154 offset:17408
	ds_read_b128 v[214:217], v153 offset:16384
	ds_read_b128 v[218:221], v153 offset:17408
	global_load_lds_dwordx4 v[250:251], off
	s_or_b32 m0, s100, 0x2000
	v_lshl_add_u64 v[250:251], v[236:237], 0, s[40:41]
	global_load_lds_dwordx4 v[250:251], off
	s_barrier
	s_waitcnt lgkmcnt(0)
	v_mfma_f32_16x16x32_bf16 v[64:67], v[190:193], v[174:177], 0
	v_mfma_f32_16x16x32_bf16 v[60:63], v[190:193], v[182:185], 0
	v_mfma_f32_16x16x32_bf16 v[56:59], v[198:201], v[174:177], 0
	v_mfma_f32_16x16x32_bf16 v[52:55], v[198:201], v[182:185], 0
	v_mfma_f32_16x16x32_bf16 v[48:51], v[206:209], v[174:177], 0
	v_mfma_f32_16x16x32_bf16 v[44:47], v[206:209], v[182:185], 0
	v_mfma_f32_16x16x32_bf16 v[40:43], v[214:217], v[174:177], 0
	v_mfma_f32_16x16x32_bf16 v[36:39], v[214:217], v[182:185], 0
	v_mfma_f32_16x16x32_bf16 v[64:67], v[194:197], v[178:181], v[64:67]
	v_mfma_f32_16x16x32_bf16 v[60:63], v[194:197], v[186:189], v[60:63]
	v_mfma_f32_16x16x32_bf16 v[56:59], v[202:205], v[178:181], v[56:59]
	v_mfma_f32_16x16x32_bf16 v[52:55], v[202:205], v[186:189], v[52:55]
	v_mfma_f32_16x16x32_bf16 v[48:51], v[210:213], v[178:181], v[48:51]
	v_mfma_f32_16x16x32_bf16 v[44:47], v[210:213], v[186:189], v[44:47]
	v_mfma_f32_16x16x32_bf16 v[40:43], v[218:221], v[178:181], v[40:43]
	v_mfma_f32_16x16x32_bf16 v[36:39], v[218:221], v[186:189], v[36:39]
	s_barrier
	s_or_b32 m0, s100, 0x14000
	v_lshl_add_u64 v[174:175], v[246:247], 0, s[42:43]
	global_load_lds_dwordx4 v[174:175], off
	s_or_b32 m0, s100, 0x16000
	v_lshl_add_u64 v[174:175], v[248:249], 0, s[42:43]
	global_load_lds_dwordx4 v[174:175], off
	s_waitcnt vmcnt(6)
	s_barrier
	v_mfma_f32_16x16x32_bf16 v[32:35], v[190:193], v[226:229], 0
	v_mfma_f32_16x16x32_bf16 v[28:31], v[190:193], v[238:241], 0
	v_mfma_f32_16x16x32_bf16 v[24:27], v[198:201], v[226:229], 0
	v_mfma_f32_16x16x32_bf16 v[20:23], v[198:201], v[238:241], 0
	v_mfma_f32_16x16x32_bf16 v[16:19], v[206:209], v[226:229], 0
	v_mfma_f32_16x16x32_bf16 v[12:15], v[206:209], v[238:241], 0
	v_mfma_f32_16x16x32_bf16 v[8:11], v[214:217], v[226:229], 0
	v_mfma_f32_16x16x32_bf16 v[4:7], v[214:217], v[238:241], 0
	v_mfma_f32_16x16x32_bf16 v[32:35], v[194:197], v[230:233], v[32:35]
	v_mfma_f32_16x16x32_bf16 v[28:31], v[194:197], v[242:245], v[28:31]
	v_mfma_f32_16x16x32_bf16 v[24:27], v[202:205], v[230:233], v[24:27]
	v_mfma_f32_16x16x32_bf16 v[20:23], v[202:205], v[242:245], v[20:23]
	v_mfma_f32_16x16x32_bf16 v[16:19], v[210:213], v[230:233], v[16:19]
	v_mfma_f32_16x16x32_bf16 v[12:15], v[210:213], v[242:245], v[12:15]
	v_mfma_f32_16x16x32_bf16 v[8:11], v[218:221], v[230:233], v[8:11]
	v_mfma_f32_16x16x32_bf16 v[4:7], v[218:221], v[242:245], v[4:7]
	s_barrier
	ds_read_b128 v[174:177], v160
	ds_read_b128 v[178:181], v160 offset:1024
	ds_read_b128 v[182:185], v160 offset:2048
	ds_read_b128 v[186:189], v160 offset:3072
	v_lshl_add_u64 v[226:227], v[222:223], 0, s[44:45]
	s_or_b32 m0, s100, 0x4000
	ds_read_b128 v[190:193], v156 offset:32768
	ds_read_b128 v[194:197], v156 offset:33792
	ds_read_b128 v[198:201], v155 offset:32768
	ds_read_b128 v[202:205], v155 offset:33792
	ds_read_b128 v[206:209], v154 offset:32768
	ds_read_b128 v[210:213], v154 offset:33792
	ds_read_b128 v[214:217], v153 offset:32768
	ds_read_b128 v[218:221], v153 offset:33792
	global_load_lds_dwordx4 v[226:227], off
	s_or_b32 m0, s100, 0x6000
	v_lshl_add_u64 v[226:227], v[236:237], 0, s[44:45]
	global_load_lds_dwordx4 v[226:227], off
	s_waitcnt lgkmcnt(8)
	s_barrier
; #define LDA8(dst, b, h) _Pragma("unroll") for (int m = 0; m < 4; ++m) _Pragma("unroll") for (int k = 0; k < 2; ++k) \
;     dst[m][k] = *(const bf16x8*)((const char*)SA8(b, h) + lds_byte8(wr * 64 + m * 16 + fr, k * 32 + fq * 8))
; #define LDB8(dst, b, h) _Pragma("unroll") for (int n = 0; n < 2; ++n) _Pragma("unroll") for (int k = 0; k < 2; ++k) \
;     dst[n][k] = *(const bf16x8*)((const char*)SB8(b, h) + lds_byte8(wc * 32 + n * 16 + fr, k * 32 + fq * 8))
; #define WAIT_V8(n) asm volatile("s_waitcnt vmcnt(" #n ")" ::: "memory")
; #define WAIT_L8(n) asm volatile("s_waitcnt lgkmcnt(" #n ")" ::: "memory")
; #define BAR8 __builtin_amdgcn_s_barrier()
; #define SCHED8 __builtin_amdgcn_sched_barrier(0)
;     ...
;     WAIT_V8(6); BAR8; MMA8(1, 1, At, B1); BAR8;
;     LDB8(B0, 1, 0); SCHED8; LDA8(At, 1, 0); STAGE8(SA8(0, 1), A, lda, brow + 128, tt + 2);
;     WAIT_L8(8); BAR8; WAIT_L8(0); MMA8(0, 0, At, B0); BAR8; SCHED8;
;     LDB8(B1, 1, 1); STAGE8(SB8(1, 0), Bt, K, bcol, tt + 3);
;     BAR8; WAIT_L8(0); MMA8(0, 1, At, B1); BAR8;
;     LDA8(At, 1, 1); STAGE8(SA8(1, 0), A, lda, brow, tt + 3);
;     BAR8; WAIT_L8(0); MMA8(1, 0, At, B0); BAR8; SCHED8;
;     STAGE8(SB8(1, 1), Bt, K, bcol + 128, tt + 3);
;     WAIT_V8(6); BAR8; MMA8(1, 1, At, B1); BAR8;
;   }
	s_waitcnt lgkmcnt(0)
	v_mfma_f32_16x16x32_bf16 v[128:131], v[190:193], v[174:177], v[128:131]
	v_mfma_f32_16x16x32_bf16 v[124:127], v[190:193], v[182:185], v[124:127]
	v_mfma_f32_16x16x32_bf16 v[120:123], v[198:201], v[174:177], v[120:123]
	v_mfma_f32_16x16x32_bf16 v[116:119], v[198:201], v[182:185], v[116:119]
	v_mfma_f32_16x16x32_bf16 v[112:115], v[206:209], v[174:177], v[112:115]
	v_mfma_f32_16x16x32_bf16 v[108:111], v[206:209], v[182:185], v[108:111]
	v_mfma_f32_16x16x32_bf16 v[104:107], v[214:217], v[174:177], v[104:107]
	v_mfma_f32_16x16x32_bf16 v[100:103], v[214:217], v[182:185], v[100:103]
	v_mfma_f32_16x16x32_bf16 v[128:131], v[194:197], v[178:181], v[128:131]
	v_mfma_f32_16x16x32_bf16 v[124:127], v[194:197], v[186:189], v[124:127]
	v_mfma_f32_16x16x32_bf16 v[120:123], v[202:205], v[178:181], v[120:123]
	v_mfma_f32_16x16x32_bf16 v[116:119], v[202:205], v[186:189], v[116:119]
	v_mfma_f32_16x16x32_bf16 v[112:115], v[210:213], v[178:181], v[112:115]
	v_mfma_f32_16x16x32_bf16 v[108:111], v[210:213], v[186:189], v[108:111]
	v_mfma_f32_16x16x32_bf16 v[104:107], v[218:221], v[178:181], v[104:107]
	v_mfma_f32_16x16x32_bf16 v[100:103], v[218:221], v[186:189], v[100:103]
	s_barrier
	v_lshl_add_u64 v[250:251], v[246:247], 0, s[46:47]
	s_or_b32 m0, s100, 0x18000
	ds_read_b128 v[226:229], v158
	ds_read_b128 v[230:233], v158 offset:1024
	ds_read_b128 v[238:241], v158 offset:2048
	ds_read_b128 v[242:245], v158 offset:3072
	global_load_lds_dwordx4 v[250:251], off
	s_or_b32 m0, s100, 0x1a000
	v_lshl_add_u64 v[250:251], v[248:249], 0, s[46:47]
	global_load_lds_dwordx4 v[250:251], off
	s_barrier
	s_waitcnt lgkmcnt(0)
	v_mfma_f32_16x16x32_bf16 v[96:99], v[190:193], v[226:229], v[96:99]
	v_mfma_f32_16x16x32_bf16 v[92:95], v[190:193], v[238:241], v[92:95]
	v_mfma_f32_16x16x32_bf16 v[88:91], v[198:201], v[226:229], v[88:91]
	v_mfma_f32_16x16x32_bf16 v[84:87], v[198:201], v[238:241], v[84:87]
	v_mfma_f32_16x16x32_bf16 v[80:83], v[206:209], v[226:229], v[80:83]
	v_mfma_f32_16x16x32_bf16 v[76:79], v[206:209], v[238:241], v[76:79]
	v_mfma_f32_16x16x32_bf16 v[72:75], v[214:217], v[226:229], v[72:75]
	v_mfma_f32_16x16x32_bf16 v[68:71], v[214:217], v[238:241], v[68:71]
	v_mfma_f32_16x16x32_bf16 v[96:99], v[194:197], v[230:233], v[96:99]
	v_mfma_f32_16x16x32_bf16 v[92:95], v[194:197], v[242:245], v[92:95]
	v_mfma_f32_16x16x32_bf16 v[88:91], v[202:205], v[230:233], v[88:91]
	v_mfma_f32_16x16x32_bf16 v[84:87], v[202:205], v[242:245], v[84:87]
	v_mfma_f32_16x16x32_bf16 v[80:83], v[210:213], v[230:233], v[80:83]
	v_mfma_f32_16x16x32_bf16 v[76:79], v[210:213], v[242:245], v[76:79]
	v_mfma_f32_16x16x32_bf16 v[72:75], v[218:221], v[230:233], v[72:75]
	v_mfma_f32_16x16x32_bf16 v[68:71], v[218:221], v[242:245], v[68:71]
	v_lshl_add_u64 v[222:223], v[222:223], 0, s[48:49]
	s_or_b32 m0, s100, 0x8000
	s_barrier
	ds_read_b128 v[190:193], v156 offset:49152
	ds_read_b128 v[194:197], v156 offset:50176
	ds_read_b128 v[198:201], v155 offset:49152
	ds_read_b128 v[202:205], v155 offset:50176
	ds_read_b128 v[206:209], v154 offset:49152
	ds_read_b128 v[210:213], v154 offset:50176
	ds_read_b128 v[214:217], v153 offset:49152
	ds_read_b128 v[218:221], v153 offset:50176
	global_load_lds_dwordx4 v[222:223], off
	s_or_b32 m0, s100, 0xa000
	v_lshl_add_u64 v[222:223], v[236:237], 0, s[48:49]
	global_load_lds_dwordx4 v[222:223], off
	s_barrier
	s_waitcnt lgkmcnt(0)
	v_mfma_f32_16x16x32_bf16 v[64:67], v[190:193], v[174:177], v[64:67]
	v_mfma_f32_16x16x32_bf16 v[60:63], v[190:193], v[182:185], v[60:63]
	v_mfma_f32_16x16x32_bf16 v[56:59], v[198:201], v[174:177], v[56:59]
	v_mfma_f32_16x16x32_bf16 v[52:55], v[198:201], v[182:185], v[52:55]
	v_mfma_f32_16x16x32_bf16 v[48:51], v[206:209], v[174:177], v[48:51]
	v_mfma_f32_16x16x32_bf16 v[44:47], v[206:209], v[182:185], v[44:47]
	v_mfma_f32_16x16x32_bf16 v[40:43], v[214:217], v[174:177], v[40:43]
	v_mfma_f32_16x16x32_bf16 v[36:39], v[214:217], v[182:185], v[36:39]
	v_mfma_f32_16x16x32_bf16 v[64:67], v[194:197], v[178:181], v[64:67]
	v_mfma_f32_16x16x32_bf16 v[60:63], v[194:197], v[186:189], v[60:63]
	v_mfma_f32_16x16x32_bf16 v[56:59], v[202:205], v[178:181], v[56:59]
	v_mfma_f32_16x16x32_bf16 v[52:55], v[202:205], v[186:189], v[52:55]
	v_mfma_f32_16x16x32_bf16 v[48:51], v[210:213], v[178:181], v[48:51]
	v_mfma_f32_16x16x32_bf16 v[44:47], v[210:213], v[186:189], v[44:47]
	v_mfma_f32_16x16x32_bf16 v[40:43], v[218:221], v[178:181], v[40:43]
	v_mfma_f32_16x16x32_bf16 v[36:39], v[218:221], v[186:189], v[36:39]
	s_barrier
	s_or_b32 m0, s100, 0x1c000
	v_lshl_add_u64 v[174:175], v[246:247], 0, s[50:51]
	global_load_lds_dwordx4 v[174:175], off
	s_or_b32 m0, s100, 0x1e000
	v_lshl_add_u64 v[174:175], v[248:249], 0, s[50:51]
	global_load_lds_dwordx4 v[174:175], off
	s_waitcnt vmcnt(6)
	s_barrier
	v_mfma_f32_16x16x32_bf16 v[32:35], v[190:193], v[226:229], v[32:35]
	v_mfma_f32_16x16x32_bf16 v[28:31], v[190:193], v[238:241], v[28:31]
	v_mfma_f32_16x16x32_bf16 v[24:27], v[198:201], v[226:229], v[24:27]
	v_mfma_f32_16x16x32_bf16 v[20:23], v[198:201], v[238:241], v[20:23]
	v_mfma_f32_16x16x32_bf16 v[16:19], v[206:209], v[226:229], v[16:19]
	v_mfma_f32_16x16x32_bf16 v[12:15], v[206:209], v[238:241], v[12:15]
	v_mfma_f32_16x16x32_bf16 v[8:11], v[214:217], v[226:229], v[8:11]
	v_mfma_f32_16x16x32_bf16 v[4:7], v[214:217], v[238:241], v[4:7]
	v_mfma_f32_16x16x32_bf16 v[32:35], v[194:197], v[230:233], v[32:35]
	v_mfma_f32_16x16x32_bf16 v[28:31], v[194:197], v[242:245], v[28:31]
	v_mfma_f32_16x16x32_bf16 v[24:27], v[202:205], v[230:233], v[24:27]
	v_mfma_f32_16x16x32_bf16 v[20:23], v[202:205], v[242:245], v[20:23]
	v_mfma_f32_16x16x32_bf16 v[16:19], v[210:213], v[230:233], v[16:19]
	v_mfma_f32_16x16x32_bf16 v[12:15], v[210:213], v[242:245], v[12:15]
	v_mfma_f32_16x16x32_bf16 v[8:11], v[218:221], v[230:233], v[8:11]
	v_mfma_f32_16x16x32_bf16 v[4:7], v[218:221], v[242:245], v[4:7]
	s_add_i32 s29, s29, 2
	s_add_u32 s12, s12, 0x100
	s_addc_u32 s13, s13, 0
	s_cmp_lt_u32 s29, 4
	s_cbranch_scc0 .Lpk_exitb_5

; #define BAR8 __builtin_amdgcn_s_barrier()
;     ...
;   const int brow = m0, bcol = n0;
;   const int wid = t >> 6, lane = t & 63, wr = wid >> 2, wc = wid & 3, fr = lane & 15, fq = lane >> 4;
;   f32x4 acc[2][2][4][2];
;   {
;     float zinit = 0.f;
;     asm volatile("" : "+v"(zinit));
; #pragma unroll
;     for (int a = 0; a < 2; ++a)
; #pragma unroll
;       for (int b = 0; b < 2; ++b)
; #pragma unroll
;         for (int m = 0; m < 4; ++m)
; #pragma unroll
;           for (int n = 0; n < 2; ++n)
; #pragma unroll
;             for (int j = 0; j < 4; ++j) acc[a][b][m][n][j] = zinit;
;   }
;   bf16x8 At[4][2], B0[2][2], B1[2][2];
;   const int nt = K / 64;
;   if (!pre) {
;     STAGE8(SB8(0, 0), Bt, K, bcol, 0); STAGE8(SA8(0, 0), A, lda, brow, 0);
;     STAGE8(SB8(0, 1), Bt, K, bcol + 128, 0); STAGE8(SA8(0, 1), A, lda, brow + 128, 0);
;   }
;   if (wr == 1) BAR8;
.LBB0_1253:
	s_and_b64 vcc, exec, s[0:1]
	s_cbranch_vccz .LBB0_1266
	s_mov_b32 s0, 25
	s_ashr_i32 s1, s0, 31
	s_xor_b64 s[8:9], s[8:9], -1
	s_lshl_b64 s[0:1], s[0:1], 3
	s_add_u32 s0, s70, s0
	s_addc_u32 s1, s71, s1
	v_readlane_b32 s2, v255, 60
	v_readlane_b32 s3, v255, 61
	s_nop 4
	s_lshl_b32 s0, s25, 8
	v_mov_b32_e32 v3, v224
	s_and_b32 s27, s0, 0x3f00
	s_lshl_b32 s0, s25, 2
	s_and_b32 s0, s0, 0xffffff00
	s_waitcnt vmcnt(10)
	v_lshlrev_b32_e32 v150, 4, v3
	s_nop 0
	v_readfirstlane_b32 s100, v150
	v_ashrrev_i32_e32 v0, 31, v3
	v_bfe_i32 v5, v3, 27, 1
	s_andn2_b64 vcc, exec, s[8:9]
	v_lshrrev_b32_e32 v1, 26, v0
	v_lshrrev_b32_e32 v0, 22, v5
	s_waitcnt vmcnt(9)
	v_add_u32_e32 v152, 0x2000, v150
	s_waitcnt vmcnt(8)
	s_cbranch_vccnz .LBB0_1256
	v_add_u32_e32 v6, v150, v0
	v_and_b32_e32 v6, 0xfffffc00, v6
	v_sub_u32_e32 v6, v150, v6
	v_lshrrev_b32_e32 v7, 4, v6
	v_add_u32_e32 v5, v3, v1
	v_bitop3_b32 v7, v7, v6, 32 bitop3:0x6c
	v_ashrrev_i32_e32 v6, 31, v6
	v_ashrrev_i32_e32 v5, 6, v5
	v_lshrrev_b32_e32 v6, 26, v6
	v_lshlrev_b32_e32 v8, 3, v5
	v_add_u32_e32 v6, v7, v6
	v_and_b32_e32 v8, -16, v8
	v_ashrrev_i32_e32 v9, 6, v6
	v_add_u32_e32 v6, v9, v8
	v_mul_i32_i24_e32 v8, 64, v9
	s_ashr_i32 s1, s0, 31
	v_lshlrev_b32_e32 v5, 5, v5
	v_sub_u32_e32 v7, v7, v8
	v_mov_b32_e32 v14, 1
	s_lshl_b64 s[8:9], s[0:1], 11
	v_and_b32_e32 v5, 32, v5
	v_ashrrev_i16_sdwa v7, v14, sext(v7) dst_sel:DWORD dst_unused:UNUSED_PAD src0_sel:DWORD src1_sel:BYTE_0
	s_add_u32 s8, s4, s8
	v_add_u32_sdwa v8, v5, sext(v7) dst_sel:DWORD dst_unused:UNUSED_PAD src0_sel:DWORD src1_sel:WORD_0
	v_ashrrev_i32_e32 v7, 31, v6
	s_addc_u32 s9, s5, s9
	v_lshlrev_b64 v[6:7], 11, v[6:7]
	v_ashrrev_i32_e32 v9, 31, v8
	v_lshl_add_u64 v[10:11], s[8:9], 0, v[6:7]
	v_lshlrev_b64 v[8:9], 1, v[8:9]
	v_lshl_add_u64 v[10:11], v[10:11], 0, v[8:9]
	s_or_b32 m0, s100, 0x10000
	s_nop 0
	global_load_lds_dwordx4 v[10:11], off
	v_add_u32_e32 v10, 0x20000, v6
	v_mov_b32_e32 v11, v7
	s_or_b32 m0, s100, 0x12000
	s_lshl_b32 s1, s27, 11
	v_lshl_add_u64 v[14:15], s[8:9], 0, v[10:11]
	v_mov_b64_e32 v[12:13], v[8:9]
	s_waitcnt lgkmcnt(0)
	s_add_u32 s8, s2, s1
	v_lshl_add_u64 v[14:15], v[14:15], 0, v[12:13]
	s_addc_u32 s9, s3, 0
	s_or_b32 s14, s0, 0x80
	global_load_lds_dwordx4 v[14:15], off
	v_lshl_add_u64 v[14:15], s[8:9], 0, v[6:7]
	s_ashr_i32 s15, s14, 31
	v_lshl_add_u64 v[14:15], v[14:15], 0, v[8:9]
	s_mov_b32 m0, s100
	s_lshl_b64 s[14:15], s[14:15], 11
	global_load_lds_dwordx4 v[14:15], off
	v_lshl_add_u64 v[14:15], s[8:9], 0, v[10:11]
	s_add_u32 s14, s4, s14
	v_lshl_add_u64 v[14:15], v[14:15], 0, v[12:13]
	s_addc_u32 s15, s5, s15
	s_or_b32 m0, s100, 0x2000
	s_nop 0
	global_load_lds_dwordx4 v[14:15], off
	v_lshl_add_u64 v[14:15], s[14:15], 0, v[6:7]
	v_lshl_add_u64 v[14:15], v[14:15], 0, v[8:9]
	s_or_b32 m0, s100, 0x14000
	s_add_u32 s8, s8, 0x40000
	global_load_lds_dwordx4 v[14:15], off
	v_lshl_add_u64 v[14:15], s[14:15], 0, v[10:11]
	s_addc_u32 s9, s9, 0
	v_lshl_add_u64 v[14:15], v[14:15], 0, v[12:13]
	s_or_b32 m0, s100, 0x16000
	v_lshl_add_u64 v[6:7], s[8:9], 0, v[6:7]
	global_load_lds_dwordx4 v[14:15], off
	s_or_b32 m0, s100, 0x4000
	v_lshl_add_u64 v[6:7], v[6:7], 0, v[8:9]
	global_load_lds_dwordx4 v[6:7], off
	v_lshl_add_u64 v[6:7], s[8:9], 0, v[10:11]
	s_or_b32 m0, s100, 0x6000
	v_lshl_add_u64 v[6:7], v[6:7], 0, v[12:13]
	global_load_lds_dwordx4 v[6:7], off

; #define LDA8(dst, b, h) _Pragma("unroll") for (int m = 0; m < 4; ++m) _Pragma("unroll") for (int k = 0; k < 2; ++k) \
;     dst[m][k] = *(const bf16x8*)((const char*)SA8(b, h) + lds_byte8(wr * 64 + m * 16 + fr, k * 32 + fq * 8))
; #define LDB8(dst, b, h) _Pragma("unroll") for (int n = 0; n < 2; ++n) _Pragma("unroll") for (int k = 0; k < 2; ++k) \
;     dst[n][k] = *(const bf16x8*)((const char*)SB8(b, h) + lds_byte8(wc * 32 + n * 16 + fr, k * 32 + fq * 8))
; #define WAIT_V8(n) asm volatile("s_waitcnt vmcnt(" #n ")" ::: "memory")
; #define WAIT_L8(n) asm volatile("s_waitcnt lgkmcnt(" #n ")" ::: "memory")
; #define BAR8 __builtin_amdgcn_s_barrier()
; #define SCHED8 __builtin_amdgcn_sched_barrier(0)
;     ...
;   if (wr == 1) BAR8;
;   WAIT_V8(4); BAR8;
;   STAGE8(SB8(1, 0), Bt, K, bcol, 1); STAGE8(SA8(1, 0), A, lda, brow, 1); STAGE8(SB8(1, 1), Bt, K, bcol + 128, 1);
;   WAIT_V8(6); BAR8;
;   for (int tt = 0; tt < nt - 2; tt += 2) {
;     LDB8(B0, 0, 0); SCHED8; LDA8(At, 0, 0); STAGE8(SA8(1, 1), A, lda, brow + 128, tt + 1);
;     WAIT_L8(8); BAR8; WAIT_L8(0); MMA8(0, 0, At, B0); BAR8; SCHED8;
.LBB0_1258:
	s_or_b64 exec, exec, s[8:9]
	v_add_u32_e32 v0, v150, v0
	v_and_b32_e32 v0, 0xfffffc00, v0
	v_sub_u32_e32 v0, v150, v0
	v_lshrrev_b32_e32 v6, 4, v0
	v_add_u32_e32 v1, v3, v1
	v_bitop3_b32 v7, v6, v0, 32 bitop3:0x6c
	v_ashrrev_i32_e32 v0, 31, v0
	v_ashrrev_i32_e32 v1, 6, v1
	v_lshrrev_b32_e32 v0, 26, v0
	v_lshlrev_b32_e32 v6, 3, v1
	v_add_u32_e32 v0, v7, v0
	v_and_b32_e32 v6, -16, v6
	v_ashrrev_i32_e32 v0, 6, v0
	s_and_b32 s1, s12, 63
	s_and_b32 s8, s20, 0xffffff00
	v_add_u32_e32 v6, v0, v6
	v_mul_i32_i24_e32 v0, 64, v0
	s_lshl_b32 s12, s1, 19
	s_ashr_i32 s9, s8, 31
	s_ashr_i32 s1, s0, 31
	v_lshlrev_b32_e32 v1, 5, v1
	v_sub_u32_e32 v0, v7, v0
	v_mov_b32_e32 v13, 1
	s_lshl_b64 s[14:15], s[8:9], 11
	s_lshl_b64 s[8:9], s[0:1], 11
	v_and_b32_e32 v1, 32, v1
	v_ashrrev_i16_sdwa v0, v13, sext(v0) dst_sel:DWORD dst_unused:UNUSED_PAD src0_sel:DWORD src1_sel:BYTE_0
	s_add_u32 s8, s4, s8
	v_add_u32_sdwa v0, v1, sext(v0) dst_sel:DWORD dst_unused:UNUSED_PAD src0_sel:DWORD src1_sel:WORD_0
	v_ashrrev_i32_e32 v7, 31, v6
	v_readlane_b32 s40, v254, 35
	s_addc_u32 s9, s5, s9
	v_lshlrev_b64 v[132:133], 11, v[6:7]
	v_ashrrev_i32_e32 v1, 31, v0
	v_readlane_b32 s41, v254, 36
	v_lshl_add_u64 v[6:7], s[8:9], 0, v[132:133]
	v_lshlrev_b64 v[8:9], 1, v[0:1]
	s_mov_b32 s13, s40
	v_lshl_add_u64 v[6:7], v[6:7], 0, v[8:9]
	s_mov_b64 s[40:41], 0x80
	v_lshl_add_u64 v[6:7], v[6:7], 0, s[40:41]
	s_or_b32 m0, s100, 0x18000
	s_waitcnt vmcnt(4)
	s_barrier
	global_load_lds_dwordx4 v[6:7], off
	v_ashrrev_i32_e32 v6, 31, v152
	v_lshrrev_b32_e32 v6, 22, v6
	v_add_u32_e32 v6, v152, v6
	v_ashrrev_i32_e32 v7, 10, v6
	v_mul_i32_i24_e32 v6, 0x400, v7
	v_sub_u32_e32 v6, v152, v6
	v_lshrrev_b32_e32 v10, 4, v6
	v_bitop3_b32 v10, v10, v6, 32 bitop3:0x6c
	v_ashrrev_i32_e32 v11, 31, v10
	v_lshrrev_b32_e32 v11, 26, v11
	v_add_u32_e32 v11, v10, v11
	v_lshlrev_b32_e32 v6, 3, v7
	v_ashrrev_i32_e32 v12, 6, v11
	v_and_b32_e32 v11, 0xc0, v11
	v_and_b32_e32 v6, -16, v6
	v_lshlrev_b32_e32 v7, 5, v7
	v_sub_u32_e32 v10, v10, v11
	v_add_u32_e32 v6, v12, v6
	v_and_b32_e32 v7, 32, v7
	v_ashrrev_i16_sdwa v10, v13, sext(v10) dst_sel:DWORD dst_unused:UNUSED_PAD src0_sel:DWORD src1_sel:BYTE_0
	v_add_u32_sdwa v134, v7, sext(v10) dst_sel:DWORD dst_unused:UNUSED_PAD src0_sel:DWORD src1_sel:WORD_0
	v_ashrrev_i32_e32 v7, 31, v6
	v_lshlrev_b64 v[136:137], 11, v[6:7]
	v_ashrrev_i32_e32 v135, 31, v134
	v_lshl_add_u64 v[6:7], s[8:9], 0, v[136:137]
	v_lshlrev_b64 v[10:11], 1, v[134:135]
	s_or_b32 m0, s100, 0x1a000
	s_lshl_b32 s1, s27, 11
	v_lshl_add_u64 v[6:7], v[6:7], 0, v[10:11]
	s_waitcnt lgkmcnt(0)
	s_add_u32 s8, s2, s1
	v_lshl_add_u64 v[6:7], v[6:7], 0, s[40:41]
	s_addc_u32 s9, s3, 0
	global_load_lds_dwordx4 v[6:7], off
	v_lshl_add_u64 v[6:7], s[8:9], 0, v[132:133]
	v_lshl_add_u64 v[6:7], v[6:7], 0, v[8:9]
	s_or_b32 s36, s0, 0x80
	v_lshl_add_u64 v[6:7], v[6:7], 0, s[40:41]
	s_or_b32 m0, s100, 0x8000
	s_ashr_i32 s37, s36, 31
	global_load_lds_dwordx4 v[6:7], off
	v_lshl_add_u64 v[6:7], s[8:9], 0, v[136:137]
	s_lshl_b64 s[36:37], s[36:37], 11
	v_lshl_add_u64 v[6:7], v[6:7], 0, v[10:11]
	s_add_u32 s36, s4, s36
	v_lshl_add_u64 v[6:7], v[6:7], 0, s[40:41]
	s_addc_u32 s37, s5, s37
	s_or_b32 m0, s100, 0xa000
	s_nop 0
	global_load_lds_dwordx4 v[6:7], off
	v_lshl_add_u64 v[6:7], s[36:37], 0, v[132:133]
	v_lshl_add_u64 v[6:7], v[6:7], 0, v[8:9]
	v_lshl_add_u64 v[6:7], v[6:7], 0, s[40:41]
	s_or_b32 m0, s100, 0x1c000
	s_nop 0
	global_load_lds_dwordx4 v[6:7], off
	v_lshl_add_u64 v[6:7], s[36:37], 0, v[136:137]
	v_lshl_add_u64 v[6:7], v[6:7], 0, v[10:11]
	v_lshl_add_u64 v[6:7], v[6:7], 0, s[40:41]
	s_or_b32 m0, s100, 0x1e000
	v_and_b32_e32 v147, 15, v3
	global_load_lds_dwordx4 v[6:7], off
	v_bfe_u32 v148, v3, 4, 2
	v_lshlrev_b32_e32 v6, 4, v148
	v_lshlrev_b32_e32 v7, 6, v147
	v_lshlrev_b32_e32 v14, 2, v3
	v_or_b32_e32 v13, v6, v7
	v_and_b32_e32 v14, 32, v14
	s_mov_b32 s1, 0x10000
	v_bitop3_b32 v16, v13, s1, v14 bitop3:0xde
	s_mov_b32 s1, 0x14000
	v_bitop3_b32 v15, v6, v14, v7 bitop3:0x36
	v_bitop3_b32 v17, v13, s1, v14 bitop3:0xde
	s_mov_b32 s1, 0x18000
	v_lshlrev_b32_e32 v7, 6, v3
	v_bitop3_b32 v18, v13, s1, v14 bitop3:0xde
	s_mov_b32 s1, 0x1c000
	v_and_b32_e32 v7, 0x3c0, v7
	v_bitop3_b32 v13, v13, s1, v14 bitop3:0xde
	v_bitop3_b32 v14, v7, v14, v6 bitop3:0x36
	v_lshl_add_u64 v[6:7], s[12:13], 0, v[132:133]
	v_lshl_add_u64 v[6:7], v[6:7], 0, v[8:9]
	v_lshl_add_u64 v[138:139], s[2:3], 0, v[6:7]
	v_lshl_add_u64 v[6:7], s[12:13], 0, v[136:137]
	v_lshl_add_u64 v[6:7], v[6:7], 0, v[10:11]
	v_lshl_add_u64 v[140:141], s[2:3], 0, v[6:7]
	v_lshl_add_u64 v[6:7], s[14:15], 0, v[132:133]
	v_lshl_add_u64 v[6:7], v[6:7], 0, v[8:9]
	v_bfe_u32 v146, v3, 6, 2
	s_waitcnt vmcnt(6)
	v_lshlrev_b32_e32 v149, 6, v5
	v_lshlrev_b32_e32 v5, 13, v5
	v_lshl_add_u64 v[142:143], s[6:7], 0, v[6:7]
	v_lshl_add_u64 v[6:7], s[14:15], 0, v[136:137]
	v_readlane_b32 s42, v254, 37
	v_readlane_b32 s43, v254, 38
	v_lshlrev_b32_e32 v12, 12, v146
	v_or_b32_e32 v19, 0x800, v5
	v_or_b32_e32 v20, 0x1000, v5
	v_or_b32_e32 v21, 0x1800, v5
	v_lshl_add_u64 v[6:7], v[6:7], 0, v[10:11]
	v_lshl_add_u64 v[144:145], s[6:7], 0, v[6:7]
	s_mov_b32 s1, -2
	s_mov_b64 s[12:13], 0
	v_add_u32_e32 v171, v16, v12
	v_add_u32_e32 v161, v15, v5
	v_add_u32_e32 v160, v14, v19
	v_add_u32_e32 v159, v14, v20
	v_add_u32_e32 v158, v14, v21
	v_add_u32_e32 v169, v17, v12
	v_add_u32_e32 v163, v18, v12
	v_add_u32_e32 v162, v13, v12
	s_mov_b64 s[36:37], 0xcaa0100
	s_mov_b64 s[40:41], 0xcae0100
	s_mov_b64 s[42:43], 0xcaa0180
	s_mov_b64 s[44:45], 0xcae0180
	s_barrier
; #define LDA8(dst, b, h) _Pragma("unroll") for (int m = 0; m < 4; ++m) _Pragma("unroll") for (int k = 0; k < 2; ++k) \
;     dst[m][k] = *(const bf16x8*)((const char*)SA8(b, h) + lds_byte8(wr * 64 + m * 16 + fr, k * 32 + fq * 8))
; #define LDB8(dst, b, h) _Pragma("unroll") for (int n = 0; n < 2; ++n) _Pragma("unroll") for (int k = 0; k < 2; ++k) \
;     dst[n][k] = *(const bf16x8*)((const char*)SB8(b, h) + lds_byte8(wc * 32 + n * 16 + fr, k * 32 + fq * 8))
; #define WAIT_L8(n) asm volatile("s_waitcnt lgkmcnt(" #n ")" ::: "memory")
; #define BAR8 __builtin_amdgcn_s_barrier()
; #define SCHED8 __builtin_amdgcn_sched_barrier(0)
;     ...
;   for (int tt = 0; tt < nt - 2; tt += 2) {
;     LDB8(B0, 0, 0); SCHED8; LDA8(At, 0, 0); STAGE8(SA8(1, 1), A, lda, brow + 128, tt + 1);
;     WAIT_L8(8); BAR8; WAIT_L8(0); MMA8(0, 0, At, B0); BAR8; SCHED8;
;     LDB8(B1, 0, 1); STAGE8(SB8(0, 0), Bt, K, bcol, tt + 2);
;     BAR8; WAIT_L8(0); MMA8(0, 1, At, B1); BAR8;
;     LDA8(At, 0, 1); STAGE8(SA8(0, 0), A, lda, brow, tt + 2);
;     BAR8; WAIT_L8(0); MMA8(1, 0, At, B0); BAR8; SCHED8;
	ds_read_b128 v[174:177], v171
	ds_read_b128 v[178:181], v171 offset:1024
	ds_read_b128 v[182:185], v171 offset:2048
	ds_read_b128 v[186:189], v171 offset:3072
	v_lshl_add_u64 v[222:223], v[138:139], 0, s[12:13]
	v_lshl_add_u64 v[226:227], v[222:223], 0, s[34:35]
	s_or_b32 m0, s100, 0xc000
	v_lshl_add_u64 v[236:237], v[140:141], 0, s[12:13]
	ds_read_b128 v[190:193], v161
	ds_read_b128 v[194:197], v161 offset:1024
	ds_read_b128 v[198:201], v160
	ds_read_b128 v[202:205], v160 offset:1024
	ds_read_b128 v[206:209], v159
	ds_read_b128 v[210:213], v159 offset:1024
	ds_read_b128 v[214:217], v158
	ds_read_b128 v[218:221], v158 offset:1024
	global_load_lds_dwordx4 v[226:227], off
	s_or_b32 m0, s100, 0xe000
	v_lshl_add_u64 v[226:227], v[236:237], 0, s[34:35]
	global_load_lds_dwordx4 v[226:227], off
	s_waitcnt lgkmcnt(8)
	s_barrier
	s_waitcnt lgkmcnt(0)
	v_mfma_f32_16x16x32_f16 v[128:131], v[190:193], v[174:177], 0
	v_mfma_f32_16x16x32_f16 v[124:127], v[190:193], v[182:185], 0
	v_mfma_f32_16x16x32_f16 v[120:123], v[198:201], v[174:177], 0
	v_mfma_f32_16x16x32_f16 v[116:119], v[198:201], v[182:185], 0
	v_mfma_f32_16x16x32_f16 v[112:115], v[206:209], v[174:177], 0
	v_mfma_f32_16x16x32_f16 v[108:111], v[206:209], v[182:185], 0
	v_mfma_f32_16x16x32_f16 v[104:107], v[214:217], v[174:177], 0
	v_mfma_f32_16x16x32_f16 v[100:103], v[214:217], v[182:185], 0
	v_mfma_f32_16x16x32_f16 v[128:131], v[194:197], v[178:181], v[128:131]
	v_mfma_f32_16x16x32_f16 v[124:127], v[194:197], v[186:189], v[124:127]
	v_mfma_f32_16x16x32_f16 v[120:123], v[202:205], v[178:181], v[120:123]
	v_mfma_f32_16x16x32_f16 v[116:119], v[202:205], v[186:189], v[116:119]
	v_mfma_f32_16x16x32_f16 v[112:115], v[210:213], v[178:181], v[112:115]
	v_mfma_f32_16x16x32_f16 v[108:111], v[210:213], v[186:189], v[108:111]
	v_mfma_f32_16x16x32_f16 v[104:107], v[218:221], v[178:181], v[104:107]
	v_mfma_f32_16x16x32_f16 v[100:103], v[218:221], v[186:189], v[100:103]
	s_barrier
	v_lshl_add_u64 v[246:247], v[142:143], 0, s[12:13]
	v_lshl_add_u64 v[248:249], v[246:247], 0, s[36:37]
	s_or_b32 m0, s100, 0x10000
	ds_read_b128 v[226:229], v169
	ds_read_b128 v[230:233], v169 offset:1024
	ds_read_b128 v[238:241], v169 offset:2048
	ds_read_b128 v[242:245], v169 offset:3072
	global_load_lds_dwordx4 v[248:249], off
	v_lshl_add_u64 v[248:249], v[144:145], 0, s[12:13]
	s_or_b32 m0, s100, 0x12000
	v_lshl_add_u64 v[250:251], v[248:249], 0, s[36:37]
	global_load_lds_dwordx4 v[250:251], off
	s_barrier
	s_waitcnt lgkmcnt(0)
	v_mfma_f32_16x16x32_f16 v[96:99], v[190:193], v[226:229], 0
	v_mfma_f32_16x16x32_f16 v[92:95], v[190:193], v[238:241], 0
	v_mfma_f32_16x16x32_f16 v[88:91], v[198:201], v[226:229], 0
	v_mfma_f32_16x16x32_f16 v[84:87], v[198:201], v[238:241], 0
	v_mfma_f32_16x16x32_f16 v[80:83], v[206:209], v[226:229], 0
	v_mfma_f32_16x16x32_f16 v[76:79], v[206:209], v[238:241], 0
	v_mfma_f32_16x16x32_f16 v[72:75], v[214:217], v[226:229], 0
	v_mfma_f32_16x16x32_f16 v[68:71], v[214:217], v[238:241], 0
	v_mfma_f32_16x16x32_f16 v[96:99], v[194:197], v[230:233], v[96:99]
	v_mfma_f32_16x16x32_f16 v[92:95], v[194:197], v[242:245], v[92:95]
	v_mfma_f32_16x16x32_f16 v[88:91], v[202:205], v[230:233], v[88:91]
	v_mfma_f32_16x16x32_f16 v[84:87], v[202:205], v[242:245], v[84:87]
	v_mfma_f32_16x16x32_f16 v[80:83], v[210:213], v[230:233], v[80:83]
	v_mfma_f32_16x16x32_f16 v[76:79], v[210:213], v[242:245], v[76:79]
	v_mfma_f32_16x16x32_f16 v[72:75], v[218:221], v[230:233], v[72:75]
	v_mfma_f32_16x16x32_f16 v[68:71], v[218:221], v[242:245], v[68:71]
	v_lshl_add_u64 v[250:251], v[222:223], 0, s[10:11]
	s_mov_b32 m0, s100
	s_barrier
	ds_read_b128 v[190:193], v161 offset:16384
	ds_read_b128 v[194:197], v161 offset:17408
	ds_read_b128 v[198:201], v160 offset:16384
	ds_read_b128 v[202:205], v160 offset:17408
	ds_read_b128 v[206:209], v159 offset:16384
	ds_read_b128 v[210:213], v159 offset:17408
	ds_read_b128 v[214:217], v158 offset:16384
	ds_read_b128 v[218:221], v158 offset:17408
	global_load_lds_dwordx4 v[250:251], off
	s_or_b32 m0, s100, 0x2000
	v_lshl_add_u64 v[250:251], v[236:237], 0, s[10:11]
	global_load_lds_dwordx4 v[250:251], off
	s_barrier
	s_waitcnt lgkmcnt(0)
	v_mfma_f32_16x16x32_f16 v[64:67], v[190:193], v[174:177], 0
	v_mfma_f32_16x16x32_f16 v[60:63], v[190:193], v[182:185], 0
	v_mfma_f32_16x16x32_f16 v[56:59], v[198:201], v[174:177], 0
	v_mfma_f32_16x16x32_f16 v[52:55], v[198:201], v[182:185], 0
	v_mfma_f32_16x16x32_f16 v[48:51], v[206:209], v[174:177], 0
	v_mfma_f32_16x16x32_f16 v[44:47], v[206:209], v[182:185], 0
	v_mfma_f32_16x16x32_f16 v[40:43], v[214:217], v[174:177], 0
	v_mfma_f32_16x16x32_f16 v[36:39], v[214:217], v[182:185], 0
	v_mfma_f32_16x16x32_f16 v[64:67], v[194:197], v[178:181], v[64:67]
	v_mfma_f32_16x16x32_f16 v[60:63], v[194:197], v[186:189], v[60:63]
	v_mfma_f32_16x16x32_f16 v[56:59], v[202:205], v[178:181], v[56:59]
	v_mfma_f32_16x16x32_f16 v[52:55], v[202:205], v[186:189], v[52:55]
	v_mfma_f32_16x16x32_f16 v[48:51], v[210:213], v[178:181], v[48:51]
	v_mfma_f32_16x16x32_f16 v[44:47], v[210:213], v[186:189], v[44:47]
	v_mfma_f32_16x16x32_f16 v[40:43], v[218:221], v[178:181], v[40:43]
	v_mfma_f32_16x16x32_f16 v[36:39], v[218:221], v[186:189], v[36:39]
	s_barrier
	s_or_b32 m0, s100, 0x14000
	v_lshl_add_u64 v[174:175], v[246:247], 0, s[40:41]
	global_load_lds_dwordx4 v[174:175], off
	s_or_b32 m0, s100, 0x16000
	v_lshl_add_u64 v[174:175], v[248:249], 0, s[40:41]
	global_load_lds_dwordx4 v[174:175], off
	s_waitcnt vmcnt(6)
	s_barrier
; #define LDA8(dst, b, h) _Pragma("unroll") for (int m = 0; m < 4; ++m) _Pragma("unroll") for (int k = 0; k < 2; ++k) \
;     dst[m][k] = *(const bf16x8*)((const char*)SA8(b, h) + lds_byte8(wr * 64 + m * 16 + fr, k * 32 + fq * 8))
; #define LDB8(dst, b, h) _Pragma("unroll") for (int n = 0; n < 2; ++n) _Pragma("unroll") for (int k = 0; k < 2; ++k) \
;     dst[n][k] = *(const bf16x8*)((const char*)SB8(b, h) + lds_byte8(wc * 32 + n * 16 + fr, k * 32 + fq * 8))
; #define WAIT_V8(n) asm volatile("s_waitcnt vmcnt(" #n ")" ::: "memory")
; #define WAIT_L8(n) asm volatile("s_waitcnt lgkmcnt(" #n ")" ::: "memory")
; #define BAR8 __builtin_amdgcn_s_barrier()
; #define SCHED8 __builtin_amdgcn_sched_barrier(0)
;     ...
;     BAR8; WAIT_L8(0); MMA8(1, 0, At, B0); BAR8; SCHED8;
;     STAGE8(SB8(0, 1), Bt, K, bcol + 128, tt + 2);
;     WAIT_V8(6); BAR8; MMA8(1, 1, At, B1); BAR8;
;     LDB8(B0, 1, 0); SCHED8; LDA8(At, 1, 0); STAGE8(SA8(0, 1), A, lda, brow + 128, tt + 2);
;     WAIT_L8(8); BAR8; WAIT_L8(0); MMA8(0, 0, At, B0); BAR8; SCHED8;
	v_mfma_f32_16x16x32_f16 v[32:35], v[190:193], v[226:229], 0
	v_mfma_f32_16x16x32_f16 v[28:31], v[190:193], v[238:241], 0
	v_mfma_f32_16x16x32_f16 v[24:27], v[198:201], v[226:229], 0
	v_mfma_f32_16x16x32_f16 v[20:23], v[198:201], v[238:241], 0
	v_mfma_f32_16x16x32_f16 v[16:19], v[206:209], v[226:229], 0
	v_mfma_f32_16x16x32_f16 v[12:15], v[206:209], v[238:241], 0
	v_mfma_f32_16x16x32_f16 v[8:11], v[214:217], v[226:229], 0
	v_mfma_f32_16x16x32_f16 v[4:7], v[214:217], v[238:241], 0
	v_mfma_f32_16x16x32_f16 v[32:35], v[194:197], v[230:233], v[32:35]
	v_mfma_f32_16x16x32_f16 v[28:31], v[194:197], v[242:245], v[28:31]
	v_mfma_f32_16x16x32_f16 v[24:27], v[202:205], v[230:233], v[24:27]
	v_mfma_f32_16x16x32_f16 v[20:23], v[202:205], v[242:245], v[20:23]
	v_mfma_f32_16x16x32_f16 v[16:19], v[210:213], v[230:233], v[16:19]
	v_mfma_f32_16x16x32_f16 v[12:15], v[210:213], v[242:245], v[12:15]
	v_mfma_f32_16x16x32_f16 v[8:11], v[218:221], v[230:233], v[8:11]
	v_mfma_f32_16x16x32_f16 v[4:7], v[218:221], v[242:245], v[4:7]
	s_barrier
	ds_read_b128 v[174:177], v163
	ds_read_b128 v[178:181], v163 offset:1024
	ds_read_b128 v[182:185], v163 offset:2048
	ds_read_b128 v[186:189], v163 offset:3072
	v_lshl_add_u64 v[226:227], v[222:223], 0, s[18:19]
	s_or_b32 m0, s100, 0x4000
	ds_read_b128 v[190:193], v161 offset:32768
	ds_read_b128 v[194:197], v161 offset:33792
	ds_read_b128 v[198:201], v160 offset:32768
	ds_read_b128 v[202:205], v160 offset:33792
	ds_read_b128 v[206:209], v159 offset:32768
	ds_read_b128 v[210:213], v159 offset:33792
	ds_read_b128 v[214:217], v158 offset:32768
	ds_read_b128 v[218:221], v158 offset:33792
	global_load_lds_dwordx4 v[226:227], off
	s_or_b32 m0, s100, 0x6000
	v_lshl_add_u64 v[226:227], v[236:237], 0, s[18:19]
	global_load_lds_dwordx4 v[226:227], off
	s_waitcnt lgkmcnt(8)
	s_barrier
	s_waitcnt lgkmcnt(0)
	v_mfma_f32_16x16x32_f16 v[128:131], v[190:193], v[174:177], v[128:131]
	v_mfma_f32_16x16x32_f16 v[124:127], v[190:193], v[182:185], v[124:127]
	v_mfma_f32_16x16x32_f16 v[120:123], v[198:201], v[174:177], v[120:123]
	v_mfma_f32_16x16x32_f16 v[116:119], v[198:201], v[182:185], v[116:119]
	v_mfma_f32_16x16x32_f16 v[112:115], v[206:209], v[174:177], v[112:115]
	v_mfma_f32_16x16x32_f16 v[108:111], v[206:209], v[182:185], v[108:111]
	v_mfma_f32_16x16x32_f16 v[104:107], v[214:217], v[174:177], v[104:107]
	v_mfma_f32_16x16x32_f16 v[100:103], v[214:217], v[182:185], v[100:103]
	v_mfma_f32_16x16x32_f16 v[128:131], v[194:197], v[178:181], v[128:131]
	v_mfma_f32_16x16x32_f16 v[124:127], v[194:197], v[186:189], v[124:127]
	v_mfma_f32_16x16x32_f16 v[120:123], v[202:205], v[178:181], v[120:123]
	v_mfma_f32_16x16x32_f16 v[116:119], v[202:205], v[186:189], v[116:119]
	v_mfma_f32_16x16x32_f16 v[112:115], v[210:213], v[178:181], v[112:115]
	v_mfma_f32_16x16x32_f16 v[108:111], v[210:213], v[186:189], v[108:111]
	v_mfma_f32_16x16x32_f16 v[104:107], v[218:221], v[178:181], v[104:107]
	v_mfma_f32_16x16x32_f16 v[100:103], v[218:221], v[186:189], v[100:103]
	s_barrier
	v_lshl_add_u64 v[250:251], v[246:247], 0, s[42:43]
	s_or_b32 m0, s100, 0x18000
	ds_read_b128 v[226:229], v162
	ds_read_b128 v[230:233], v162 offset:1024
	ds_read_b128 v[238:241], v162 offset:2048
	ds_read_b128 v[242:245], v162 offset:3072
	global_load_lds_dwordx4 v[250:251], off
	s_or_b32 m0, s100, 0x1a000
	v_lshl_add_u64 v[250:251], v[248:249], 0, s[42:43]
	global_load_lds_dwordx4 v[250:251], off
	s_barrier
; #define LDA8(dst, b, h) _Pragma("unroll") for (int m = 0; m < 4; ++m) _Pragma("unroll") for (int k = 0; k < 2; ++k) \
;     dst[m][k] = *(const bf16x8*)((const char*)SA8(b, h) + lds_byte8(wr * 64 + m * 16 + fr, k * 32 + fq * 8))
; #define LDB8(dst, b, h) _Pragma("unroll") for (int n = 0; n < 2; ++n) _Pragma("unroll") for (int k = 0; k < 2; ++k) \
;     dst[n][k] = *(const bf16x8*)((const char*)SB8(b, h) + lds_byte8(wc * 32 + n * 16 + fr, k * 32 + fq * 8))
; #define WAIT_V8(n) asm volatile("s_waitcnt vmcnt(" #n ")" ::: "memory")
; #define WAIT_L8(n) asm volatile("s_waitcnt lgkmcnt(" #n ")" ::: "memory")
; #define BAR8 __builtin_amdgcn_s_barrier()
; #define SCHED8 __builtin_amdgcn_sched_barrier(0)
;     ...
;     WAIT_L8(8); BAR8; WAIT_L8(0); MMA8(0, 0, At, B0); BAR8; SCHED8;
;     LDB8(B1, 1, 1); STAGE8(SB8(1, 0), Bt, K, bcol, tt + 3);
;     BAR8; WAIT_L8(0); MMA8(0, 1, At, B1); BAR8;
;     LDA8(At, 1, 1); STAGE8(SA8(1, 0), A, lda, brow, tt + 3);
;     BAR8; WAIT_L8(0); MMA8(1, 0, At, B0); BAR8; SCHED8;
;     STAGE8(SB8(1, 1), Bt, K, bcol + 128, tt + 3);
;     WAIT_V8(6); BAR8; MMA8(1, 1, At, B1); BAR8;
;   }
	s_waitcnt lgkmcnt(0)
	v_mfma_f32_16x16x32_f16 v[96:99], v[190:193], v[226:229], v[96:99]
	v_mfma_f32_16x16x32_f16 v[92:95], v[190:193], v[238:241], v[92:95]
	v_mfma_f32_16x16x32_f16 v[88:91], v[198:201], v[226:229], v[88:91]
	v_mfma_f32_16x16x32_f16 v[84:87], v[198:201], v[238:241], v[84:87]
	v_mfma_f32_16x16x32_f16 v[80:83], v[206:209], v[226:229], v[80:83]
	v_mfma_f32_16x16x32_f16 v[76:79], v[206:209], v[238:241], v[76:79]
	v_mfma_f32_16x16x32_f16 v[72:75], v[214:217], v[226:229], v[72:75]
	v_mfma_f32_16x16x32_f16 v[68:71], v[214:217], v[238:241], v[68:71]
	v_mfma_f32_16x16x32_f16 v[96:99], v[194:197], v[230:233], v[96:99]
	v_mfma_f32_16x16x32_f16 v[92:95], v[194:197], v[242:245], v[92:95]
	v_mfma_f32_16x16x32_f16 v[88:91], v[202:205], v[230:233], v[88:91]
	v_mfma_f32_16x16x32_f16 v[84:87], v[202:205], v[242:245], v[84:87]
	v_mfma_f32_16x16x32_f16 v[80:83], v[210:213], v[230:233], v[80:83]
	v_mfma_f32_16x16x32_f16 v[76:79], v[210:213], v[242:245], v[76:79]
	v_mfma_f32_16x16x32_f16 v[72:75], v[218:221], v[230:233], v[72:75]
	v_mfma_f32_16x16x32_f16 v[68:71], v[218:221], v[242:245], v[68:71]
	v_lshl_add_u64 v[222:223], v[222:223], 0, s[22:23]
	s_or_b32 m0, s100, 0x8000
	s_barrier
	ds_read_b128 v[190:193], v161 offset:49152
	ds_read_b128 v[194:197], v161 offset:50176
	ds_read_b128 v[198:201], v160 offset:49152
	ds_read_b128 v[202:205], v160 offset:50176
	ds_read_b128 v[206:209], v159 offset:49152
	ds_read_b128 v[210:213], v159 offset:50176
	ds_read_b128 v[214:217], v158 offset:49152
	ds_read_b128 v[218:221], v158 offset:50176
	global_load_lds_dwordx4 v[222:223], off
	s_or_b32 m0, s100, 0xa000
	v_lshl_add_u64 v[222:223], v[236:237], 0, s[22:23]
	global_load_lds_dwordx4 v[222:223], off
	s_barrier
	s_waitcnt lgkmcnt(0)
	v_mfma_f32_16x16x32_f16 v[64:67], v[190:193], v[174:177], v[64:67]
	v_mfma_f32_16x16x32_f16 v[60:63], v[190:193], v[182:185], v[60:63]
	v_mfma_f32_16x16x32_f16 v[56:59], v[198:201], v[174:177], v[56:59]
	v_mfma_f32_16x16x32_f16 v[52:55], v[198:201], v[182:185], v[52:55]
	v_mfma_f32_16x16x32_f16 v[48:51], v[206:209], v[174:177], v[48:51]
	v_mfma_f32_16x16x32_f16 v[44:47], v[206:209], v[182:185], v[44:47]
	v_mfma_f32_16x16x32_f16 v[40:43], v[214:217], v[174:177], v[40:43]
	v_mfma_f32_16x16x32_f16 v[36:39], v[214:217], v[182:185], v[36:39]
	v_mfma_f32_16x16x32_f16 v[64:67], v[194:197], v[178:181], v[64:67]
	v_mfma_f32_16x16x32_f16 v[60:63], v[194:197], v[186:189], v[60:63]
	v_mfma_f32_16x16x32_f16 v[56:59], v[202:205], v[178:181], v[56:59]
	v_mfma_f32_16x16x32_f16 v[52:55], v[202:205], v[186:189], v[52:55]
	v_mfma_f32_16x16x32_f16 v[48:51], v[210:213], v[178:181], v[48:51]
	v_mfma_f32_16x16x32_f16 v[44:47], v[210:213], v[186:189], v[44:47]
	v_mfma_f32_16x16x32_f16 v[40:43], v[218:221], v[178:181], v[40:43]
	v_mfma_f32_16x16x32_f16 v[36:39], v[218:221], v[186:189], v[36:39]
	s_barrier
	s_or_b32 m0, s100, 0x1c000
	v_lshl_add_u64 v[174:175], v[246:247], 0, s[44:45]
	global_load_lds_dwordx4 v[174:175], off
	s_or_b32 m0, s100, 0x1e000
	v_lshl_add_u64 v[174:175], v[248:249], 0, s[44:45]
	global_load_lds_dwordx4 v[174:175], off
	s_waitcnt vmcnt(6)
	s_barrier
	v_mfma_f32_16x16x32_f16 v[32:35], v[190:193], v[226:229], v[32:35]
	v_mfma_f32_16x16x32_f16 v[28:31], v[190:193], v[238:241], v[28:31]
	v_mfma_f32_16x16x32_f16 v[24:27], v[198:201], v[226:229], v[24:27]
	v_mfma_f32_16x16x32_f16 v[20:23], v[198:201], v[238:241], v[20:23]
	v_mfma_f32_16x16x32_f16 v[16:19], v[206:209], v[226:229], v[16:19]
	v_mfma_f32_16x16x32_f16 v[12:15], v[206:209], v[238:241], v[12:15]
	v_mfma_f32_16x16x32_f16 v[8:11], v[214:217], v[226:229], v[8:11]
	v_mfma_f32_16x16x32_f16 v[4:7], v[214:217], v[238:241], v[4:7]
	v_mfma_f32_16x16x32_f16 v[32:35], v[194:197], v[230:233], v[32:35]
	v_mfma_f32_16x16x32_f16 v[28:31], v[194:197], v[242:245], v[28:31]
	v_mfma_f32_16x16x32_f16 v[24:27], v[202:205], v[230:233], v[24:27]
	v_mfma_f32_16x16x32_f16 v[20:23], v[202:205], v[242:245], v[20:23]
	v_mfma_f32_16x16x32_f16 v[16:19], v[210:213], v[230:233], v[16:19]
	v_mfma_f32_16x16x32_f16 v[12:15], v[210:213], v[242:245], v[12:15]
	v_mfma_f32_16x16x32_f16 v[8:11], v[218:221], v[230:233], v[8:11]
	v_mfma_f32_16x16x32_f16 v[4:7], v[218:221], v[242:245], v[4:7]
	s_add_i32 s1, s1, 2
	s_add_u32 s12, s12, 0x100
	s_addc_u32 s13, s13, 0
	s_cmp_lt_u32 s1, 12
	s_cbranch_scc0 .Lpk_exitb_6

; #define BAR8 __builtin_amdgcn_s_barrier()
;     ...
;   const int brow = m0, bcol = n0;
;   const int wid = t >> 6, lane = t & 63, wr = wid >> 2, wc = wid & 3, fr = lane & 15, fq = lane >> 4;
;   f32x4 acc[2][2][4][2];
;   {
;     float zinit = 0.f;
;     asm volatile("" : "+v"(zinit));
; #pragma unroll
;     for (int a = 0; a < 2; ++a)
; #pragma unroll
;       for (int b = 0; b < 2; ++b)
; #pragma unroll
;         for (int m = 0; m < 4; ++m)
; #pragma unroll
;           for (int n = 0; n < 2; ++n)
; #pragma unroll
;             for (int j = 0; j < 4; ++j) acc[a][b][m][n][j] = zinit;
;   }
;   bf16x8 At[4][2], B0[2][2], B1[2][2];
;   const int nt = K / 64;
;   if (!pre) {
;     STAGE8(SB8(0, 0), Bt, K, bcol, 0); STAGE8(SA8(0, 0), A, lda, brow, 0);
;     STAGE8(SB8(0, 1), Bt, K, bcol + 128, 0); STAGE8(SA8(0, 1), A, lda, brow + 128, 0);
;   }
;   if (wr == 1) BAR8;
.LBB0_1322:
	s_mov_b32 s0, 24
	s_mov_b32 s0, 25
	s_ashr_i32 s1, s0, 31
	s_lshl_b64 s[0:1], s[0:1], 3
	s_add_u32 s0, s70, s0
	s_addc_u32 s1, s71, s1
	v_readlane_b32 s6, v255, 60
	v_readlane_b32 s7, v255, 61
	s_nop 4
	s_mov_b32 s0, 25
	s_ashr_i32 s1, s0, 31
	s_lshl_b64 s[0:1], s[0:1], 3
	s_add_u32 s0, s70, s0
	s_addc_u32 s1, s71, s1
	s_mov_b32 s2, 25
	v_readlane_b32 s0, v255, 60
	v_readlane_b32 s1, v255, 61
	s_nop 4
	s_ashr_i32 s3, s2, 31
	s_lshl_b64 s[2:3], s[2:3], 3
	s_add_u32 s2, s70, s2
	s_addc_u32 s3, s71, s3
	v_mov_b32_e32 v3, v224
	v_readlane_b32 s2, v255, 60
	v_readlane_b32 s3, v255, 61
	s_nop 4
	s_lshl_b32 s8, s24, 8
	v_bfe_i32 v1, v3, 27, 1
	s_waitcnt vmcnt(10)
	v_lshlrev_b32_e32 v150, 4, v3
	s_nop 0
	v_readfirstlane_b32 s100, v150
	v_lshrrev_b32_e32 v1, 22, v1
	v_add_u32_e32 v1, v150, v1
	v_and_b32_e32 v1, 0xfffffc00, v1
	v_ashrrev_i32_e32 v0, 31, v3
	v_sub_u32_e32 v1, v150, v1
	v_lshrrev_b32_e32 v0, 26, v0
	v_lshrrev_b32_e32 v5, 4, v1
	v_add_u32_e32 v0, v3, v0
	v_bitop3_b32 v6, v5, v1, 32 bitop3:0x6c
	v_ashrrev_i32_e32 v1, 31, v1
	v_ashrrev_i32_e32 v0, 6, v0
	v_lshrrev_b32_e32 v1, 26, v1
	v_lshlrev_b32_e32 v5, 3, v0
	v_add_u32_e32 v1, v6, v1
	v_and_b32_e32 v5, -16, v5
	v_ashrrev_i32_e32 v1, 6, v1
	s_and_b32 s25, s8, 0x3f00
	s_lshl_b32 s8, s24, 2
	v_add_u32_e32 v5, v1, v5
	v_mul_i32_i24_e32 v1, 64, v1
	s_and_b32 s8, s8, 0xffffff00
	v_lshlrev_b32_e32 v0, 5, v0
	v_sub_u32_e32 v1, v6, v1
	v_mov_b32_e32 v15, 1
	s_mul_i32 s12, s8, 0x1600
	v_and_b32_e32 v0, 32, v0
	v_ashrrev_i16_sdwa v1, v15, sext(v1) dst_sel:DWORD dst_unused:UNUSED_PAD src0_sel:DWORD src1_sel:BYTE_0
	s_movk_i32 s27, 0xb00
	s_mul_hi_i32 s9, s8, 0x1600
	s_add_u32 s12, s14, s12
	v_add_u32_sdwa v0, v0, sext(v1) dst_sel:DWORD dst_unused:UNUSED_PAD src0_sel:DWORD src1_sel:WORD_0
	v_mad_i64_i32 v[132:133], s[30:31], v5, s27, 0
	s_addc_u32 s13, s15, s9
	v_lshlrev_b64 v[24:25], 1, v[132:133]
	v_ashrrev_i32_e32 v1, 31, v0
	v_lshl_add_u64 v[8:9], s[12:13], 0, v[24:25]
	v_lshlrev_b64 v[6:7], 1, v[0:1]
	s_waitcnt vmcnt(9)
	v_add_u32_e32 v152, 0x2000, v150
	v_lshl_add_u64 v[10:11], v[8:9], 0, v[6:7]
	v_ashrrev_i32_e32 v8, 31, v152
	v_lshrrev_b32_e32 v8, 22, v8
	v_add_u32_e32 v8, v152, v8
	v_ashrrev_i32_e32 v8, 10, v8
	v_mul_i32_i24_e32 v9, 0x400, v8
	v_sub_u32_e32 v9, v152, v9
	v_lshrrev_b32_e32 v12, 4, v9
	v_bitop3_b32 v9, v12, v9, 32 bitop3:0x6c
	v_ashrrev_i32_e32 v13, 31, v9
	v_lshrrev_b32_e32 v13, 26, v13
	v_lshlrev_b32_e32 v12, 3, v8
	v_add_u32_e32 v13, v9, v13
	s_waitcnt vmcnt(8)
	s_or_b32 m0, s100, 0x10000
	v_and_b32_e32 v12, -16, v12
	v_ashrrev_i32_e32 v14, 6, v13
	global_load_lds_dwordx4 v[10:11], off
	v_add_u32_e32 v22, v14, v12
	v_and_b32_e32 v12, 0xc0, v13
	s_or_b32 m0, s100, 0x12000
	s_mul_i32 s9, s25, 0xb00
	v_lshlrev_b32_e32 v8, 5, v8
	v_sub_u32_e32 v9, v9, v12
	v_mad_i64_i32 v[136:137], s[30:31], v22, s27, 0
	s_lshl_b32 s27, s9, 1
	v_and_b32_e32 v8, 32, v8
	v_ashrrev_i16_sdwa v9, v15, sext(v9) dst_sel:DWORD dst_unused:UNUSED_PAD src0_sel:DWORD src1_sel:BYTE_0
	s_waitcnt lgkmcnt(0)
	s_add_u32 s9, s2, s27
	v_add_u32_sdwa v134, v8, sext(v9) dst_sel:DWORD dst_unused:UNUSED_PAD src0_sel:DWORD src1_sel:WORD_0
	v_lshlrev_b64 v[26:27], 1, v[136:137]
	s_addc_u32 s29, s3, 0
	v_lshl_add_u64 v[12:13], s[12:13], 0, v[26:27]
	v_ashrrev_i32_e32 v135, 31, v134
	s_add_u32 s12, s9, 0x2000000
	v_lshlrev_b64 v[8:9], 1, v[134:135]
	s_addc_u32 s13, s29, 0
	v_lshl_add_u64 v[12:13], v[12:13], 0, v[8:9]
	v_lshl_add_u64 v[14:15], s[12:13], 0, v[24:25]
	global_load_lds_dwordx4 v[12:13], off
	v_lshl_add_u64 v[14:15], v[14:15], 0, v[6:7]
	s_mov_b32 m0, s100
	v_lshl_add_u64 v[16:17], s[12:13], 0, v[26:27]
	s_or_b32 s30, s8, 0x80
	global_load_lds_dwordx4 v[14:15], off
	s_or_b32 m0, s100, 0x2000
	s_mul_i32 s12, s30, 0x1600
	s_mul_hi_i32 s13, s30, 0x1600
	s_add_u32 s12, s14, s12
	s_addc_u32 s13, s15, s13
	v_lshl_add_u64 v[16:17], v[16:17], 0, v[8:9]
	v_lshl_add_u64 v[18:19], s[12:13], 0, v[24:25]
	global_load_lds_dwordx4 v[16:17], off
	v_lshl_add_u64 v[18:19], v[18:19], 0, v[6:7]
	s_or_b32 m0, s100, 0x14000
	v_lshl_add_u64 v[20:21], s[12:13], 0, v[26:27]
	global_load_lds_dwordx4 v[18:19], off
	s_or_b32 m0, s100, 0x16000
	s_add_u32 s12, s9, 0x20b0000
	s_addc_u32 s13, s29, 0
	v_lshl_add_u64 v[20:21], v[20:21], 0, v[8:9]
	v_lshl_add_u64 v[24:25], s[12:13], 0, v[24:25]
	global_load_lds_dwordx4 v[20:21], off
	v_lshl_add_u64 v[24:25], v[24:25], 0, v[6:7]
	s_or_b32 m0, s100, 0x4000
	s_nop 0
	global_load_lds_dwordx4 v[24:25], off
	v_lshl_add_u64 v[24:25], s[12:13], 0, v[26:27]
	v_lshl_add_u64 v[24:25], v[24:25], 0, v[8:9]
	s_or_b32 m0, s100, 0x6000
	v_ashrrev_i32_e32 v23, 8, v3
	global_load_lds_dwordx4 v[24:25], off
	v_cmp_eq_u32_e32 vcc, 1, v23
	s_and_saveexec_b64 s[12:13], vcc
	s_cbranch_execz .LBB0_1324
	s_barrier
; #define LDA8(dst, b, h) _Pragma("unroll") for (int m = 0; m < 4; ++m) _Pragma("unroll") for (int k = 0; k < 2; ++k) \
;     dst[m][k] = *(const bf16x8*)((const char*)SA8(b, h) + lds_byte8(wr * 64 + m * 16 + fr, k * 32 + fq * 8))
; #define LDB8(dst, b, h) _Pragma("unroll") for (int n = 0; n < 2; ++n) _Pragma("unroll") for (int k = 0; k < 2; ++k) \
;     dst[n][k] = *(const bf16x8*)((const char*)SB8(b, h) + lds_byte8(wc * 32 + n * 16 + fr, k * 32 + fq * 8))
; #define WAIT_V8(n) asm volatile("s_waitcnt vmcnt(" #n ")" ::: "memory")
; #define WAIT_L8(n) asm volatile("s_waitcnt lgkmcnt(" #n ")" ::: "memory")
; #define BAR8 __builtin_amdgcn_s_barrier()
; #define SCHED8 __builtin_amdgcn_sched_barrier(0)
;     ...
;   if (wr == 1) BAR8;
;   WAIT_V8(4); BAR8;
;   STAGE8(SB8(1, 0), Bt, K, bcol, 1); STAGE8(SA8(1, 0), A, lda, brow, 1); STAGE8(SB8(1, 1), Bt, K, bcol + 128, 1);
;   WAIT_V8(6); BAR8;
;   for (int tt = 0; tt < nt - 2; tt += 2) {
;     LDB8(B0, 0, 0); SCHED8; LDA8(At, 0, 0); STAGE8(SA8(1, 1), A, lda, brow + 128, tt + 1);
;     WAIT_L8(8); BAR8; WAIT_L8(0); MMA8(0, 0, At, B0); BAR8; SCHED8;
.LBB0_1324:
	s_or_b64 exec, exec, s[12:13]
	s_mov_b64 s[36:37], 0x80
	v_lshl_add_u64 v[10:11], v[10:11], 0, s[36:37]
	s_or_b32 m0, s100, 0x18000
	s_waitcnt vmcnt(4)
	s_barrier
	global_load_lds_dwordx4 v[10:11], off
	v_lshl_add_u64 v[10:11], v[12:13], 0, s[36:37]
	s_or_b32 m0, s100, 0x1a000
	s_nop 0
	global_load_lds_dwordx4 v[10:11], off
	v_lshl_add_u64 v[10:11], v[14:15], 0, s[36:37]
	s_or_b32 m0, s100, 0x8000
	s_nop 0
	global_load_lds_dwordx4 v[10:11], off
	v_lshl_add_u64 v[10:11], v[16:17], 0, s[36:37]
	s_or_b32 m0, s100, 0xa000
	s_nop 0
	global_load_lds_dwordx4 v[10:11], off
	s_or_b32 m0, s100, 0x1c000
	v_lshl_add_u64 v[10:11], v[18:19], 0, s[36:37]
	global_load_lds_dwordx4 v[10:11], off
	v_lshl_add_u64 v[10:11], v[20:21], 0, s[36:37]
	s_or_b32 m0, s100, 0x1e000
	v_and_b32_e32 v147, 15, v3
	global_load_lds_dwordx4 v[10:11], off
	v_bfe_u32 v148, v3, 4, 2
	v_lshlrev_b32_e32 v10, 4, v148
	v_lshlrev_b32_e32 v11, 6, v147
	v_lshlrev_b32_e32 v13, 2, v3
	v_or_b32_e32 v12, v10, v11
	v_and_b32_e32 v13, 32, v13
	s_mov_b32 s12, 0x10000
	v_bitop3_b32 v18, v12, s12, v13 bitop3:0xde
	s_mov_b32 s12, 0x14000
	v_bitop3_b32 v17, v10, v13, v11 bitop3:0x36
	v_bitop3_b32 v19, v12, s12, v13 bitop3:0xde
	s_mov_b32 s12, 0x18000
	v_lshlrev_b32_e32 v11, 6, v3
	v_bitop3_b32 v20, v12, s12, v13 bitop3:0xde
	s_mov_b32 s12, 0x1c000
	v_and_b32_e32 v11, 0x3c0, v11
	s_movk_i32 s31, 0x1600
	s_and_b32 s29, s21, 0xffffff00
	v_bitop3_b32 v21, v12, s12, v13 bitop3:0xde
	v_bitop3_b32 v24, v11, v13, v10 bitop3:0x36
	v_mad_i64_i32 v[10:11], s[12:13], v5, s31, 0
	v_mov_b32_e32 v5, 0x1600
	v_mad_i64_i32 v[12:13], s[12:13], s29, v5, v[10:11]
	v_lshl_add_u64 v[12:13], v[12:13], 0, v[6:7]
	v_lshl_add_u64 v[138:139], s[4:5], 0, v[12:13]
	v_mad_i64_i32 v[12:13], s[12:13], v22, s31, 0
	v_mad_i64_i32 v[14:15], s[12:13], s29, v5, v[12:13]
	s_bfe_u32 s29, s20, 0x60008
	v_mov_b32_e32 v5, 0x160000
	v_mad_u64_u32 v[10:11], s[12:13], s29, v5, v[10:11]
	v_lshl_add_u64 v[6:7], v[10:11], 0, v[6:7]
	v_bfe_u32 v146, v3, 6, 2
	s_waitcnt vmcnt(6)
	v_lshlrev_b32_e32 v149, 6, v23
	v_lshlrev_b32_e32 v23, 13, v23
	v_lshl_add_u64 v[142:143], s[2:3], 0, v[6:7]
	v_mad_u64_u32 v[6:7], s[12:13], s29, v5, v[12:13]
	v_lshlrev_b32_e32 v16, 12, v146
	v_or_b32_e32 v25, 0x800, v23
	v_or_b32_e32 v26, 0x1000, v23
	v_or_b32_e32 v27, 0x1800, v23
	v_lshl_add_u64 v[14:15], v[14:15], 0, v[8:9]
	v_lshl_add_u64 v[6:7], v[6:7], 0, v[8:9]
	s_ashr_i32 s9, s8, 31
	v_lshl_add_u64 v[140:141], s[4:5], 0, v[14:15]
	v_lshl_add_u64 v[144:145], s[2:3], 0, v[6:7]
	s_mov_b32 s29, -2
	s_mov_b64 s[12:13], 0
	v_add_u32_e32 v171, v18, v16
	v_add_u32_e32 v156, v17, v23
	v_add_u32_e32 v155, v24, v25
	v_add_u32_e32 v154, v24, v26
	v_add_u32_e32 v153, v24, v27
	v_add_u32_e32 v169, v19, v16
	v_add_u32_e32 v159, v20, v16
	v_add_u32_e32 v158, v21, v16
	s_mov_b64 s[36:37], 0x20b0080
	s_mov_b64 s[38:39], 0xd5a0100
	s_mov_b64 s[40:41], 0x2000100
	s_mov_b64 s[42:43], 0xd650100
	s_mov_b64 s[44:45], 0x20b0100
	s_mov_b64 s[46:47], 0xd5a0180
	s_mov_b64 s[48:49], 0x2000180
	s_mov_b64 s[50:51], 0xd650180
	s_barrier
	ds_read_b128 v[174:177], v171
	ds_read_b128 v[178:181], v171 offset:1024
	ds_read_b128 v[182:185], v171 offset:2048
	ds_read_b128 v[186:189], v171 offset:3072
	v_lshl_add_u64 v[222:223], v[142:143], 0, s[12:13]
	v_lshl_add_u64 v[226:227], v[222:223], 0, s[36:37]
	s_or_b32 m0, s100, 0xc000
	v_lshl_add_u64 v[236:237], v[144:145], 0, s[12:13]
	ds_read_b128 v[190:193], v156
	ds_read_b128 v[194:197], v156 offset:1024
	ds_read_b128 v[198:201], v155
	ds_read_b128 v[202:205], v155 offset:1024
	ds_read_b128 v[206:209], v154
	ds_read_b128 v[210:213], v154 offset:1024
	ds_read_b128 v[214:217], v153
	ds_read_b128 v[218:221], v153 offset:1024
	global_load_lds_dwordx4 v[226:227], off
	s_or_b32 m0, s100, 0xe000
	v_lshl_add_u64 v[226:227], v[236:237], 0, s[36:37]
	global_load_lds_dwordx4 v[226:227], off
	s_waitcnt lgkmcnt(8)
	s_barrier
	s_waitcnt lgkmcnt(0)
	v_mfma_f32_16x16x32_bf16 v[128:131], v[190:193], v[174:177], 0
	v_mfma_f32_16x16x32_bf16 v[124:127], v[190:193], v[182:185], 0
	v_mfma_f32_16x16x32_bf16 v[120:123], v[198:201], v[174:177], 0
	v_mfma_f32_16x16x32_bf16 v[116:119], v[198:201], v[182:185], 0
	v_mfma_f32_16x16x32_bf16 v[112:115], v[206:209], v[174:177], 0
	v_mfma_f32_16x16x32_bf16 v[108:111], v[206:209], v[182:185], 0
	v_mfma_f32_16x16x32_bf16 v[104:107], v[214:217], v[174:177], 0
	v_mfma_f32_16x16x32_bf16 v[100:103], v[214:217], v[182:185], 0
	v_mfma_f32_16x16x32_bf16 v[128:131], v[194:197], v[178:181], v[128:131]
	v_mfma_f32_16x16x32_bf16 v[124:127], v[194:197], v[186:189], v[124:127]
	v_mfma_f32_16x16x32_bf16 v[120:123], v[202:205], v[178:181], v[120:123]
	v_mfma_f32_16x16x32_bf16 v[116:119], v[202:205], v[186:189], v[116:119]
	v_mfma_f32_16x16x32_bf16 v[112:115], v[210:213], v[178:181], v[112:115]
	v_mfma_f32_16x16x32_bf16 v[108:111], v[210:213], v[186:189], v[108:111]
	v_mfma_f32_16x16x32_bf16 v[104:107], v[218:221], v[178:181], v[104:107]
	v_mfma_f32_16x16x32_bf16 v[100:103], v[218:221], v[186:189], v[100:103]
	s_barrier
	v_lshl_add_u64 v[246:247], v[138:139], 0, s[12:13]
	v_lshl_add_u64 v[248:249], v[246:247], 0, s[38:39]
	s_or_b32 m0, s100, 0x10000
	ds_read_b128 v[226:229], v169
	ds_read_b128 v[230:233], v169 offset:1024
	ds_read_b128 v[238:241], v169 offset:2048
	ds_read_b128 v[242:245], v169 offset:3072
	global_load_lds_dwordx4 v[248:249], off
	v_lshl_add_u64 v[248:249], v[140:141], 0, s[12:13]
	s_or_b32 m0, s100, 0x12000
	v_lshl_add_u64 v[250:251], v[248:249], 0, s[38:39]
	global_load_lds_dwordx4 v[250:251], off
	s_barrier
; #define LDA8(dst, b, h) _Pragma("unroll") for (int m = 0; m < 4; ++m) _Pragma("unroll") for (int k = 0; k < 2; ++k) \
;     dst[m][k] = *(const bf16x8*)((const char*)SA8(b, h) + lds_byte8(wr * 64 + m * 16 + fr, k * 32 + fq * 8))
; #define LDB8(dst, b, h) _Pragma("unroll") for (int n = 0; n < 2; ++n) _Pragma("unroll") for (int k = 0; k < 2; ++k) \
;     dst[n][k] = *(const bf16x8*)((const char*)SB8(b, h) + lds_byte8(wc * 32 + n * 16 + fr, k * 32 + fq * 8))
; #define WAIT_V8(n) asm volatile("s_waitcnt vmcnt(" #n ")" ::: "memory")
; #define WAIT_L8(n) asm volatile("s_waitcnt lgkmcnt(" #n ")" ::: "memory")
; #define BAR8 __builtin_amdgcn_s_barrier()
; #define SCHED8 __builtin_amdgcn_sched_barrier(0)
;     ...
;     WAIT_L8(8); BAR8; WAIT_L8(0); MMA8(0, 0, At, B0); BAR8; SCHED8;
;     LDB8(B1, 0, 1); STAGE8(SB8(0, 0), Bt, K, bcol, tt + 2);
;     BAR8; WAIT_L8(0); MMA8(0, 1, At, B1); BAR8;
;     LDA8(At, 0, 1); STAGE8(SA8(0, 0), A, lda, brow, tt + 2);
;     BAR8; WAIT_L8(0); MMA8(1, 0, At, B0); BAR8; SCHED8;
;     STAGE8(SB8(0, 1), Bt, K, bcol + 128, tt + 2);
;     WAIT_V8(6); BAR8; MMA8(1, 1, At, B1); BAR8;
	s_waitcnt lgkmcnt(0)
	v_mfma_f32_16x16x32_bf16 v[96:99], v[190:193], v[226:229], 0
	v_mfma_f32_16x16x32_bf16 v[92:95], v[190:193], v[238:241], 0
	v_mfma_f32_16x16x32_bf16 v[88:91], v[198:201], v[226:229], 0
	v_mfma_f32_16x16x32_bf16 v[84:87], v[198:201], v[238:241], 0
	v_mfma_f32_16x16x32_bf16 v[80:83], v[206:209], v[226:229], 0
	v_mfma_f32_16x16x32_bf16 v[76:79], v[206:209], v[238:241], 0
	v_mfma_f32_16x16x32_bf16 v[72:75], v[214:217], v[226:229], 0
	v_mfma_f32_16x16x32_bf16 v[68:71], v[214:217], v[238:241], 0
	v_mfma_f32_16x16x32_bf16 v[96:99], v[194:197], v[230:233], v[96:99]
	v_mfma_f32_16x16x32_bf16 v[92:95], v[194:197], v[242:245], v[92:95]
	v_mfma_f32_16x16x32_bf16 v[88:91], v[202:205], v[230:233], v[88:91]
	v_mfma_f32_16x16x32_bf16 v[84:87], v[202:205], v[242:245], v[84:87]
	v_mfma_f32_16x16x32_bf16 v[80:83], v[210:213], v[230:233], v[80:83]
	v_mfma_f32_16x16x32_bf16 v[76:79], v[210:213], v[242:245], v[76:79]
	v_mfma_f32_16x16x32_bf16 v[72:75], v[218:221], v[230:233], v[72:75]
	v_mfma_f32_16x16x32_bf16 v[68:71], v[218:221], v[242:245], v[68:71]
	v_lshl_add_u64 v[250:251], v[222:223], 0, s[40:41]
	s_mov_b32 m0, s100
	s_barrier
	ds_read_b128 v[190:193], v156 offset:16384
	ds_read_b128 v[194:197], v156 offset:17408
	ds_read_b128 v[198:201], v155 offset:16384
	ds_read_b128 v[202:205], v155 offset:17408
	ds_read_b128 v[206:209], v154 offset:16384
	ds_read_b128 v[210:213], v154 offset:17408
	ds_read_b128 v[214:217], v153 offset:16384
	ds_read_b128 v[218:221], v153 offset:17408
	global_load_lds_dwordx4 v[250:251], off
	s_or_b32 m0, s100, 0x2000
	v_lshl_add_u64 v[250:251], v[236:237], 0, s[40:41]
	global_load_lds_dwordx4 v[250:251], off
	s_barrier
	s_waitcnt lgkmcnt(0)
	v_mfma_f32_16x16x32_bf16 v[64:67], v[190:193], v[174:177], 0
	v_mfma_f32_16x16x32_bf16 v[60:63], v[190:193], v[182:185], 0
	v_mfma_f32_16x16x32_bf16 v[56:59], v[198:201], v[174:177], 0
	v_mfma_f32_16x16x32_bf16 v[52:55], v[198:201], v[182:185], 0
	v_mfma_f32_16x16x32_bf16 v[48:51], v[206:209], v[174:177], 0
	v_mfma_f32_16x16x32_bf16 v[44:47], v[206:209], v[182:185], 0
	v_mfma_f32_16x16x32_bf16 v[40:43], v[214:217], v[174:177], 0
	v_mfma_f32_16x16x32_bf16 v[36:39], v[214:217], v[182:185], 0
	v_mfma_f32_16x16x32_bf16 v[64:67], v[194:197], v[178:181], v[64:67]
	v_mfma_f32_16x16x32_bf16 v[60:63], v[194:197], v[186:189], v[60:63]
	v_mfma_f32_16x16x32_bf16 v[56:59], v[202:205], v[178:181], v[56:59]
	v_mfma_f32_16x16x32_bf16 v[52:55], v[202:205], v[186:189], v[52:55]
	v_mfma_f32_16x16x32_bf16 v[48:51], v[210:213], v[178:181], v[48:51]
	v_mfma_f32_16x16x32_bf16 v[44:47], v[210:213], v[186:189], v[44:47]
	v_mfma_f32_16x16x32_bf16 v[40:43], v[218:221], v[178:181], v[40:43]
	v_mfma_f32_16x16x32_bf16 v[36:39], v[218:221], v[186:189], v[36:39]
	s_barrier
	s_or_b32 m0, s100, 0x14000
	v_lshl_add_u64 v[174:175], v[246:247], 0, s[42:43]
	global_load_lds_dwordx4 v[174:175], off
	s_or_b32 m0, s100, 0x16000
	v_lshl_add_u64 v[174:175], v[248:249], 0, s[42:43]
	global_load_lds_dwordx4 v[174:175], off
	s_waitcnt vmcnt(6)
	s_barrier
	v_mfma_f32_16x16x32_bf16 v[32:35], v[190:193], v[226:229], 0
	v_mfma_f32_16x16x32_bf16 v[28:31], v[190:193], v[238:241], 0
	v_mfma_f32_16x16x32_bf16 v[24:27], v[198:201], v[226:229], 0
	v_mfma_f32_16x16x32_bf16 v[20:23], v[198:201], v[238:241], 0
	v_mfma_f32_16x16x32_bf16 v[16:19], v[206:209], v[226:229], 0
	v_mfma_f32_16x16x32_bf16 v[12:15], v[206:209], v[238:241], 0
	v_mfma_f32_16x16x32_bf16 v[8:11], v[214:217], v[226:229], 0
	v_mfma_f32_16x16x32_bf16 v[4:7], v[214:217], v[238:241], 0
	v_mfma_f32_16x16x32_bf16 v[32:35], v[194:197], v[230:233], v[32:35]
	v_mfma_f32_16x16x32_bf16 v[28:31], v[194:197], v[242:245], v[28:31]
	v_mfma_f32_16x16x32_bf16 v[24:27], v[202:205], v[230:233], v[24:27]
	v_mfma_f32_16x16x32_bf16 v[20:23], v[202:205], v[242:245], v[20:23]
	v_mfma_f32_16x16x32_bf16 v[16:19], v[210:213], v[230:233], v[16:19]
	v_mfma_f32_16x16x32_bf16 v[12:15], v[210:213], v[242:245], v[12:15]
	v_mfma_f32_16x16x32_bf16 v[8:11], v[218:221], v[230:233], v[8:11]
	v_mfma_f32_16x16x32_bf16 v[4:7], v[218:221], v[242:245], v[4:7]
	s_barrier
	ds_read_b128 v[174:177], v159
	ds_read_b128 v[178:181], v159 offset:1024
	ds_read_b128 v[182:185], v159 offset:2048
	ds_read_b128 v[186:189], v159 offset:3072
	v_lshl_add_u64 v[226:227], v[222:223], 0, s[44:45]
	s_or_b32 m0, s100, 0x4000
	ds_read_b128 v[190:193], v156 offset:32768
	ds_read_b128 v[194:197], v156 offset:33792
	ds_read_b128 v[198:201], v155 offset:32768
	ds_read_b128 v[202:205], v155 offset:33792
	ds_read_b128 v[206:209], v154 offset:32768
	ds_read_b128 v[210:213], v154 offset:33792
	ds_read_b128 v[214:217], v153 offset:32768
	ds_read_b128 v[218:221], v153 offset:33792
	global_load_lds_dwordx4 v[226:227], off
	s_or_b32 m0, s100, 0x6000
	v_lshl_add_u64 v[226:227], v[236:237], 0, s[44:45]
	global_load_lds_dwordx4 v[226:227], off
	s_waitcnt lgkmcnt(8)
	s_barrier
; #define LDA8(dst, b, h) _Pragma("unroll") for (int m = 0; m < 4; ++m) _Pragma("unroll") for (int k = 0; k < 2; ++k) \
;     dst[m][k] = *(const bf16x8*)((const char*)SA8(b, h) + lds_byte8(wr * 64 + m * 16 + fr, k * 32 + fq * 8))
; #define LDB8(dst, b, h) _Pragma("unroll") for (int n = 0; n < 2; ++n) _Pragma("unroll") for (int k = 0; k < 2; ++k) \
;     dst[n][k] = *(const bf16x8*)((const char*)SB8(b, h) + lds_byte8(wc * 32 + n * 16 + fr, k * 32 + fq * 8))
; #define WAIT_V8(n) asm volatile("s_waitcnt vmcnt(" #n ")" ::: "memory")
; #define WAIT_L8(n) asm volatile("s_waitcnt lgkmcnt(" #n ")" ::: "memory")
; #define BAR8 __builtin_amdgcn_s_barrier()
; #define SCHED8 __builtin_amdgcn_sched_barrier(0)
;     ...
;     WAIT_V8(6); BAR8; MMA8(1, 1, At, B1); BAR8;
;     LDB8(B0, 1, 0); SCHED8; LDA8(At, 1, 0); STAGE8(SA8(0, 1), A, lda, brow + 128, tt + 2);
;     WAIT_L8(8); BAR8; WAIT_L8(0); MMA8(0, 0, At, B0); BAR8; SCHED8;
;     LDB8(B1, 1, 1); STAGE8(SB8(1, 0), Bt, K, bcol, tt + 3);
;     BAR8; WAIT_L8(0); MMA8(0, 1, At, B1); BAR8;
;     LDA8(At, 1, 1); STAGE8(SA8(1, 0), A, lda, brow, tt + 3);
;     BAR8; WAIT_L8(0); MMA8(1, 0, At, B0); BAR8; SCHED8;
;     STAGE8(SB8(1, 1), Bt, K, bcol + 128, tt + 3);
;     WAIT_V8(6); BAR8; MMA8(1, 1, At, B1); BAR8;
;   }
	s_waitcnt lgkmcnt(0)
	v_mfma_f32_16x16x32_bf16 v[128:131], v[190:193], v[174:177], v[128:131]
	v_mfma_f32_16x16x32_bf16 v[124:127], v[190:193], v[182:185], v[124:127]
	v_mfma_f32_16x16x32_bf16 v[120:123], v[198:201], v[174:177], v[120:123]
	v_mfma_f32_16x16x32_bf16 v[116:119], v[198:201], v[182:185], v[116:119]
	v_mfma_f32_16x16x32_bf16 v[112:115], v[206:209], v[174:177], v[112:115]
	v_mfma_f32_16x16x32_bf16 v[108:111], v[206:209], v[182:185], v[108:111]
	v_mfma_f32_16x16x32_bf16 v[104:107], v[214:217], v[174:177], v[104:107]
	v_mfma_f32_16x16x32_bf16 v[100:103], v[214:217], v[182:185], v[100:103]
	v_mfma_f32_16x16x32_bf16 v[128:131], v[194:197], v[178:181], v[128:131]
	v_mfma_f32_16x16x32_bf16 v[124:127], v[194:197], v[186:189], v[124:127]
	v_mfma_f32_16x16x32_bf16 v[120:123], v[202:205], v[178:181], v[120:123]
	v_mfma_f32_16x16x32_bf16 v[116:119], v[202:205], v[186:189], v[116:119]
	v_mfma_f32_16x16x32_bf16 v[112:115], v[210:213], v[178:181], v[112:115]
	v_mfma_f32_16x16x32_bf16 v[108:111], v[210:213], v[186:189], v[108:111]
	v_mfma_f32_16x16x32_bf16 v[104:107], v[218:221], v[178:181], v[104:107]
	v_mfma_f32_16x16x32_bf16 v[100:103], v[218:221], v[186:189], v[100:103]
	s_barrier
	v_lshl_add_u64 v[250:251], v[246:247], 0, s[46:47]
	s_or_b32 m0, s100, 0x18000
	ds_read_b128 v[226:229], v158
	ds_read_b128 v[230:233], v158 offset:1024
	ds_read_b128 v[238:241], v158 offset:2048
	ds_read_b128 v[242:245], v158 offset:3072
	global_load_lds_dwordx4 v[250:251], off
	s_or_b32 m0, s100, 0x1a000
	v_lshl_add_u64 v[250:251], v[248:249], 0, s[46:47]
	global_load_lds_dwordx4 v[250:251], off
	s_barrier
	s_waitcnt lgkmcnt(0)
	v_mfma_f32_16x16x32_bf16 v[96:99], v[190:193], v[226:229], v[96:99]
	v_mfma_f32_16x16x32_bf16 v[92:95], v[190:193], v[238:241], v[92:95]
	v_mfma_f32_16x16x32_bf16 v[88:91], v[198:201], v[226:229], v[88:91]
	v_mfma_f32_16x16x32_bf16 v[84:87], v[198:201], v[238:241], v[84:87]
	v_mfma_f32_16x16x32_bf16 v[80:83], v[206:209], v[226:229], v[80:83]
	v_mfma_f32_16x16x32_bf16 v[76:79], v[206:209], v[238:241], v[76:79]
	v_mfma_f32_16x16x32_bf16 v[72:75], v[214:217], v[226:229], v[72:75]
	v_mfma_f32_16x16x32_bf16 v[68:71], v[214:217], v[238:241], v[68:71]
	v_mfma_f32_16x16x32_bf16 v[96:99], v[194:197], v[230:233], v[96:99]
	v_mfma_f32_16x16x32_bf16 v[92:95], v[194:197], v[242:245], v[92:95]
	v_mfma_f32_16x16x32_bf16 v[88:91], v[202:205], v[230:233], v[88:91]
	v_mfma_f32_16x16x32_bf16 v[84:87], v[202:205], v[242:245], v[84:87]
	v_mfma_f32_16x16x32_bf16 v[80:83], v[210:213], v[230:233], v[80:83]
	v_mfma_f32_16x16x32_bf16 v[76:79], v[210:213], v[242:245], v[76:79]
	v_mfma_f32_16x16x32_bf16 v[72:75], v[218:221], v[230:233], v[72:75]
	v_mfma_f32_16x16x32_bf16 v[68:71], v[218:221], v[242:245], v[68:71]
	v_lshl_add_u64 v[222:223], v[222:223], 0, s[48:49]
	s_or_b32 m0, s100, 0x8000
	s_barrier
	ds_read_b128 v[190:193], v156 offset:49152
	ds_read_b128 v[194:197], v156 offset:50176
	ds_read_b128 v[198:201], v155 offset:49152
	ds_read_b128 v[202:205], v155 offset:50176
	ds_read_b128 v[206:209], v154 offset:49152
	ds_read_b128 v[210:213], v154 offset:50176
	ds_read_b128 v[214:217], v153 offset:49152
	ds_read_b128 v[218:221], v153 offset:50176
	global_load_lds_dwordx4 v[222:223], off
	s_or_b32 m0, s100, 0xa000
	v_lshl_add_u64 v[222:223], v[236:237], 0, s[48:49]
	global_load_lds_dwordx4 v[222:223], off
	s_barrier
	s_waitcnt lgkmcnt(0)
	v_mfma_f32_16x16x32_bf16 v[64:67], v[190:193], v[174:177], v[64:67]
	v_mfma_f32_16x16x32_bf16 v[60:63], v[190:193], v[182:185], v[60:63]
	v_mfma_f32_16x16x32_bf16 v[56:59], v[198:201], v[174:177], v[56:59]
	v_mfma_f32_16x16x32_bf16 v[52:55], v[198:201], v[182:185], v[52:55]
	v_mfma_f32_16x16x32_bf16 v[48:51], v[206:209], v[174:177], v[48:51]
	v_mfma_f32_16x16x32_bf16 v[44:47], v[206:209], v[182:185], v[44:47]
	v_mfma_f32_16x16x32_bf16 v[40:43], v[214:217], v[174:177], v[40:43]
	v_mfma_f32_16x16x32_bf16 v[36:39], v[214:217], v[182:185], v[36:39]
	v_mfma_f32_16x16x32_bf16 v[64:67], v[194:197], v[178:181], v[64:67]
	v_mfma_f32_16x16x32_bf16 v[60:63], v[194:197], v[186:189], v[60:63]
	v_mfma_f32_16x16x32_bf16 v[56:59], v[202:205], v[178:181], v[56:59]
	v_mfma_f32_16x16x32_bf16 v[52:55], v[202:205], v[186:189], v[52:55]
	v_mfma_f32_16x16x32_bf16 v[48:51], v[210:213], v[178:181], v[48:51]
	v_mfma_f32_16x16x32_bf16 v[44:47], v[210:213], v[186:189], v[44:47]
	v_mfma_f32_16x16x32_bf16 v[40:43], v[218:221], v[178:181], v[40:43]
	v_mfma_f32_16x16x32_bf16 v[36:39], v[218:221], v[186:189], v[36:39]
	s_barrier
	s_or_b32 m0, s100, 0x1c000
	v_lshl_add_u64 v[174:175], v[246:247], 0, s[50:51]
	global_load_lds_dwordx4 v[174:175], off
	s_or_b32 m0, s100, 0x1e000
	v_lshl_add_u64 v[174:175], v[248:249], 0, s[50:51]
	global_load_lds_dwordx4 v[174:175], off
	s_waitcnt vmcnt(6)
	s_barrier
	v_mfma_f32_16x16x32_bf16 v[32:35], v[190:193], v[226:229], v[32:35]
	v_mfma_f32_16x16x32_bf16 v[28:31], v[190:193], v[238:241], v[28:31]
	v_mfma_f32_16x16x32_bf16 v[24:27], v[198:201], v[226:229], v[24:27]
	v_mfma_f32_16x16x32_bf16 v[20:23], v[198:201], v[238:241], v[20:23]
	v_mfma_f32_16x16x32_bf16 v[16:19], v[206:209], v[226:229], v[16:19]
	v_mfma_f32_16x16x32_bf16 v[12:15], v[206:209], v[238:241], v[12:15]
	v_mfma_f32_16x16x32_bf16 v[8:11], v[214:217], v[226:229], v[8:11]
	v_mfma_f32_16x16x32_bf16 v[4:7], v[214:217], v[238:241], v[4:7]
	v_mfma_f32_16x16x32_bf16 v[32:35], v[194:197], v[230:233], v[32:35]
	v_mfma_f32_16x16x32_bf16 v[28:31], v[194:197], v[242:245], v[28:31]
	v_mfma_f32_16x16x32_bf16 v[24:27], v[202:205], v[230:233], v[24:27]
	v_mfma_f32_16x16x32_bf16 v[20:23], v[202:205], v[242:245], v[20:23]
	v_mfma_f32_16x16x32_bf16 v[16:19], v[210:213], v[230:233], v[16:19]
	v_mfma_f32_16x16x32_bf16 v[12:15], v[210:213], v[242:245], v[12:15]
	v_mfma_f32_16x16x32_bf16 v[8:11], v[218:221], v[230:233], v[8:11]
	v_mfma_f32_16x16x32_bf16 v[4:7], v[218:221], v[242:245], v[4:7]
	s_add_i32 s29, s29, 2
	s_add_u32 s12, s12, 0x100
	s_addc_u32 s13, s13, 0
	s_cmp_lt_u32 s29, 40
	s_cbranch_scc0 .Lpk_exitb_7
